# GLA state/out: next item's prefetch loads issued after the first log-gate pass so the in-order wait for the gate weights does not also wait for the prefetch
# speedup vs baseline: 1.0182x; 1.0036x over previous
; DEVI unsigned cvt_pk(float lo, float hi) { f32v2_t f = {lo, hi}; bf16v2_t v = __builtin_convertvector(f, bf16v2_t); return __builtin_bit_cast(unsigned, v); }
; DEVI float logsigf_(float x) { return fminf(x, 0.f) - __logf(1.f + __expf(-fabsf(x))); }
; template <int KIND>
; DEVI void mix_state_phase(unsigned char* smem, const MixArgs a) {
;     ...
;         lds_barrier();
; #pragma unroll
;         for (int k = 0; k < 8; ++k) { const int i = tid + k * 512, t = i >> 5, c8 = (i & 31) * 8; *(u32x4*)(VTF + t * VSP + c8) = pvv[k]; }
;         if (KIND == 0) {
; #pragma unroll
;             for (int k = 0; k < 5; ++k) { const int q = tid + k * 512; if (q < 131 * 16) *(u32x4*)(RAWK + (q >> 4) * 128 + (q & 15) * 8) = pkr[k]; }
;             if (tid < 128) { fI[tid] = pg[0] + a.gateb[h]; fB[tid] = logsigf_(pg[1] + a.gateb[4 + h]); }
;         } else {
; #pragma unroll
;             for (int k = 0; k < 4; ++k) { const int i = tid + k * 512; *(u32x4*)(KT + (i >> 4) * LP + (i & 15) * 8) = pkr[k]; gl[i] = pg[k]; }
;         }
;         lds_barrier();
;         if (item + (int)gridDim.x < 16 * NCH) ST_PREF(item + (int)gridDim.x);
;         (void)c;
;         if (KIND == 0) {
;             if (tid < 64) { float x0 = fB[2 * tid], x1 = fB[2 * tid + 1]; float sc = x0 + x1;
; #pragma unroll
;                 for (int o = 1; o < 64; o <<= 1) { const float t = __shfl_up(sc, o); if (tid >= o) sc += t; }
;                 fB[2 * tid] = sc - x1; fB[2 * tid + 1] = sc; }
;             lds_barrier();
;             const float bl = fB[127];
; #pragma unroll 2
;             for (int i = tid; i < 128 * 16; i += 512) { const int t = i >> 4, c8 = (i & 15) * 8; float v[8]; mlstm_conv8_lds(RAWK, a.convw, t, c8, 512 + h * 128 + c8, v); const float w = __expf(bl - fB[t] + fI[t]);
;                 u32x4 pw; pw.x = cvt_pk(v[0] * w, v[1] * w); pw.y = cvt_pk(v[2] * w, v[3] * w); pw.z = cvt_pk(v[4] * w, v[5] * w); pw.w = cvt_pk(v[6] * w, v[7] * w);
;                 *(u32x4*)(KT + t * LP + c8) = pw; }
;         } else {
;             const int ch = tid & 127, sg = tid >> 7; float w2r[16];
; #pragma unroll
;             for (int r = 0; r < 16; ++r) w2r[r] = a.w2[r * 512 + h * 128 + ch];
;             const float gb = a.gateb[h * 128 + ch]; float ssum = 0.f;
;             for (int t = sg * 32; t < sg * 32 + 32; ++t) ssum += gla_la(gl, t, w2r, gb);
.LBB0_511:
	s_waitcnt lgkmcnt(0)
	s_barrier
	s_waitcnt vmcnt(15)
	ds_write_b128 v101, v[0:3] offset:16384
	s_waitcnt vmcnt(14)
	ds_write_b128 v102, v[4:7] offset:16384
	s_waitcnt vmcnt(13)
	ds_write_b128 v103, v[10:13] offset:16384
	s_waitcnt vmcnt(12)
	ds_write_b128 v104, v[14:17] offset:16384
	s_waitcnt vmcnt(11)
	ds_write_b128 v105, v[18:21] offset:16384
	s_waitcnt vmcnt(10)
	ds_write_b128 v106, v[22:25] offset:16384
	s_waitcnt vmcnt(9)
	ds_write_b128 v107, v[26:29] offset:16384
	s_waitcnt vmcnt(8)
	ds_write_b128 v108, v[30:33] offset:16384
	s_waitcnt vmcnt(7)
	ds_write_b128 v109, v[34:37]
	s_waitcnt vmcnt(6)
	ds_write_b32 v95, v85 offset:4096
	s_waitcnt vmcnt(5)
	ds_write_b128 v110, v[38:41]
	s_waitcnt vmcnt(4)
	ds_write_b32 v95, v97 offset:6144
	s_waitcnt vmcnt(3)
	ds_write_b128 v111, v[42:45]
	s_waitcnt vmcnt(2)
	ds_write_b32 v95, v98 offset:8192
	s_waitcnt vmcnt(1)
	ds_write_b128 v112, v[46:49]
	s_waitcnt vmcnt(0)
	ds_write_b32 v95, v87 offset:10240
	s_add_i32 s46, s14, s22
	s_waitcnt lgkmcnt(0)
	s_barrier
.LBB0_513:
	s_ashr_i32 s15, s14, 31
	s_lshr_b32 s0, s15, 26
	s_add_i32 s0, s14, s0
	s_lshl_b32 s0, s0, 1
	s_and_b32 s0, s0, 0x180
	v_or_b32_e32 v8, s0, v94
	v_lshlrev_b32_e32 v8, 2, v8
	v_lshl_add_u64 v[92:93], s[84:85], 0, v[8:9]
	v_add_co_u32_e32 v122, vcc, s50, v92
	s_movk_i32 s0, 0x4000
	s_nop 0
	v_addc_co_u32_e32 v123, vcc, 0, v93, vcc
	v_add_co_u32_e32 v50, vcc, s49, v92
	s_nop 1
	v_addc_co_u32_e32 v51, vcc, 0, v93, vcc
	v_add_co_u32_e32 v124, vcc, s53, v92
	s_nop 1
	v_addc_co_u32_e32 v125, vcc, 0, v93, vcc
	v_add_co_u32_e32 v88, vcc, s0, v92
	s_movk_i32 s0, 0x5000
	s_nop 0
	v_addc_co_u32_e32 v89, vcc, 0, v93, vcc
	v_add_co_u32_e32 v126, vcc, s0, v92
	s_movk_i32 s0, 0x6000
	s_nop 0
	v_addc_co_u32_e32 v127, vcc, 0, v93, vcc
	v_add_co_u32_e32 v120, vcc, s0, v92
	v_readlane_b32 s0, v254, 7
	s_nop 0
	v_addc_co_u32_e32 v121, vcc, 0, v93, vcc
	global_load_dword v116, v[50:51], off offset:-4096
	global_load_dword v117, v[50:51], off
	global_load_dword v118, v[50:51], off offset:2048
	s_nop 0
	global_load_dword v50, v[88:89], off offset:-4096
	global_load_dword v52, v[88:89], off
	global_load_dword v53, v[88:89], off offset:2048
	s_nop 0
	global_load_dword v88, v[120:121], off offset:-4096
	global_load_dword v90, v[120:121], off
	global_load_dword v91, v[120:121], off offset:2048
	v_add_co_u32_e32 v128, vcc, 0x7000, v92
	v_readlane_b32 s1, v254, 8
	s_nop 0
	v_addc_co_u32_e32 v129, vcc, 0, v93, vcc
	global_load_dword v119, v8, s[84:85]
	global_load_dword v120, v8, s[84:85] offset:2048
	global_load_dword v121, v[122:123], off offset:2048
	global_load_dword v51, v[124:125], off offset:2048
	global_load_dword v89, v[126:127], off offset:2048
	global_load_dword v92, v[128:129], off
	s_nop 0
	global_load_dword v8, v8, s[0:1]
	s_nop 0
	global_load_dword v93, v[128:129], off offset:2048
	s_mov_b32 s0, 0
	v_mov_b32_e32 v122, 0
.LBB0_514:
	v_add_u32_e32 v123, s0, v99
	ds_read_b128 v[124:127], v123
	ds_read_b128 v[128:131], v123 offset:16
	ds_read_b128 v[132:135], v123 offset:32
	ds_read_b128 v[136:139], v123 offset:48
	ds_read_b128 v[176:179], v123 offset:64
	ds_read_b128 v[180:183], v123 offset:80
	ds_read_b128 v[184:187], v123 offset:96
	ds_read_b128 v[188:191], v123 offset:112
	s_addk_i32 s0, 0x80
	s_waitcnt vmcnt(1) lgkmcnt(7)
	v_fma_f32 v140, v119, v124, v8
	v_fmac_f32_e32 v140, v120, v125
	v_fmac_f32_e32 v140, v116, v126
	v_fmac_f32_e32 v140, v121, v127
	s_waitcnt lgkmcnt(6)
	v_fmac_f32_e32 v140, v117, v128
	v_fmac_f32_e32 v140, v118, v129
	v_pk_mul_f32 v[124:125], v[50:51], v[130:131]
	v_add_f32_e32 v124, v140, v124
	v_add_f32_e32 v126, v124, v125
	s_waitcnt lgkmcnt(5)
	v_pk_mul_f32 v[124:125], v[52:53], v[132:133]
	s_nop 0
	v_add_f32_e32 v124, v126, v124
	v_add_f32_e32 v126, v124, v125
	v_pk_mul_f32 v[124:125], v[88:89], v[134:135]
	s_nop 0
	v_add_f32_e32 v124, v126, v124
	v_add_f32_e32 v126, v124, v125
	s_waitcnt lgkmcnt(4)
	v_pk_mul_f32 v[124:125], v[90:91], v[136:137]
	s_nop 0
	v_add_f32_e32 v124, v126, v124
	v_add_f32_e32 v126, v124, v125
	s_waitcnt vmcnt(0)
	v_pk_mul_f32 v[124:125], v[92:93], v[138:139]
	s_nop 0
	v_add_f32_e32 v124, v126, v124
	v_add_f32_e32 v124, v124, v125
	v_min_f32_e32 v125, 0, v124
	v_mul_f32_e64 v124, |v124|, s73
	v_exp_f32_e32 v124, v124
	s_nop 0
	v_add_f32_e32 v124, 1.0, v124
	v_cmp_gt_f32_e32 vcc, s94, v124
	s_nop 1
	v_cndmask_b32_e64 v126, 0, 32, vcc
	v_ldexp_f32 v124, v124, v126
	v_log_f32_e32 v124, v124
	s_nop 0
	v_mul_f32_e32 v126, 0x3f317217, v124
	v_fma_f32 v126, v124, s97, -v126
	v_fmac_f32_e32 v126, 0x3377d1cf, v124
	v_fmac_f32_e32 v126, 0x3f317217, v124
	v_cmp_lt_f32_e64 s[12:13], |v124|, s23
	s_nop 1
	v_cndmask_b32_e64 v124, v124, v126, s[12:13]
	v_cndmask_b32_e32 v126, 0, v211, vcc
	v_sub_f32_e32 v124, v124, v126
	v_sub_f32_e32 v124, v125, v124
	v_fmac_f32_e32 v122, 0x3d800000, v124
	v_mov_b32_e32 v192, v124
	s_waitcnt lgkmcnt(0)
; DEVI float logsigf_(float x) { return fminf(x, 0.f) - __logf(1.f + __expf(-fabsf(x))); }
; DEVI float gla_la(const float* gl, int t, const float* w2r, float gb) { float x = gb;
; #pragma unroll
;     for (int r = 0; r < 16; ++r) x += gl[t * 16 + r] * w2r[r];
;     return logsigf_(x) * (1.f / 16.f); }
; template <int KIND>
; DEVI void mix_state_phase(unsigned char* smem, const MixArgs a) {
;     ...
;             const int ch = tid & 127, sg = tid >> 7; float w2r[16];
; #pragma unroll
;             for (int r = 0; r < 16; ++r) w2r[r] = a.w2[r * 512 + h * 128 + ch];
;             const float gb = a.gateb[h * 128 + ch]; float ssum = 0.f;
;             for (int t = sg * 32; t < sg * 32 + 32; ++t) ssum += gla_la(gl, t, w2r, gb);
	v_fma_f32 v128, v119, v176, v8
	v_fmac_f32_e32 v128, v120, v177
	v_fmac_f32_e32 v128, v116, v178
	v_fmac_f32_e32 v128, v121, v179
	v_fmac_f32_e32 v128, v117, v180
	v_fmac_f32_e32 v128, v118, v181
	v_pk_mul_f32 v[124:125], v[50:51], v[182:183]
	s_nop 0
	v_add_f32_e32 v124, v128, v124
	v_add_f32_e32 v128, v124, v125
	v_pk_mul_f32 v[124:125], v[52:53], v[184:185]
	s_nop 0
	v_add_f32_e32 v124, v128, v124
	v_add_f32_e32 v128, v124, v125
	v_pk_mul_f32 v[124:125], v[88:89], v[186:187]
	s_nop 0
	v_add_f32_e32 v124, v128, v124
	v_add_f32_e32 v128, v124, v125
	v_pk_mul_f32 v[124:125], v[90:91], v[188:189]
	s_nop 0
	v_add_f32_e32 v123, v128, v124
	v_add_f32_e32 v123, v123, v125
	v_pk_mul_f32 v[124:125], v[92:93], v[190:191]
	s_nop 0
	v_add_f32_e32 v123, v123, v124
	v_add_f32_e32 v123, v123, v125
	v_min_f32_e32 v124, 0, v123
	v_mul_f32_e64 v123, |v123|, s73
	v_exp_f32_e32 v123, v123
	s_nop 0
	v_add_f32_e32 v123, 1.0, v123
	v_cmp_gt_f32_e32 vcc, s94, v123
	s_nop 1
	v_cndmask_b32_e64 v125, 0, 32, vcc
	v_ldexp_f32 v123, v123, v125
	v_log_f32_e32 v123, v123
	s_nop 0
	v_mul_f32_e32 v125, 0x3f317217, v123
	v_fma_f32 v125, v123, s97, -v125
	v_fmac_f32_e32 v125, 0x3377d1cf, v123
	v_fmac_f32_e32 v125, 0x3f317217, v123
	v_cmp_lt_f32_e64 s[12:13], |v123|, s23
	s_nop 1
	v_cndmask_b32_e64 v123, v123, v125, s[12:13]
	v_cndmask_b32_e32 v125, 0, v211, vcc
	v_sub_f32_e32 v123, v123, v125
	v_sub_f32_e32 v123, v124, v123
	v_fmac_f32_e32 v122, 0x3d800000, v123
	v_mov_b32_e32 v193, v123
	v_add_u32_e32 v123, s0, v99
	ds_read_b128 v[124:127], v123
	ds_read_b128 v[128:131], v123 offset:16
	ds_read_b128 v[132:135], v123 offset:32
	ds_read_b128 v[136:139], v123 offset:48
	ds_read_b128 v[176:179], v123 offset:64
	ds_read_b128 v[180:183], v123 offset:80
	ds_read_b128 v[184:187], v123 offset:96
	ds_read_b128 v[188:191], v123 offset:112
	s_addk_i32 s0, 0x80
	s_waitcnt vmcnt(1) lgkmcnt(7)
	v_fma_f32 v140, v119, v124, v8
	v_fmac_f32_e32 v140, v120, v125
	v_fmac_f32_e32 v140, v116, v126
	v_fmac_f32_e32 v140, v121, v127
	s_waitcnt lgkmcnt(6)
	v_fmac_f32_e32 v140, v117, v128
	v_fmac_f32_e32 v140, v118, v129
	v_pk_mul_f32 v[124:125], v[50:51], v[130:131]
	v_add_f32_e32 v124, v140, v124
	v_add_f32_e32 v126, v124, v125
	s_waitcnt lgkmcnt(5)
	v_pk_mul_f32 v[124:125], v[52:53], v[132:133]
	s_nop 0
	v_add_f32_e32 v124, v126, v124
	v_add_f32_e32 v126, v124, v125
	v_pk_mul_f32 v[124:125], v[88:89], v[134:135]
	s_nop 0
	v_add_f32_e32 v124, v126, v124
	v_add_f32_e32 v126, v124, v125
	s_waitcnt lgkmcnt(4)
	v_pk_mul_f32 v[124:125], v[90:91], v[136:137]
	s_nop 0
	v_add_f32_e32 v124, v126, v124
	v_add_f32_e32 v126, v124, v125
	s_waitcnt vmcnt(0)
	v_pk_mul_f32 v[124:125], v[92:93], v[138:139]
	s_nop 0
	v_add_f32_e32 v124, v126, v124
	v_add_f32_e32 v124, v124, v125
	v_min_f32_e32 v125, 0, v124
	v_mul_f32_e64 v124, |v124|, s73
	v_exp_f32_e32 v124, v124
	s_nop 0
	v_add_f32_e32 v124, 1.0, v124
	v_cmp_gt_f32_e32 vcc, s94, v124
	s_nop 1
	v_cndmask_b32_e64 v126, 0, 32, vcc
	v_ldexp_f32 v124, v124, v126
	v_log_f32_e32 v124, v124
	s_nop 0
	v_mul_f32_e32 v126, 0x3f317217, v124
	v_fma_f32 v126, v124, s97, -v126
	v_fmac_f32_e32 v126, 0x3377d1cf, v124
	v_fmac_f32_e32 v126, 0x3f317217, v124
	v_cmp_lt_f32_e64 s[12:13], |v124|, s23
	s_nop 1
	v_cndmask_b32_e64 v124, v124, v126, s[12:13]
	v_cndmask_b32_e32 v126, 0, v211, vcc
	v_sub_f32_e32 v124, v124, v126
	v_sub_f32_e32 v124, v125, v124
	v_fmac_f32_e32 v122, 0x3d800000, v124
	v_mov_b32_e32 v194, v124
	s_waitcnt lgkmcnt(0)
	v_fma_f32 v128, v119, v176, v8
	v_fmac_f32_e32 v128, v120, v177
	v_fmac_f32_e32 v128, v116, v178
	v_fmac_f32_e32 v128, v121, v179
	v_fmac_f32_e32 v128, v117, v180
	v_fmac_f32_e32 v128, v118, v181
	v_pk_mul_f32 v[124:125], v[50:51], v[182:183]
	s_nop 0
	v_add_f32_e32 v124, v128, v124
	v_add_f32_e32 v128, v124, v125
	v_pk_mul_f32 v[124:125], v[52:53], v[184:185]
	s_nop 0
	v_add_f32_e32 v124, v128, v124
	v_add_f32_e32 v128, v124, v125
	v_pk_mul_f32 v[124:125], v[88:89], v[186:187]
	s_nop 0
	v_add_f32_e32 v124, v128, v124
	v_add_f32_e32 v128, v124, v125
	v_pk_mul_f32 v[124:125], v[90:91], v[188:189]
	s_nop 0
	v_add_f32_e32 v123, v128, v124
	v_add_f32_e32 v123, v123, v125
	v_pk_mul_f32 v[124:125], v[92:93], v[190:191]
	s_nop 0
	v_add_f32_e32 v123, v123, v124
	v_add_f32_e32 v123, v123, v125
	v_min_f32_e32 v124, 0, v123
	v_mul_f32_e64 v123, |v123|, s73
	v_exp_f32_e32 v123, v123
	s_nop 0
	v_add_f32_e32 v123, 1.0, v123
	v_cmp_gt_f32_e32 vcc, s94, v123
	s_nop 1
	v_cndmask_b32_e64 v125, 0, 32, vcc
	v_ldexp_f32 v123, v123, v125
	v_log_f32_e32 v123, v123
	s_nop 0
	v_mul_f32_e32 v125, 0x3f317217, v123
	v_fma_f32 v125, v123, s97, -v125
	v_fmac_f32_e32 v125, 0x3377d1cf, v123
	v_fmac_f32_e32 v125, 0x3f317217, v123
	v_cmp_lt_f32_e64 s[12:13], |v123|, s23
	s_nop 1
	v_cndmask_b32_e64 v123, v123, v125, s[12:13]
	v_cndmask_b32_e32 v125, 0, v211, vcc
	v_sub_f32_e32 v123, v123, v125
	v_sub_f32_e32 v123, v124, v123
	v_fmac_f32_e32 v122, 0x3d800000, v123
	v_mov_b32_e32 v195, v123
	v_add_u32_e32 v123, s0, v99
	ds_read_b128 v[124:127], v123
	ds_read_b128 v[128:131], v123 offset:16
	ds_read_b128 v[132:135], v123 offset:32
	ds_read_b128 v[136:139], v123 offset:48
	ds_read_b128 v[176:179], v123 offset:64
	ds_read_b128 v[180:183], v123 offset:80
	ds_read_b128 v[184:187], v123 offset:96
	ds_read_b128 v[188:191], v123 offset:112
	s_addk_i32 s0, 0x80
	s_waitcnt vmcnt(1) lgkmcnt(7)
	v_fma_f32 v140, v119, v124, v8
	v_fmac_f32_e32 v140, v120, v125
	v_fmac_f32_e32 v140, v116, v126
	v_fmac_f32_e32 v140, v121, v127
	s_waitcnt lgkmcnt(6)
	v_fmac_f32_e32 v140, v117, v128
	v_fmac_f32_e32 v140, v118, v129
	v_pk_mul_f32 v[124:125], v[50:51], v[130:131]
	v_add_f32_e32 v124, v140, v124
	v_add_f32_e32 v126, v124, v125
	s_waitcnt lgkmcnt(5)
; DEVI float logsigf_(float x) { return fminf(x, 0.f) - __logf(1.f + __expf(-fabsf(x))); }
; DEVI float gla_la(const float* gl, int t, const float* w2r, float gb) { float x = gb;
; #pragma unroll
;     for (int r = 0; r < 16; ++r) x += gl[t * 16 + r] * w2r[r];
;     return logsigf_(x) * (1.f / 16.f); }
; template <int KIND>
; DEVI void mix_state_phase(unsigned char* smem, const MixArgs a) {
;     ...
;             const int ch = tid & 127, sg = tid >> 7; float w2r[16];
; #pragma unroll
;             for (int r = 0; r < 16; ++r) w2r[r] = a.w2[r * 512 + h * 128 + ch];
;             const float gb = a.gateb[h * 128 + ch]; float ssum = 0.f;
;             for (int t = sg * 32; t < sg * 32 + 32; ++t) ssum += gla_la(gl, t, w2r, gb);
	v_pk_mul_f32 v[124:125], v[52:53], v[132:133]
	s_nop 0
	v_add_f32_e32 v124, v126, v124
	v_add_f32_e32 v126, v124, v125
	v_pk_mul_f32 v[124:125], v[88:89], v[134:135]
	s_nop 0
	v_add_f32_e32 v124, v126, v124
	v_add_f32_e32 v126, v124, v125
	s_waitcnt lgkmcnt(4)
	v_pk_mul_f32 v[124:125], v[90:91], v[136:137]
	s_nop 0
	v_add_f32_e32 v124, v126, v124
	v_add_f32_e32 v126, v124, v125
	s_waitcnt vmcnt(0)
	v_pk_mul_f32 v[124:125], v[92:93], v[138:139]
	s_nop 0
	v_add_f32_e32 v124, v126, v124
	v_add_f32_e32 v124, v124, v125
	v_min_f32_e32 v125, 0, v124
	v_mul_f32_e64 v124, |v124|, s73
	v_exp_f32_e32 v124, v124
	s_nop 0
	v_add_f32_e32 v124, 1.0, v124
	v_cmp_gt_f32_e32 vcc, s94, v124
	s_nop 1
	v_cndmask_b32_e64 v126, 0, 32, vcc
	v_ldexp_f32 v124, v124, v126
	v_log_f32_e32 v124, v124
	s_nop 0
	v_mul_f32_e32 v126, 0x3f317217, v124
	v_fma_f32 v126, v124, s97, -v126
	v_fmac_f32_e32 v126, 0x3377d1cf, v124
	v_fmac_f32_e32 v126, 0x3f317217, v124
	v_cmp_lt_f32_e64 s[12:13], |v124|, s23
	s_nop 1
	v_cndmask_b32_e64 v124, v124, v126, s[12:13]
	v_cndmask_b32_e32 v126, 0, v211, vcc
	v_sub_f32_e32 v124, v124, v126
	v_sub_f32_e32 v124, v125, v124
	v_fmac_f32_e32 v122, 0x3d800000, v124
	v_mov_b32_e32 v196, v124
	s_waitcnt lgkmcnt(0)
	v_fma_f32 v128, v119, v176, v8
	v_fmac_f32_e32 v128, v120, v177
	v_fmac_f32_e32 v128, v116, v178
	v_fmac_f32_e32 v128, v121, v179
	v_fmac_f32_e32 v128, v117, v180
	v_fmac_f32_e32 v128, v118, v181
	v_pk_mul_f32 v[124:125], v[50:51], v[182:183]
	s_nop 0
	v_add_f32_e32 v124, v128, v124
	v_add_f32_e32 v128, v124, v125
	v_pk_mul_f32 v[124:125], v[52:53], v[184:185]
	s_nop 0
	v_add_f32_e32 v124, v128, v124
	v_add_f32_e32 v128, v124, v125
	v_pk_mul_f32 v[124:125], v[88:89], v[186:187]
	s_nop 0
	v_add_f32_e32 v124, v128, v124
	v_add_f32_e32 v128, v124, v125
	v_pk_mul_f32 v[124:125], v[90:91], v[188:189]
	s_nop 0
	v_add_f32_e32 v123, v128, v124
	v_add_f32_e32 v123, v123, v125
	v_pk_mul_f32 v[124:125], v[92:93], v[190:191]
	s_nop 0
	v_add_f32_e32 v123, v123, v124
	v_add_f32_e32 v123, v123, v125
	v_min_f32_e32 v124, 0, v123
	v_mul_f32_e64 v123, |v123|, s73
	v_exp_f32_e32 v123, v123
	s_nop 0
	v_add_f32_e32 v123, 1.0, v123
	v_cmp_gt_f32_e32 vcc, s94, v123
	s_nop 1
	v_cndmask_b32_e64 v125, 0, 32, vcc
	v_ldexp_f32 v123, v123, v125
	v_log_f32_e32 v123, v123
	s_nop 0
	v_mul_f32_e32 v125, 0x3f317217, v123
	v_fma_f32 v125, v123, s97, -v125
	v_fmac_f32_e32 v125, 0x3377d1cf, v123
	v_fmac_f32_e32 v125, 0x3f317217, v123
	v_cmp_lt_f32_e64 s[12:13], |v123|, s23
	s_nop 1
	v_cndmask_b32_e64 v123, v123, v125, s[12:13]
	v_cndmask_b32_e32 v125, 0, v211, vcc
	v_sub_f32_e32 v123, v123, v125
	v_sub_f32_e32 v123, v124, v123
	v_fmac_f32_e32 v122, 0x3d800000, v123
	v_mov_b32_e32 v197, v123
	v_add_u32_e32 v123, s0, v99
	ds_read_b128 v[124:127], v123
	ds_read_b128 v[128:131], v123 offset:16
	ds_read_b128 v[132:135], v123 offset:32
	ds_read_b128 v[136:139], v123 offset:48
	ds_read_b128 v[176:179], v123 offset:64
	ds_read_b128 v[180:183], v123 offset:80
	ds_read_b128 v[184:187], v123 offset:96
	ds_read_b128 v[188:191], v123 offset:112
	s_addk_i32 s0, 0x80
	s_waitcnt vmcnt(1) lgkmcnt(7)
	v_fma_f32 v140, v119, v124, v8
	v_fmac_f32_e32 v140, v120, v125
	v_fmac_f32_e32 v140, v116, v126
	v_fmac_f32_e32 v140, v121, v127
	s_waitcnt lgkmcnt(6)
	v_fmac_f32_e32 v140, v117, v128
	v_fmac_f32_e32 v140, v118, v129
	v_pk_mul_f32 v[124:125], v[50:51], v[130:131]
	v_add_f32_e32 v124, v140, v124
	v_add_f32_e32 v126, v124, v125
	s_waitcnt lgkmcnt(5)
	v_pk_mul_f32 v[124:125], v[52:53], v[132:133]
	s_nop 0
	v_add_f32_e32 v124, v126, v124
	v_add_f32_e32 v126, v124, v125
	v_pk_mul_f32 v[124:125], v[88:89], v[134:135]
	s_nop 0
	v_add_f32_e32 v124, v126, v124
	v_add_f32_e32 v126, v124, v125
	s_waitcnt lgkmcnt(4)
	v_pk_mul_f32 v[124:125], v[90:91], v[136:137]
	s_nop 0
	v_add_f32_e32 v124, v126, v124
	v_add_f32_e32 v126, v124, v125
	s_waitcnt vmcnt(0)
	v_pk_mul_f32 v[124:125], v[92:93], v[138:139]
	s_nop 0
	v_add_f32_e32 v124, v126, v124
	v_add_f32_e32 v124, v124, v125
	v_min_f32_e32 v125, 0, v124
	v_mul_f32_e64 v124, |v124|, s73
	v_exp_f32_e32 v124, v124
	s_nop 0
	v_add_f32_e32 v124, 1.0, v124
	v_cmp_gt_f32_e32 vcc, s94, v124
	s_nop 1
	v_cndmask_b32_e64 v126, 0, 32, vcc
	v_ldexp_f32 v124, v124, v126
	v_log_f32_e32 v124, v124
	s_nop 0
	v_mul_f32_e32 v126, 0x3f317217, v124
	v_fma_f32 v126, v124, s97, -v126
	v_fmac_f32_e32 v126, 0x3377d1cf, v124
	v_fmac_f32_e32 v126, 0x3f317217, v124
	v_cmp_lt_f32_e64 s[12:13], |v124|, s23
	s_nop 1
	v_cndmask_b32_e64 v124, v124, v126, s[12:13]
	v_cndmask_b32_e32 v126, 0, v211, vcc
	v_sub_f32_e32 v124, v124, v126
	v_sub_f32_e32 v124, v125, v124
	v_fmac_f32_e32 v122, 0x3d800000, v124
	v_mov_b32_e32 v198, v124
	s_waitcnt lgkmcnt(0)
	v_fma_f32 v128, v119, v176, v8
	v_fmac_f32_e32 v128, v120, v177
	v_fmac_f32_e32 v128, v116, v178
	v_fmac_f32_e32 v128, v121, v179
	v_fmac_f32_e32 v128, v117, v180
	v_fmac_f32_e32 v128, v118, v181
	v_pk_mul_f32 v[124:125], v[50:51], v[182:183]
	s_nop 0
	v_add_f32_e32 v124, v128, v124
	v_add_f32_e32 v128, v124, v125
	v_pk_mul_f32 v[124:125], v[52:53], v[184:185]
	s_nop 0
	v_add_f32_e32 v124, v128, v124
	v_add_f32_e32 v128, v124, v125
	v_pk_mul_f32 v[124:125], v[88:89], v[186:187]
	s_nop 0
	v_add_f32_e32 v124, v128, v124
	v_add_f32_e32 v128, v124, v125
	v_pk_mul_f32 v[124:125], v[90:91], v[188:189]
	s_nop 0
	v_add_f32_e32 v123, v128, v124
	v_add_f32_e32 v123, v123, v125
	v_pk_mul_f32 v[124:125], v[92:93], v[190:191]
	s_nop 0
	v_add_f32_e32 v123, v123, v124
	v_add_f32_e32 v123, v123, v125
	v_min_f32_e32 v124, 0, v123
	v_mul_f32_e64 v123, |v123|, s73
	v_exp_f32_e32 v123, v123
	s_nop 0
	v_add_f32_e32 v123, 1.0, v123
	v_cmp_gt_f32_e32 vcc, s94, v123
	s_nop 1
	v_cndmask_b32_e64 v125, 0, 32, vcc
	v_ldexp_f32 v123, v123, v125
	v_log_f32_e32 v123, v123
	s_nop 0
	v_mul_f32_e32 v125, 0x3f317217, v123
	v_fma_f32 v125, v123, s97, -v125
	v_fmac_f32_e32 v125, 0x3377d1cf, v123
	v_fmac_f32_e32 v125, 0x3f317217, v123
	v_cmp_lt_f32_e64 s[12:13], |v123|, s23
	s_nop 1
	v_cndmask_b32_e64 v123, v123, v125, s[12:13]
	v_cndmask_b32_e32 v125, 0, v211, vcc
	v_sub_f32_e32 v123, v123, v125
	v_sub_f32_e32 v123, v124, v123
	v_fmac_f32_e32 v122, 0x3d800000, v123
	v_mov_b32_e32 v199, v123
	v_add_u32_e32 v123, s0, v99
	ds_read_b128 v[124:127], v123
	ds_read_b128 v[128:131], v123 offset:16
	ds_read_b128 v[132:135], v123 offset:32
	ds_read_b128 v[136:139], v123 offset:48
	ds_read_b128 v[176:179], v123 offset:64
	ds_read_b128 v[180:183], v123 offset:80
	ds_read_b128 v[184:187], v123 offset:96
	ds_read_b128 v[188:191], v123 offset:112
	s_addk_i32 s0, 0x80
	s_waitcnt vmcnt(1) lgkmcnt(7)
; DEVI float logsigf_(float x) { return fminf(x, 0.f) - __logf(1.f + __expf(-fabsf(x))); }
; DEVI float gla_la(const float* gl, int t, const float* w2r, float gb) { float x = gb;
; #pragma unroll
;     for (int r = 0; r < 16; ++r) x += gl[t * 16 + r] * w2r[r];
;     return logsigf_(x) * (1.f / 16.f); }
; template <int KIND>
; DEVI void mix_state_phase(unsigned char* smem, const MixArgs a) {
;     ...
;             const int ch = tid & 127, sg = tid >> 7; float w2r[16];
; #pragma unroll
;             for (int r = 0; r < 16; ++r) w2r[r] = a.w2[r * 512 + h * 128 + ch];
;             const float gb = a.gateb[h * 128 + ch]; float ssum = 0.f;
;             for (int t = sg * 32; t < sg * 32 + 32; ++t) ssum += gla_la(gl, t, w2r, gb);
	v_fma_f32 v140, v119, v124, v8
	v_fmac_f32_e32 v140, v120, v125
	v_fmac_f32_e32 v140, v116, v126
	v_fmac_f32_e32 v140, v121, v127
	s_waitcnt lgkmcnt(6)
	v_fmac_f32_e32 v140, v117, v128
	v_fmac_f32_e32 v140, v118, v129
	v_pk_mul_f32 v[124:125], v[50:51], v[130:131]
	v_add_f32_e32 v124, v140, v124
	v_add_f32_e32 v126, v124, v125
	s_waitcnt lgkmcnt(5)
	v_pk_mul_f32 v[124:125], v[52:53], v[132:133]
	s_nop 0
	v_add_f32_e32 v124, v126, v124
	v_add_f32_e32 v126, v124, v125
	v_pk_mul_f32 v[124:125], v[88:89], v[134:135]
	s_nop 0
	v_add_f32_e32 v124, v126, v124
	v_add_f32_e32 v126, v124, v125
	s_waitcnt lgkmcnt(4)
	v_pk_mul_f32 v[124:125], v[90:91], v[136:137]
	s_nop 0
	v_add_f32_e32 v124, v126, v124
	v_add_f32_e32 v126, v124, v125
	s_waitcnt vmcnt(0)
	v_pk_mul_f32 v[124:125], v[92:93], v[138:139]
	s_nop 0
	v_add_f32_e32 v124, v126, v124
	v_add_f32_e32 v124, v124, v125
	v_min_f32_e32 v125, 0, v124
	v_mul_f32_e64 v124, |v124|, s73
	v_exp_f32_e32 v124, v124
	s_nop 0
	v_add_f32_e32 v124, 1.0, v124
	v_cmp_gt_f32_e32 vcc, s94, v124
	s_nop 1
	v_cndmask_b32_e64 v126, 0, 32, vcc
	v_ldexp_f32 v124, v124, v126
	v_log_f32_e32 v124, v124
	s_nop 0
	v_mul_f32_e32 v126, 0x3f317217, v124
	v_fma_f32 v126, v124, s97, -v126
	v_fmac_f32_e32 v126, 0x3377d1cf, v124
	v_fmac_f32_e32 v126, 0x3f317217, v124
	v_cmp_lt_f32_e64 s[12:13], |v124|, s23
	s_nop 1
	v_cndmask_b32_e64 v124, v124, v126, s[12:13]
	v_cndmask_b32_e32 v126, 0, v211, vcc
	v_sub_f32_e32 v124, v124, v126
	v_sub_f32_e32 v124, v125, v124
	v_fmac_f32_e32 v122, 0x3d800000, v124
	v_mov_b32_e32 v200, v124
	s_waitcnt lgkmcnt(0)
	v_fma_f32 v128, v119, v176, v8
	v_fmac_f32_e32 v128, v120, v177
	v_fmac_f32_e32 v128, v116, v178
	v_fmac_f32_e32 v128, v121, v179
	v_fmac_f32_e32 v128, v117, v180
	v_fmac_f32_e32 v128, v118, v181
	v_pk_mul_f32 v[124:125], v[50:51], v[182:183]
	s_nop 0
	v_add_f32_e32 v124, v128, v124
	v_add_f32_e32 v128, v124, v125
	v_pk_mul_f32 v[124:125], v[52:53], v[184:185]
	s_nop 0
	v_add_f32_e32 v124, v128, v124
	v_add_f32_e32 v128, v124, v125
	v_pk_mul_f32 v[124:125], v[88:89], v[186:187]
	s_nop 0
	v_add_f32_e32 v124, v128, v124
	v_add_f32_e32 v128, v124, v125
	v_pk_mul_f32 v[124:125], v[90:91], v[188:189]
	s_nop 0
	v_add_f32_e32 v123, v128, v124
	v_add_f32_e32 v123, v123, v125
	v_pk_mul_f32 v[124:125], v[92:93], v[190:191]
	s_nop 0
	v_add_f32_e32 v123, v123, v124
	v_add_f32_e32 v123, v123, v125
	v_min_f32_e32 v124, 0, v123
	v_mul_f32_e64 v123, |v123|, s73
	v_exp_f32_e32 v123, v123
	s_nop 0
	v_add_f32_e32 v123, 1.0, v123
	v_cmp_gt_f32_e32 vcc, s94, v123
	s_nop 1
	v_cndmask_b32_e64 v125, 0, 32, vcc
	v_ldexp_f32 v123, v123, v125
	v_log_f32_e32 v123, v123
	s_nop 0
	v_mul_f32_e32 v125, 0x3f317217, v123
	v_fma_f32 v125, v123, s97, -v125
	v_fmac_f32_e32 v125, 0x3377d1cf, v123
	v_fmac_f32_e32 v125, 0x3f317217, v123
	v_cmp_lt_f32_e64 s[12:13], |v123|, s23
	s_nop 1
	v_cndmask_b32_e64 v123, v123, v125, s[12:13]
	v_cndmask_b32_e32 v125, 0, v211, vcc
	v_sub_f32_e32 v123, v123, v125
	v_sub_f32_e32 v123, v124, v123
	v_fmac_f32_e32 v122, 0x3d800000, v123
	v_mov_b32_e32 v201, v123
	v_add_u32_e32 v123, s0, v99
	ds_read_b128 v[124:127], v123
	ds_read_b128 v[128:131], v123 offset:16
	ds_read_b128 v[132:135], v123 offset:32
	ds_read_b128 v[136:139], v123 offset:48
	ds_read_b128 v[176:179], v123 offset:64
	ds_read_b128 v[180:183], v123 offset:80
	ds_read_b128 v[184:187], v123 offset:96
	ds_read_b128 v[188:191], v123 offset:112
	s_addk_i32 s0, 0x80
	s_waitcnt vmcnt(1) lgkmcnt(7)
	v_fma_f32 v140, v119, v124, v8
	v_fmac_f32_e32 v140, v120, v125
	v_fmac_f32_e32 v140, v116, v126
	v_fmac_f32_e32 v140, v121, v127
	s_waitcnt lgkmcnt(6)
	v_fmac_f32_e32 v140, v117, v128
	v_fmac_f32_e32 v140, v118, v129
	v_pk_mul_f32 v[124:125], v[50:51], v[130:131]
	v_add_f32_e32 v124, v140, v124
	v_add_f32_e32 v126, v124, v125
	s_waitcnt lgkmcnt(5)
	v_pk_mul_f32 v[124:125], v[52:53], v[132:133]
	s_nop 0
	v_add_f32_e32 v124, v126, v124
	v_add_f32_e32 v126, v124, v125
	v_pk_mul_f32 v[124:125], v[88:89], v[134:135]
	s_nop 0
	v_add_f32_e32 v124, v126, v124
	v_add_f32_e32 v126, v124, v125
	s_waitcnt lgkmcnt(4)
	v_pk_mul_f32 v[124:125], v[90:91], v[136:137]
	s_nop 0
	v_add_f32_e32 v124, v126, v124
	v_add_f32_e32 v126, v124, v125
	s_waitcnt vmcnt(0)
	v_pk_mul_f32 v[124:125], v[92:93], v[138:139]
	s_nop 0
	v_add_f32_e32 v124, v126, v124
	v_add_f32_e32 v124, v124, v125
	v_min_f32_e32 v125, 0, v124
	v_mul_f32_e64 v124, |v124|, s73
	v_exp_f32_e32 v124, v124
	s_nop 0
	v_add_f32_e32 v124, 1.0, v124
	v_cmp_gt_f32_e32 vcc, s94, v124
	s_nop 1
	v_cndmask_b32_e64 v126, 0, 32, vcc
	v_ldexp_f32 v124, v124, v126
	v_log_f32_e32 v124, v124
	s_nop 0
	v_mul_f32_e32 v126, 0x3f317217, v124
	v_fma_f32 v126, v124, s97, -v126
	v_fmac_f32_e32 v126, 0x3377d1cf, v124
	v_fmac_f32_e32 v126, 0x3f317217, v124
	v_cmp_lt_f32_e64 s[12:13], |v124|, s23
	s_nop 1
	v_cndmask_b32_e64 v124, v124, v126, s[12:13]
	v_cndmask_b32_e32 v126, 0, v211, vcc
	v_sub_f32_e32 v124, v124, v126
	v_sub_f32_e32 v124, v125, v124
	v_fmac_f32_e32 v122, 0x3d800000, v124
	v_mov_b32_e32 v202, v124
	s_waitcnt lgkmcnt(0)
; DEVI float logsigf_(float x) { return fminf(x, 0.f) - __logf(1.f + __expf(-fabsf(x))); }
; DEVI float gla_la(const float* gl, int t, const float* w2r, float gb) { float x = gb;
; #pragma unroll
;     for (int r = 0; r < 16; ++r) x += gl[t * 16 + r] * w2r[r];
;     return logsigf_(x) * (1.f / 16.f); }
; template <int KIND>
; DEVI void mix_state_phase(unsigned char* smem, const MixArgs a) {
;     ...
;             const int ch = tid & 127, sg = tid >> 7; float w2r[16];
; #pragma unroll
;             for (int r = 0; r < 16; ++r) w2r[r] = a.w2[r * 512 + h * 128 + ch];
;             const float gb = a.gateb[h * 128 + ch]; float ssum = 0.f;
;             for (int t = sg * 32; t < sg * 32 + 32; ++t) ssum += gla_la(gl, t, w2r, gb);
	v_fma_f32 v128, v119, v176, v8
	v_fmac_f32_e32 v128, v120, v177
	v_fmac_f32_e32 v128, v116, v178
	v_fmac_f32_e32 v128, v121, v179
	v_fmac_f32_e32 v128, v117, v180
	v_fmac_f32_e32 v128, v118, v181
	v_pk_mul_f32 v[124:125], v[50:51], v[182:183]
	s_nop 0
	v_add_f32_e32 v124, v128, v124
	v_add_f32_e32 v128, v124, v125
	v_pk_mul_f32 v[124:125], v[52:53], v[184:185]
	s_nop 0
	v_add_f32_e32 v124, v128, v124
	v_add_f32_e32 v128, v124, v125
	v_pk_mul_f32 v[124:125], v[88:89], v[186:187]
	s_nop 0
	v_add_f32_e32 v124, v128, v124
	v_add_f32_e32 v128, v124, v125
	v_pk_mul_f32 v[124:125], v[90:91], v[188:189]
	s_nop 0
	v_add_f32_e32 v123, v128, v124
	v_add_f32_e32 v123, v123, v125
	v_pk_mul_f32 v[124:125], v[92:93], v[190:191]
	s_nop 0
	v_add_f32_e32 v123, v123, v124
	v_add_f32_e32 v123, v123, v125
	v_min_f32_e32 v124, 0, v123
	v_mul_f32_e64 v123, |v123|, s73
	v_exp_f32_e32 v123, v123
	s_nop 0
	v_add_f32_e32 v123, 1.0, v123
	v_cmp_gt_f32_e32 vcc, s94, v123
	s_nop 1
	v_cndmask_b32_e64 v125, 0, 32, vcc
	v_ldexp_f32 v123, v123, v125
	v_log_f32_e32 v123, v123
	s_nop 0
	v_mul_f32_e32 v125, 0x3f317217, v123
	v_fma_f32 v125, v123, s97, -v125
	v_fmac_f32_e32 v125, 0x3377d1cf, v123
	v_fmac_f32_e32 v125, 0x3f317217, v123
	v_cmp_lt_f32_e64 s[12:13], |v123|, s23
	s_nop 1
	v_cndmask_b32_e64 v123, v123, v125, s[12:13]
	v_cndmask_b32_e32 v125, 0, v211, vcc
	v_sub_f32_e32 v123, v123, v125
	v_sub_f32_e32 v123, v124, v123
	v_fmac_f32_e32 v122, 0x3d800000, v123
	v_mov_b32_e32 v203, v123
	v_add_u32_e32 v123, s0, v99
	ds_read_b128 v[124:127], v123
	ds_read_b128 v[128:131], v123 offset:16
	ds_read_b128 v[132:135], v123 offset:32
	ds_read_b128 v[136:139], v123 offset:48
	ds_read_b128 v[176:179], v123 offset:64
	ds_read_b128 v[180:183], v123 offset:80
	ds_read_b128 v[184:187], v123 offset:96
	ds_read_b128 v[188:191], v123 offset:112
	s_addk_i32 s0, 0x80
	s_waitcnt vmcnt(1) lgkmcnt(7)
	v_fma_f32 v140, v119, v124, v8
	v_fmac_f32_e32 v140, v120, v125
	v_fmac_f32_e32 v140, v116, v126
	v_fmac_f32_e32 v140, v121, v127
	s_waitcnt lgkmcnt(6)
	v_fmac_f32_e32 v140, v117, v128
	v_fmac_f32_e32 v140, v118, v129
	v_pk_mul_f32 v[124:125], v[50:51], v[130:131]
	v_add_f32_e32 v124, v140, v124
	v_add_f32_e32 v126, v124, v125
	s_waitcnt lgkmcnt(5)
	v_pk_mul_f32 v[124:125], v[52:53], v[132:133]
	s_nop 0
	v_add_f32_e32 v124, v126, v124
	v_add_f32_e32 v126, v124, v125
	v_pk_mul_f32 v[124:125], v[88:89], v[134:135]
	s_nop 0
	v_add_f32_e32 v124, v126, v124
	v_add_f32_e32 v126, v124, v125
	s_waitcnt lgkmcnt(4)
	v_pk_mul_f32 v[124:125], v[90:91], v[136:137]
	s_nop 0
	v_add_f32_e32 v124, v126, v124
	v_add_f32_e32 v126, v124, v125
	s_waitcnt vmcnt(0)
	v_pk_mul_f32 v[124:125], v[92:93], v[138:139]
	s_nop 0
	v_add_f32_e32 v124, v126, v124
	v_add_f32_e32 v124, v124, v125
	v_min_f32_e32 v125, 0, v124
	v_mul_f32_e64 v124, |v124|, s73
	v_exp_f32_e32 v124, v124
	s_nop 0
	v_add_f32_e32 v124, 1.0, v124
	v_cmp_gt_f32_e32 vcc, s94, v124
	s_nop 1
	v_cndmask_b32_e64 v126, 0, 32, vcc
	v_ldexp_f32 v124, v124, v126
	v_log_f32_e32 v124, v124
	s_nop 0
	v_mul_f32_e32 v126, 0x3f317217, v124
	v_fma_f32 v126, v124, s97, -v126
	v_fmac_f32_e32 v126, 0x3377d1cf, v124
	v_fmac_f32_e32 v126, 0x3f317217, v124
	v_cmp_lt_f32_e64 s[12:13], |v124|, s23
	s_nop 1
	v_cndmask_b32_e64 v124, v124, v126, s[12:13]
	v_cndmask_b32_e32 v126, 0, v211, vcc
	v_sub_f32_e32 v124, v124, v126
	v_sub_f32_e32 v124, v125, v124
	v_fmac_f32_e32 v122, 0x3d800000, v124
	v_mov_b32_e32 v204, v124
	s_waitcnt lgkmcnt(0)
	v_fma_f32 v128, v119, v176, v8
	v_fmac_f32_e32 v128, v120, v177
	v_fmac_f32_e32 v128, v116, v178
	v_fmac_f32_e32 v128, v121, v179
	v_fmac_f32_e32 v128, v117, v180
	v_fmac_f32_e32 v128, v118, v181
	v_pk_mul_f32 v[124:125], v[50:51], v[182:183]
	s_nop 0
	v_add_f32_e32 v124, v128, v124
	v_add_f32_e32 v128, v124, v125
	v_pk_mul_f32 v[124:125], v[52:53], v[184:185]
	s_nop 0
	v_add_f32_e32 v124, v128, v124
	v_add_f32_e32 v128, v124, v125
	v_pk_mul_f32 v[124:125], v[88:89], v[186:187]
	s_nop 0
	v_add_f32_e32 v124, v128, v124
	v_add_f32_e32 v128, v124, v125
	v_pk_mul_f32 v[124:125], v[90:91], v[188:189]
	s_nop 0
	v_add_f32_e32 v123, v128, v124
	v_add_f32_e32 v123, v123, v125
	v_pk_mul_f32 v[124:125], v[92:93], v[190:191]
	s_nop 0
	v_add_f32_e32 v123, v123, v124
	v_add_f32_e32 v123, v123, v125
	v_min_f32_e32 v124, 0, v123
	v_mul_f32_e64 v123, |v123|, s73
	v_exp_f32_e32 v123, v123
	s_nop 0
	v_add_f32_e32 v123, 1.0, v123
	v_cmp_gt_f32_e32 vcc, s94, v123
	s_nop 1
	v_cndmask_b32_e64 v125, 0, 32, vcc
	v_ldexp_f32 v123, v123, v125
	v_log_f32_e32 v123, v123
	s_nop 0
	v_mul_f32_e32 v125, 0x3f317217, v123
	v_fma_f32 v125, v123, s97, -v125
	v_fmac_f32_e32 v125, 0x3377d1cf, v123
	v_fmac_f32_e32 v125, 0x3f317217, v123
	v_cmp_lt_f32_e64 s[12:13], |v123|, s23
	s_nop 1
	v_cndmask_b32_e64 v123, v123, v125, s[12:13]
	v_cndmask_b32_e32 v125, 0, v211, vcc
	v_sub_f32_e32 v123, v123, v125
	v_sub_f32_e32 v123, v124, v123
	v_fmac_f32_e32 v122, 0x3d800000, v123
	v_mov_b32_e32 v205, v123
	v_add_u32_e32 v123, s0, v99
	ds_read_b128 v[124:127], v123
	ds_read_b128 v[128:131], v123 offset:16
	ds_read_b128 v[132:135], v123 offset:32
	ds_read_b128 v[136:139], v123 offset:48
	ds_read_b128 v[176:179], v123 offset:64
	ds_read_b128 v[180:183], v123 offset:80
	ds_read_b128 v[184:187], v123 offset:96
	ds_read_b128 v[188:191], v123 offset:112
	s_addk_i32 s0, 0x80
	s_waitcnt vmcnt(1) lgkmcnt(7)
	v_fma_f32 v140, v119, v124, v8
	v_fmac_f32_e32 v140, v120, v125
	v_fmac_f32_e32 v140, v116, v126
	v_fmac_f32_e32 v140, v121, v127
	s_waitcnt lgkmcnt(6)
	v_fmac_f32_e32 v140, v117, v128
	v_fmac_f32_e32 v140, v118, v129
	v_pk_mul_f32 v[124:125], v[50:51], v[130:131]
	v_add_f32_e32 v124, v140, v124
	v_add_f32_e32 v126, v124, v125
	s_waitcnt lgkmcnt(5)
; DEVI float logsigf_(float x) { return fminf(x, 0.f) - __logf(1.f + __expf(-fabsf(x))); }
; DEVI float gla_la(const float* gl, int t, const float* w2r, float gb) { float x = gb;
; #pragma unroll
;     for (int r = 0; r < 16; ++r) x += gl[t * 16 + r] * w2r[r];
;     return logsigf_(x) * (1.f / 16.f); }
; template <int KIND>
; DEVI void mix_state_phase(unsigned char* smem, const MixArgs a) {
;     ...
;             const int ch = tid & 127, sg = tid >> 7; float w2r[16];
; #pragma unroll
;             for (int r = 0; r < 16; ++r) w2r[r] = a.w2[r * 512 + h * 128 + ch];
;             const float gb = a.gateb[h * 128 + ch]; float ssum = 0.f;
;             for (int t = sg * 32; t < sg * 32 + 32; ++t) ssum += gla_la(gl, t, w2r, gb);
	v_pk_mul_f32 v[124:125], v[52:53], v[132:133]
	s_nop 0
	v_add_f32_e32 v124, v126, v124
	v_add_f32_e32 v126, v124, v125
	v_pk_mul_f32 v[124:125], v[88:89], v[134:135]
	s_nop 0
	v_add_f32_e32 v124, v126, v124
	v_add_f32_e32 v126, v124, v125
	s_waitcnt lgkmcnt(4)
	v_pk_mul_f32 v[124:125], v[90:91], v[136:137]
	s_nop 0
	v_add_f32_e32 v124, v126, v124
	v_add_f32_e32 v126, v124, v125
	s_waitcnt vmcnt(0)
	v_pk_mul_f32 v[124:125], v[92:93], v[138:139]
	s_nop 0
	v_add_f32_e32 v124, v126, v124
	v_add_f32_e32 v124, v124, v125
	v_min_f32_e32 v125, 0, v124
	v_mul_f32_e64 v124, |v124|, s73
	v_exp_f32_e32 v124, v124
	s_nop 0
	v_add_f32_e32 v124, 1.0, v124
	v_cmp_gt_f32_e32 vcc, s94, v124
	s_nop 1
	v_cndmask_b32_e64 v126, 0, 32, vcc
	v_ldexp_f32 v124, v124, v126
	v_log_f32_e32 v124, v124
	s_nop 0
	v_mul_f32_e32 v126, 0x3f317217, v124
	v_fma_f32 v126, v124, s97, -v126
	v_fmac_f32_e32 v126, 0x3377d1cf, v124
	v_fmac_f32_e32 v126, 0x3f317217, v124
	v_cmp_lt_f32_e64 s[12:13], |v124|, s23
	s_nop 1
	v_cndmask_b32_e64 v124, v124, v126, s[12:13]
	v_cndmask_b32_e32 v126, 0, v211, vcc
	v_sub_f32_e32 v124, v124, v126
	v_sub_f32_e32 v124, v125, v124
	v_fmac_f32_e32 v122, 0x3d800000, v124
	v_mov_b32_e32 v206, v124
	s_waitcnt lgkmcnt(0)
	v_fma_f32 v128, v119, v176, v8
	v_fmac_f32_e32 v128, v120, v177
	v_fmac_f32_e32 v128, v116, v178
	v_fmac_f32_e32 v128, v121, v179
	v_fmac_f32_e32 v128, v117, v180
	v_fmac_f32_e32 v128, v118, v181
	v_pk_mul_f32 v[124:125], v[50:51], v[182:183]
	s_nop 0
	v_add_f32_e32 v124, v128, v124
	v_add_f32_e32 v128, v124, v125
	v_pk_mul_f32 v[124:125], v[52:53], v[184:185]
	s_nop 0
	v_add_f32_e32 v124, v128, v124
	v_add_f32_e32 v128, v124, v125
	v_pk_mul_f32 v[124:125], v[88:89], v[186:187]
	s_nop 0
	v_add_f32_e32 v124, v128, v124
	v_add_f32_e32 v128, v124, v125
	v_pk_mul_f32 v[124:125], v[90:91], v[188:189]
	s_nop 0
	v_add_f32_e32 v123, v128, v124
	v_add_f32_e32 v123, v123, v125
	v_pk_mul_f32 v[124:125], v[92:93], v[190:191]
	s_nop 0
	v_add_f32_e32 v123, v123, v124
	v_add_f32_e32 v123, v123, v125
	v_min_f32_e32 v124, 0, v123
	v_mul_f32_e64 v123, |v123|, s73
	v_exp_f32_e32 v123, v123
	s_nop 0
	v_add_f32_e32 v123, 1.0, v123
	v_cmp_gt_f32_e32 vcc, s94, v123
	s_nop 1
	v_cndmask_b32_e64 v125, 0, 32, vcc
	v_ldexp_f32 v123, v123, v125
	v_log_f32_e32 v123, v123
	s_nop 0
	v_mul_f32_e32 v125, 0x3f317217, v123
	v_fma_f32 v125, v123, s97, -v125
	v_fmac_f32_e32 v125, 0x3377d1cf, v123
	v_fmac_f32_e32 v125, 0x3f317217, v123
	v_cmp_lt_f32_e64 s[12:13], |v123|, s23
	s_nop 1
	v_cndmask_b32_e64 v123, v123, v125, s[12:13]
	v_cndmask_b32_e32 v125, 0, v211, vcc
	v_sub_f32_e32 v123, v123, v125
	v_sub_f32_e32 v123, v124, v123
	v_fmac_f32_e32 v122, 0x3d800000, v123
	v_mov_b32_e32 v207, v123
	v_add_u32_e32 v123, s0, v99
	ds_read_b128 v[124:127], v123
	ds_read_b128 v[128:131], v123 offset:16
	ds_read_b128 v[132:135], v123 offset:32
	ds_read_b128 v[136:139], v123 offset:48
	ds_read_b128 v[176:179], v123 offset:64
	ds_read_b128 v[180:183], v123 offset:80
	ds_read_b128 v[184:187], v123 offset:96
	ds_read_b128 v[188:191], v123 offset:112
	s_addk_i32 s0, 0x80
	s_waitcnt vmcnt(1) lgkmcnt(7)
	v_fma_f32 v140, v119, v124, v8
	v_fmac_f32_e32 v140, v120, v125
	v_fmac_f32_e32 v140, v116, v126
	v_fmac_f32_e32 v140, v121, v127
	s_waitcnt lgkmcnt(6)
	v_fmac_f32_e32 v140, v117, v128
	v_fmac_f32_e32 v140, v118, v129
	v_pk_mul_f32 v[124:125], v[50:51], v[130:131]
	v_add_f32_e32 v124, v140, v124
	v_add_f32_e32 v126, v124, v125
	s_waitcnt lgkmcnt(5)
	v_pk_mul_f32 v[124:125], v[52:53], v[132:133]
	s_nop 0
	v_add_f32_e32 v124, v126, v124
	v_add_f32_e32 v126, v124, v125
	v_pk_mul_f32 v[124:125], v[88:89], v[134:135]
	s_nop 0
	v_add_f32_e32 v124, v126, v124
	v_add_f32_e32 v126, v124, v125
	s_waitcnt lgkmcnt(4)
	v_pk_mul_f32 v[124:125], v[90:91], v[136:137]
	s_nop 0
	v_add_f32_e32 v124, v126, v124
	v_add_f32_e32 v126, v124, v125
	s_waitcnt vmcnt(0)
	v_pk_mul_f32 v[124:125], v[92:93], v[138:139]
	s_nop 0
	v_add_f32_e32 v124, v126, v124
	v_add_f32_e32 v124, v124, v125
	v_min_f32_e32 v125, 0, v124
	v_mul_f32_e64 v124, |v124|, s73
	v_exp_f32_e32 v124, v124
	s_nop 0
	v_add_f32_e32 v124, 1.0, v124
	v_cmp_gt_f32_e32 vcc, s94, v124
	s_nop 1
	v_cndmask_b32_e64 v126, 0, 32, vcc
	v_ldexp_f32 v124, v124, v126
	v_log_f32_e32 v124, v124
	s_nop 0
	v_mul_f32_e32 v126, 0x3f317217, v124
	v_fma_f32 v126, v124, s97, -v126
	v_fmac_f32_e32 v126, 0x3377d1cf, v124
	v_fmac_f32_e32 v126, 0x3f317217, v124
	v_cmp_lt_f32_e64 s[12:13], |v124|, s23
	s_nop 1
	v_cndmask_b32_e64 v124, v124, v126, s[12:13]
	v_cndmask_b32_e32 v126, 0, v211, vcc
	v_sub_f32_e32 v124, v124, v126
	v_sub_f32_e32 v124, v125, v124
	v_fmac_f32_e32 v122, 0x3d800000, v124
	v_mov_b32_e32 v213, v124
	s_waitcnt lgkmcnt(0)
	v_fma_f32 v128, v119, v176, v8
	v_fmac_f32_e32 v128, v120, v177
	v_fmac_f32_e32 v128, v116, v178
	v_fmac_f32_e32 v128, v121, v179
	v_fmac_f32_e32 v128, v117, v180
	v_fmac_f32_e32 v128, v118, v181
	v_pk_mul_f32 v[124:125], v[50:51], v[182:183]
	s_nop 0
	v_add_f32_e32 v124, v128, v124
	v_add_f32_e32 v128, v124, v125
	v_pk_mul_f32 v[124:125], v[52:53], v[184:185]
	s_nop 0
	v_add_f32_e32 v124, v128, v124
	v_add_f32_e32 v128, v124, v125
	v_pk_mul_f32 v[124:125], v[88:89], v[186:187]
	s_nop 0
	v_add_f32_e32 v124, v128, v124
	v_add_f32_e32 v128, v124, v125
	v_pk_mul_f32 v[124:125], v[90:91], v[188:189]
	s_nop 0
	v_add_f32_e32 v123, v128, v124
	v_add_f32_e32 v123, v123, v125
	v_pk_mul_f32 v[124:125], v[92:93], v[190:191]
	s_nop 0
	v_add_f32_e32 v123, v123, v124
	v_add_f32_e32 v123, v123, v125
	v_min_f32_e32 v124, 0, v123
	v_mul_f32_e64 v123, |v123|, s73
	v_exp_f32_e32 v123, v123
	s_nop 0
	v_add_f32_e32 v123, 1.0, v123
	v_cmp_gt_f32_e32 vcc, s94, v123
	s_nop 1
	v_cndmask_b32_e64 v125, 0, 32, vcc
	v_ldexp_f32 v123, v123, v125
	v_log_f32_e32 v123, v123
	s_nop 0
	v_mul_f32_e32 v125, 0x3f317217, v123
	v_fma_f32 v125, v123, s97, -v125
	v_fmac_f32_e32 v125, 0x3377d1cf, v123
	v_fmac_f32_e32 v125, 0x3f317217, v123
	v_cmp_lt_f32_e64 s[12:13], |v123|, s23
	s_nop 1
	v_cndmask_b32_e64 v123, v123, v125, s[12:13]
	v_cndmask_b32_e32 v125, 0, v211, vcc
	v_sub_f32_e32 v123, v123, v125
	v_sub_f32_e32 v123, v124, v123
	v_fmac_f32_e32 v122, 0x3d800000, v123
	v_mov_b32_e32 v214, v123
	v_add_u32_e32 v123, s0, v99
	ds_read_b128 v[124:127], v123
	ds_read_b128 v[128:131], v123 offset:16
	ds_read_b128 v[132:135], v123 offset:32
	ds_read_b128 v[136:139], v123 offset:48
	ds_read_b128 v[176:179], v123 offset:64
	ds_read_b128 v[180:183], v123 offset:80
	ds_read_b128 v[184:187], v123 offset:96
	ds_read_b128 v[188:191], v123 offset:112
	s_addk_i32 s0, 0x80
	s_waitcnt vmcnt(1) lgkmcnt(7)
; DEVI float logsigf_(float x) { return fminf(x, 0.f) - __logf(1.f + __expf(-fabsf(x))); }
; DEVI float gla_la(const float* gl, int t, const float* w2r, float gb) { float x = gb;
; #pragma unroll
;     for (int r = 0; r < 16; ++r) x += gl[t * 16 + r] * w2r[r];
;     return logsigf_(x) * (1.f / 16.f); }
; template <int KIND>
; DEVI void mix_state_phase(unsigned char* smem, const MixArgs a) {
;     ...
;             const int ch = tid & 127, sg = tid >> 7; float w2r[16];
; #pragma unroll
;             for (int r = 0; r < 16; ++r) w2r[r] = a.w2[r * 512 + h * 128 + ch];
;             const float gb = a.gateb[h * 128 + ch]; float ssum = 0.f;
;             for (int t = sg * 32; t < sg * 32 + 32; ++t) ssum += gla_la(gl, t, w2r, gb);
	v_fma_f32 v140, v119, v124, v8
	v_fmac_f32_e32 v140, v120, v125
	v_fmac_f32_e32 v140, v116, v126
	v_fmac_f32_e32 v140, v121, v127
	s_waitcnt lgkmcnt(6)
	v_fmac_f32_e32 v140, v117, v128
	v_fmac_f32_e32 v140, v118, v129
	v_pk_mul_f32 v[124:125], v[50:51], v[130:131]
	v_add_f32_e32 v124, v140, v124
	v_add_f32_e32 v126, v124, v125
	s_waitcnt lgkmcnt(5)
	v_pk_mul_f32 v[124:125], v[52:53], v[132:133]
	s_nop 0
	v_add_f32_e32 v124, v126, v124
	v_add_f32_e32 v126, v124, v125
	v_pk_mul_f32 v[124:125], v[88:89], v[134:135]
	s_nop 0
	v_add_f32_e32 v124, v126, v124
	v_add_f32_e32 v126, v124, v125
	s_waitcnt lgkmcnt(4)
	v_pk_mul_f32 v[124:125], v[90:91], v[136:137]
	s_nop 0
	v_add_f32_e32 v124, v126, v124
	v_add_f32_e32 v126, v124, v125
	s_waitcnt vmcnt(0)
	v_pk_mul_f32 v[124:125], v[92:93], v[138:139]
	s_nop 0
	v_add_f32_e32 v124, v126, v124
	v_add_f32_e32 v124, v124, v125
	v_min_f32_e32 v125, 0, v124
	v_mul_f32_e64 v124, |v124|, s73
	v_exp_f32_e32 v124, v124
	s_nop 0
	v_add_f32_e32 v124, 1.0, v124
	v_cmp_gt_f32_e32 vcc, s94, v124
	s_nop 1
	v_cndmask_b32_e64 v126, 0, 32, vcc
	v_ldexp_f32 v124, v124, v126
	v_log_f32_e32 v124, v124
	s_nop 0
	v_mul_f32_e32 v126, 0x3f317217, v124
	v_fma_f32 v126, v124, s97, -v126
	v_fmac_f32_e32 v126, 0x3377d1cf, v124
	v_fmac_f32_e32 v126, 0x3f317217, v124
	v_cmp_lt_f32_e64 s[12:13], |v124|, s23
	s_nop 1
	v_cndmask_b32_e64 v124, v124, v126, s[12:13]
	v_cndmask_b32_e32 v126, 0, v211, vcc
	v_sub_f32_e32 v124, v124, v126
	v_sub_f32_e32 v124, v125, v124
	v_fmac_f32_e32 v122, 0x3d800000, v124
	v_mov_b32_e32 v215, v124
	s_waitcnt lgkmcnt(0)
	v_fma_f32 v128, v119, v176, v8
	v_fmac_f32_e32 v128, v120, v177
	v_fmac_f32_e32 v128, v116, v178
	v_fmac_f32_e32 v128, v121, v179
	v_fmac_f32_e32 v128, v117, v180
	v_fmac_f32_e32 v128, v118, v181
	v_pk_mul_f32 v[124:125], v[50:51], v[182:183]
	s_nop 0
	v_add_f32_e32 v124, v128, v124
	v_add_f32_e32 v128, v124, v125
	v_pk_mul_f32 v[124:125], v[52:53], v[184:185]
	s_nop 0
	v_add_f32_e32 v124, v128, v124
	v_add_f32_e32 v128, v124, v125
	v_pk_mul_f32 v[124:125], v[88:89], v[186:187]
	s_nop 0
	v_add_f32_e32 v124, v128, v124
	v_add_f32_e32 v128, v124, v125
	v_pk_mul_f32 v[124:125], v[90:91], v[188:189]
	s_nop 0
	v_add_f32_e32 v123, v128, v124
	v_add_f32_e32 v123, v123, v125
	v_pk_mul_f32 v[124:125], v[92:93], v[190:191]
	s_nop 0
	v_add_f32_e32 v123, v123, v124
	v_add_f32_e32 v123, v123, v125
	v_min_f32_e32 v124, 0, v123
	v_mul_f32_e64 v123, |v123|, s73
	v_exp_f32_e32 v123, v123
	s_nop 0
	v_add_f32_e32 v123, 1.0, v123
	v_cmp_gt_f32_e32 vcc, s94, v123
	s_nop 1
	v_cndmask_b32_e64 v125, 0, 32, vcc
	v_ldexp_f32 v123, v123, v125
	v_log_f32_e32 v123, v123
	s_nop 0
	v_mul_f32_e32 v125, 0x3f317217, v123
	v_fma_f32 v125, v123, s97, -v125
	v_fmac_f32_e32 v125, 0x3377d1cf, v123
	v_fmac_f32_e32 v125, 0x3f317217, v123
	v_cmp_lt_f32_e64 s[12:13], |v123|, s23
	s_nop 1
	v_cndmask_b32_e64 v123, v123, v125, s[12:13]
	v_cndmask_b32_e32 v125, 0, v211, vcc
	v_sub_f32_e32 v123, v123, v125
	v_sub_f32_e32 v123, v124, v123
	v_fmac_f32_e32 v122, 0x3d800000, v123
	v_mov_b32_e32 v216, v123
	v_add_u32_e32 v123, s0, v99
	ds_read_b128 v[124:127], v123
	ds_read_b128 v[128:131], v123 offset:16
	ds_read_b128 v[132:135], v123 offset:32
	ds_read_b128 v[136:139], v123 offset:48
	ds_read_b128 v[176:179], v123 offset:64
	ds_read_b128 v[180:183], v123 offset:80
	ds_read_b128 v[184:187], v123 offset:96
	ds_read_b128 v[188:191], v123 offset:112
	s_addk_i32 s0, 0x80
	s_waitcnt vmcnt(1) lgkmcnt(7)
	v_fma_f32 v140, v119, v124, v8
	v_fmac_f32_e32 v140, v120, v125
	v_fmac_f32_e32 v140, v116, v126
	v_fmac_f32_e32 v140, v121, v127
	s_waitcnt lgkmcnt(6)
	v_fmac_f32_e32 v140, v117, v128
	v_fmac_f32_e32 v140, v118, v129
	v_pk_mul_f32 v[124:125], v[50:51], v[130:131]
	v_add_f32_e32 v124, v140, v124
	v_add_f32_e32 v126, v124, v125
	s_waitcnt lgkmcnt(5)
	v_pk_mul_f32 v[124:125], v[52:53], v[132:133]
	s_nop 0
	v_add_f32_e32 v124, v126, v124
	v_add_f32_e32 v126, v124, v125
	v_pk_mul_f32 v[124:125], v[88:89], v[134:135]
	s_nop 0
	v_add_f32_e32 v124, v126, v124
	v_add_f32_e32 v126, v124, v125
	s_waitcnt lgkmcnt(4)
	v_pk_mul_f32 v[124:125], v[90:91], v[136:137]
	s_nop 0
	v_add_f32_e32 v124, v126, v124
	v_add_f32_e32 v126, v124, v125
	s_waitcnt vmcnt(0)
	v_pk_mul_f32 v[124:125], v[92:93], v[138:139]
	s_nop 0
	v_add_f32_e32 v124, v126, v124
	v_add_f32_e32 v124, v124, v125
	v_min_f32_e32 v125, 0, v124
	v_mul_f32_e64 v124, |v124|, s73
	v_exp_f32_e32 v124, v124
	s_nop 0
	v_add_f32_e32 v124, 1.0, v124
	v_cmp_gt_f32_e32 vcc, s94, v124
	s_nop 1
	v_cndmask_b32_e64 v126, 0, 32, vcc
	v_ldexp_f32 v124, v124, v126
	v_log_f32_e32 v124, v124
	s_nop 0
	v_mul_f32_e32 v126, 0x3f317217, v124
	v_fma_f32 v126, v124, s97, -v126
	v_fmac_f32_e32 v126, 0x3377d1cf, v124
	v_fmac_f32_e32 v126, 0x3f317217, v124
	v_cmp_lt_f32_e64 s[12:13], |v124|, s23
	s_nop 1
	v_cndmask_b32_e64 v124, v124, v126, s[12:13]
	v_cndmask_b32_e32 v126, 0, v211, vcc
	v_sub_f32_e32 v124, v124, v126
	v_sub_f32_e32 v124, v125, v124
	v_fmac_f32_e32 v122, 0x3d800000, v124
	v_mov_b32_e32 v217, v124
	s_waitcnt lgkmcnt(0)
; DEVI float logsigf_(float x) { return fminf(x, 0.f) - __logf(1.f + __expf(-fabsf(x))); }
; DEVI float gla_la(const float* gl, int t, const float* w2r, float gb) { float x = gb;
; #pragma unroll
;     for (int r = 0; r < 16; ++r) x += gl[t * 16 + r] * w2r[r];
;     return logsigf_(x) * (1.f / 16.f); }
; template <int KIND>
; DEVI void mix_state_phase(unsigned char* smem, const MixArgs a) {
;     ...
;             const int ch = tid & 127, sg = tid >> 7; float w2r[16];
; #pragma unroll
;             for (int r = 0; r < 16; ++r) w2r[r] = a.w2[r * 512 + h * 128 + ch];
;             const float gb = a.gateb[h * 128 + ch]; float ssum = 0.f;
;             for (int t = sg * 32; t < sg * 32 + 32; ++t) ssum += gla_la(gl, t, w2r, gb);
	v_fma_f32 v128, v119, v176, v8
	v_fmac_f32_e32 v128, v120, v177
	v_fmac_f32_e32 v128, v116, v178
	v_fmac_f32_e32 v128, v121, v179
	v_fmac_f32_e32 v128, v117, v180
	v_fmac_f32_e32 v128, v118, v181
	v_pk_mul_f32 v[124:125], v[50:51], v[182:183]
	s_nop 0
	v_add_f32_e32 v124, v128, v124
	v_add_f32_e32 v128, v124, v125
	v_pk_mul_f32 v[124:125], v[52:53], v[184:185]
	s_nop 0
	v_add_f32_e32 v124, v128, v124
	v_add_f32_e32 v128, v124, v125
	v_pk_mul_f32 v[124:125], v[88:89], v[186:187]
	s_nop 0
	v_add_f32_e32 v124, v128, v124
	v_add_f32_e32 v128, v124, v125
	v_pk_mul_f32 v[124:125], v[90:91], v[188:189]
	s_nop 0
	v_add_f32_e32 v123, v128, v124
	v_add_f32_e32 v123, v123, v125
	v_pk_mul_f32 v[124:125], v[92:93], v[190:191]
	s_nop 0
	v_add_f32_e32 v123, v123, v124
	v_add_f32_e32 v123, v123, v125
	v_min_f32_e32 v124, 0, v123
	v_mul_f32_e64 v123, |v123|, s73
	v_exp_f32_e32 v123, v123
	s_nop 0
	v_add_f32_e32 v123, 1.0, v123
	v_cmp_gt_f32_e32 vcc, s94, v123
	s_nop 1
	v_cndmask_b32_e64 v125, 0, 32, vcc
	v_ldexp_f32 v123, v123, v125
	v_log_f32_e32 v123, v123
	s_nop 0
	v_mul_f32_e32 v125, 0x3f317217, v123
	v_fma_f32 v125, v123, s97, -v125
	v_fmac_f32_e32 v125, 0x3377d1cf, v123
	v_fmac_f32_e32 v125, 0x3f317217, v123
	v_cmp_lt_f32_e64 s[12:13], |v123|, s23
	s_nop 1
	v_cndmask_b32_e64 v123, v123, v125, s[12:13]
	v_cndmask_b32_e32 v125, 0, v211, vcc
	v_sub_f32_e32 v123, v123, v125
	v_sub_f32_e32 v123, v124, v123
	v_fmac_f32_e32 v122, 0x3d800000, v123
	v_mov_b32_e32 v218, v123
	v_add_u32_e32 v123, s0, v99
	ds_read_b128 v[124:127], v123
	ds_read_b128 v[128:131], v123 offset:16
	ds_read_b128 v[132:135], v123 offset:32
	ds_read_b128 v[136:139], v123 offset:48
	ds_read_b128 v[176:179], v123 offset:64
	ds_read_b128 v[180:183], v123 offset:80
	ds_read_b128 v[184:187], v123 offset:96
	ds_read_b128 v[188:191], v123 offset:112
	s_addk_i32 s0, 0x80
	s_waitcnt vmcnt(1) lgkmcnt(7)
	v_fma_f32 v140, v119, v124, v8
	v_fmac_f32_e32 v140, v120, v125
	v_fmac_f32_e32 v140, v116, v126
	v_fmac_f32_e32 v140, v121, v127
	s_waitcnt lgkmcnt(6)
	v_fmac_f32_e32 v140, v117, v128
	v_fmac_f32_e32 v140, v118, v129
	v_pk_mul_f32 v[124:125], v[50:51], v[130:131]
	v_add_f32_e32 v124, v140, v124
	v_add_f32_e32 v126, v124, v125
	s_waitcnt lgkmcnt(5)
	v_pk_mul_f32 v[124:125], v[52:53], v[132:133]
	s_nop 0
	v_add_f32_e32 v124, v126, v124
	v_add_f32_e32 v126, v124, v125
	v_pk_mul_f32 v[124:125], v[88:89], v[134:135]
	s_nop 0
	v_add_f32_e32 v124, v126, v124
	v_add_f32_e32 v126, v124, v125
	s_waitcnt lgkmcnt(4)
	v_pk_mul_f32 v[124:125], v[90:91], v[136:137]
	s_nop 0
	v_add_f32_e32 v124, v126, v124
	v_add_f32_e32 v126, v124, v125
	s_waitcnt vmcnt(0)
	v_pk_mul_f32 v[124:125], v[92:93], v[138:139]
	s_nop 0
	v_add_f32_e32 v124, v126, v124
	v_add_f32_e32 v124, v124, v125
	v_min_f32_e32 v125, 0, v124
	v_mul_f32_e64 v124, |v124|, s73
	v_exp_f32_e32 v124, v124
	s_nop 0
	v_add_f32_e32 v124, 1.0, v124
	v_cmp_gt_f32_e32 vcc, s94, v124
	s_nop 1
	v_cndmask_b32_e64 v126, 0, 32, vcc
	v_ldexp_f32 v124, v124, v126
	v_log_f32_e32 v124, v124
	s_nop 0
	v_mul_f32_e32 v126, 0x3f317217, v124
	v_fma_f32 v126, v124, s97, -v126
	v_fmac_f32_e32 v126, 0x3377d1cf, v124
	v_fmac_f32_e32 v126, 0x3f317217, v124
	v_cmp_lt_f32_e64 s[12:13], |v124|, s23
	s_nop 1
	v_cndmask_b32_e64 v124, v124, v126, s[12:13]
	v_cndmask_b32_e32 v126, 0, v211, vcc
	v_sub_f32_e32 v124, v124, v126
	v_sub_f32_e32 v124, v125, v124
	v_fmac_f32_e32 v122, 0x3d800000, v124
	v_mov_b32_e32 v219, v124
	s_waitcnt lgkmcnt(0)
	v_fma_f32 v128, v119, v176, v8
	v_fmac_f32_e32 v128, v120, v177
	v_fmac_f32_e32 v128, v116, v178
	v_fmac_f32_e32 v128, v121, v179
	v_fmac_f32_e32 v128, v117, v180
	v_fmac_f32_e32 v128, v118, v181
	v_pk_mul_f32 v[124:125], v[50:51], v[182:183]
	s_nop 0
	v_add_f32_e32 v124, v128, v124
	v_add_f32_e32 v128, v124, v125
	v_pk_mul_f32 v[124:125], v[52:53], v[184:185]
	s_nop 0
	v_add_f32_e32 v124, v128, v124
	v_add_f32_e32 v128, v124, v125
	v_pk_mul_f32 v[124:125], v[88:89], v[186:187]
	s_nop 0
	v_add_f32_e32 v124, v128, v124
	v_add_f32_e32 v128, v124, v125
	v_pk_mul_f32 v[124:125], v[90:91], v[188:189]
	s_nop 0
	v_add_f32_e32 v123, v128, v124
	v_add_f32_e32 v123, v123, v125
	v_pk_mul_f32 v[124:125], v[92:93], v[190:191]
	s_nop 0
	v_add_f32_e32 v123, v123, v124
	v_add_f32_e32 v123, v123, v125
	v_min_f32_e32 v124, 0, v123
	v_mul_f32_e64 v123, |v123|, s73
	v_exp_f32_e32 v123, v123
	s_nop 0
	v_add_f32_e32 v123, 1.0, v123
	v_cmp_gt_f32_e32 vcc, s94, v123
	s_nop 1
	v_cndmask_b32_e64 v125, 0, 32, vcc
	v_ldexp_f32 v123, v123, v125
	v_log_f32_e32 v123, v123
	s_nop 0
	v_mul_f32_e32 v125, 0x3f317217, v123
	v_fma_f32 v125, v123, s97, -v125
	v_fmac_f32_e32 v125, 0x3377d1cf, v123
	v_fmac_f32_e32 v125, 0x3f317217, v123
	v_cmp_lt_f32_e64 s[12:13], |v123|, s23
	s_nop 1
	v_cndmask_b32_e64 v123, v123, v125, s[12:13]
	v_cndmask_b32_e32 v125, 0, v211, vcc
	v_sub_f32_e32 v123, v123, v125
	v_sub_f32_e32 v123, v124, v123
	v_fmac_f32_e32 v122, 0x3d800000, v123
	v_mov_b32_e32 v220, v123
	v_add_u32_e32 v123, s0, v99
	ds_read_b128 v[124:127], v123
	ds_read_b128 v[128:131], v123 offset:16
	ds_read_b128 v[132:135], v123 offset:32
	ds_read_b128 v[136:139], v123 offset:48
	ds_read_b128 v[176:179], v123 offset:64
	ds_read_b128 v[180:183], v123 offset:80
	ds_read_b128 v[184:187], v123 offset:96
	ds_read_b128 v[188:191], v123 offset:112
	s_addk_i32 s0, 0x80
	s_waitcnt vmcnt(1) lgkmcnt(7)
	v_fma_f32 v140, v119, v124, v8
	v_fmac_f32_e32 v140, v120, v125
	v_fmac_f32_e32 v140, v116, v126
	v_fmac_f32_e32 v140, v121, v127
	s_waitcnt lgkmcnt(6)
	v_fmac_f32_e32 v140, v117, v128
	v_fmac_f32_e32 v140, v118, v129
	v_pk_mul_f32 v[124:125], v[50:51], v[130:131]
	v_add_f32_e32 v124, v140, v124
	v_add_f32_e32 v126, v124, v125
	s_waitcnt lgkmcnt(5)
; DEVI float logsigf_(float x) { return fminf(x, 0.f) - __logf(1.f + __expf(-fabsf(x))); }
; DEVI float gla_la(const float* gl, int t, const float* w2r, float gb) { float x = gb;
; #pragma unroll
;     for (int r = 0; r < 16; ++r) x += gl[t * 16 + r] * w2r[r];
;     return logsigf_(x) * (1.f / 16.f); }
; template <int KIND>
; DEVI void mix_state_phase(unsigned char* smem, const MixArgs a) {
;     ...
;             const int ch = tid & 127, sg = tid >> 7; float w2r[16];
; #pragma unroll
;             for (int r = 0; r < 16; ++r) w2r[r] = a.w2[r * 512 + h * 128 + ch];
;             const float gb = a.gateb[h * 128 + ch]; float ssum = 0.f;
;             for (int t = sg * 32; t < sg * 32 + 32; ++t) ssum += gla_la(gl, t, w2r, gb);
	v_pk_mul_f32 v[124:125], v[52:53], v[132:133]
	s_nop 0
	v_add_f32_e32 v124, v126, v124
	v_add_f32_e32 v126, v124, v125
	v_pk_mul_f32 v[124:125], v[88:89], v[134:135]
	s_nop 0
	v_add_f32_e32 v124, v126, v124
	v_add_f32_e32 v126, v124, v125
	s_waitcnt lgkmcnt(4)
	v_pk_mul_f32 v[124:125], v[90:91], v[136:137]
	s_nop 0
	v_add_f32_e32 v124, v126, v124
	v_add_f32_e32 v126, v124, v125
	s_waitcnt vmcnt(0)
	v_pk_mul_f32 v[124:125], v[92:93], v[138:139]
	s_nop 0
	v_add_f32_e32 v124, v126, v124
	v_add_f32_e32 v124, v124, v125
	v_min_f32_e32 v125, 0, v124
	v_mul_f32_e64 v124, |v124|, s73
	v_exp_f32_e32 v124, v124
	s_nop 0
	v_add_f32_e32 v124, 1.0, v124
	v_cmp_gt_f32_e32 vcc, s94, v124
	s_nop 1
	v_cndmask_b32_e64 v126, 0, 32, vcc
	v_ldexp_f32 v124, v124, v126
	v_log_f32_e32 v124, v124
	s_nop 0
	v_mul_f32_e32 v126, 0x3f317217, v124
	v_fma_f32 v126, v124, s97, -v126
	v_fmac_f32_e32 v126, 0x3377d1cf, v124
	v_fmac_f32_e32 v126, 0x3f317217, v124
	v_cmp_lt_f32_e64 s[12:13], |v124|, s23
	s_nop 1
	v_cndmask_b32_e64 v124, v124, v126, s[12:13]
	v_cndmask_b32_e32 v126, 0, v211, vcc
	v_sub_f32_e32 v124, v124, v126
	v_sub_f32_e32 v124, v125, v124
	v_fmac_f32_e32 v122, 0x3d800000, v124
	v_mov_b32_e32 v221, v124
	s_waitcnt lgkmcnt(0)
	v_fma_f32 v128, v119, v176, v8
	v_fmac_f32_e32 v128, v120, v177
	v_fmac_f32_e32 v128, v116, v178
	v_fmac_f32_e32 v128, v121, v179
	v_fmac_f32_e32 v128, v117, v180
	v_fmac_f32_e32 v128, v118, v181
	v_pk_mul_f32 v[124:125], v[50:51], v[182:183]
	s_nop 0
	v_add_f32_e32 v124, v128, v124
	v_add_f32_e32 v128, v124, v125
	v_pk_mul_f32 v[124:125], v[52:53], v[184:185]
	s_nop 0
	v_add_f32_e32 v124, v128, v124
	v_add_f32_e32 v128, v124, v125
	v_pk_mul_f32 v[124:125], v[88:89], v[186:187]
	s_nop 0
	v_add_f32_e32 v124, v128, v124
	v_add_f32_e32 v128, v124, v125
	v_pk_mul_f32 v[124:125], v[90:91], v[188:189]
	s_nop 0
	v_add_f32_e32 v123, v128, v124
	v_add_f32_e32 v123, v123, v125
	v_pk_mul_f32 v[124:125], v[92:93], v[190:191]
	s_nop 0
	v_add_f32_e32 v123, v123, v124
	v_add_f32_e32 v123, v123, v125
	v_min_f32_e32 v124, 0, v123
	v_mul_f32_e64 v123, |v123|, s73
	v_exp_f32_e32 v123, v123
	s_nop 0
	v_add_f32_e32 v123, 1.0, v123
	v_cmp_gt_f32_e32 vcc, s94, v123
	s_nop 1
	v_cndmask_b32_e64 v125, 0, 32, vcc
	v_ldexp_f32 v123, v123, v125
	v_log_f32_e32 v123, v123
	s_nop 0
	v_mul_f32_e32 v125, 0x3f317217, v123
	v_fma_f32 v125, v123, s97, -v125
	v_fmac_f32_e32 v125, 0x3377d1cf, v123
	v_fmac_f32_e32 v125, 0x3f317217, v123
	v_cmp_lt_f32_e64 s[12:13], |v123|, s23
	s_nop 1
	v_cndmask_b32_e64 v123, v123, v125, s[12:13]
	v_cndmask_b32_e32 v125, 0, v211, vcc
	v_sub_f32_e32 v123, v123, v125
	v_sub_f32_e32 v123, v124, v123
	v_fmac_f32_e32 v122, 0x3d800000, v123
	v_mov_b32_e32 v222, v123
	v_add_u32_e32 v123, s0, v99
	ds_read_b128 v[124:127], v123
	ds_read_b128 v[128:131], v123 offset:16
	ds_read_b128 v[132:135], v123 offset:32
	ds_read_b128 v[136:139], v123 offset:48
	ds_read_b128 v[176:179], v123 offset:64
	ds_read_b128 v[180:183], v123 offset:80
	ds_read_b128 v[184:187], v123 offset:96
	ds_read_b128 v[188:191], v123 offset:112
	s_addk_i32 s0, 0x80
	s_waitcnt vmcnt(1) lgkmcnt(7)
	v_fma_f32 v140, v119, v124, v8
	v_fmac_f32_e32 v140, v120, v125
	v_fmac_f32_e32 v140, v116, v126
	v_fmac_f32_e32 v140, v121, v127
	s_waitcnt lgkmcnt(6)
	v_fmac_f32_e32 v140, v117, v128
	v_fmac_f32_e32 v140, v118, v129
	v_pk_mul_f32 v[124:125], v[50:51], v[130:131]
	v_add_f32_e32 v124, v140, v124
	v_add_f32_e32 v126, v124, v125
	s_waitcnt lgkmcnt(5)
	v_pk_mul_f32 v[124:125], v[52:53], v[132:133]
	s_nop 0
	v_add_f32_e32 v124, v126, v124
	v_add_f32_e32 v126, v124, v125
	v_pk_mul_f32 v[124:125], v[88:89], v[134:135]
	s_nop 0
	v_add_f32_e32 v124, v126, v124
	v_add_f32_e32 v126, v124, v125
	s_waitcnt lgkmcnt(4)
	v_pk_mul_f32 v[124:125], v[90:91], v[136:137]
	s_nop 0
	v_add_f32_e32 v124, v126, v124
	v_add_f32_e32 v126, v124, v125
	s_waitcnt vmcnt(0)
	v_pk_mul_f32 v[124:125], v[92:93], v[138:139]
	s_nop 0
	v_add_f32_e32 v124, v126, v124
	v_add_f32_e32 v124, v124, v125
	v_min_f32_e32 v125, 0, v124
	v_mul_f32_e64 v124, |v124|, s73
	v_exp_f32_e32 v124, v124
	s_nop 0
	v_add_f32_e32 v124, 1.0, v124
	v_cmp_gt_f32_e32 vcc, s94, v124
	s_nop 1
	v_cndmask_b32_e64 v126, 0, 32, vcc
	v_ldexp_f32 v124, v124, v126
	v_log_f32_e32 v124, v124
	s_nop 0
	v_mul_f32_e32 v126, 0x3f317217, v124
	v_fma_f32 v126, v124, s97, -v126
	v_fmac_f32_e32 v126, 0x3377d1cf, v124
	v_fmac_f32_e32 v126, 0x3f317217, v124
	v_cmp_lt_f32_e64 s[12:13], |v124|, s23
	s_nop 1
	v_cndmask_b32_e64 v124, v124, v126, s[12:13]
	v_cndmask_b32_e32 v126, 0, v211, vcc
	v_sub_f32_e32 v124, v124, v126
	v_sub_f32_e32 v124, v125, v124
	v_fmac_f32_e32 v122, 0x3d800000, v124
	v_mov_b32_e32 v223, v124
	s_waitcnt lgkmcnt(0)
	v_fma_f32 v128, v119, v176, v8
	v_fmac_f32_e32 v128, v120, v177
	v_fmac_f32_e32 v128, v116, v178
	v_fmac_f32_e32 v128, v121, v179
	v_fmac_f32_e32 v128, v117, v180
	v_fmac_f32_e32 v128, v118, v181
	v_pk_mul_f32 v[124:125], v[50:51], v[182:183]
	s_nop 0
	v_add_f32_e32 v124, v128, v124
	v_add_f32_e32 v128, v124, v125
	v_pk_mul_f32 v[124:125], v[52:53], v[184:185]
	s_nop 0
	v_add_f32_e32 v124, v128, v124
	v_add_f32_e32 v128, v124, v125
	v_pk_mul_f32 v[124:125], v[88:89], v[186:187]
	s_nop 0
	v_add_f32_e32 v124, v128, v124
	v_add_f32_e32 v128, v124, v125
	v_pk_mul_f32 v[124:125], v[90:91], v[188:189]
	s_nop 0
	v_add_f32_e32 v123, v128, v124
	v_add_f32_e32 v123, v123, v125
	v_pk_mul_f32 v[124:125], v[92:93], v[190:191]
	s_nop 0
	v_add_f32_e32 v123, v123, v124
	v_add_f32_e32 v123, v123, v125
	v_min_f32_e32 v124, 0, v123
	v_mul_f32_e64 v123, |v123|, s73
	v_exp_f32_e32 v123, v123
	s_nop 0
	v_add_f32_e32 v123, 1.0, v123
	v_cmp_gt_f32_e32 vcc, s94, v123
	s_nop 1
	v_cndmask_b32_e64 v125, 0, 32, vcc
	v_ldexp_f32 v123, v123, v125
	v_log_f32_e32 v123, v123
	s_nop 0
	v_mul_f32_e32 v125, 0x3f317217, v123
	v_fma_f32 v125, v123, s97, -v125
	v_fmac_f32_e32 v125, 0x3377d1cf, v123
	v_fmac_f32_e32 v125, 0x3f317217, v123
	v_cmp_lt_f32_e64 s[12:13], |v123|, s23
	s_nop 1
	v_cndmask_b32_e64 v123, v123, v125, s[12:13]
	v_cndmask_b32_e32 v125, 0, v211, vcc
	v_sub_f32_e32 v123, v123, v125
	v_sub_f32_e32 v123, v124, v123
	v_fmac_f32_e32 v122, 0x3d800000, v123
	v_mov_b32_e32 v224, v123
	v_add_u32_e32 v123, s0, v99
	ds_read_b128 v[124:127], v123
	ds_read_b128 v[128:131], v123 offset:16
	ds_read_b128 v[132:135], v123 offset:32
	ds_read_b128 v[136:139], v123 offset:48
	ds_read_b128 v[176:179], v123 offset:64
	ds_read_b128 v[180:183], v123 offset:80
	ds_read_b128 v[184:187], v123 offset:96
	ds_read_b128 v[188:191], v123 offset:112
	s_addk_i32 s0, 0x80
	s_waitcnt vmcnt(1) lgkmcnt(7)
; DEVI float logsigf_(float x) { return fminf(x, 0.f) - __logf(1.f + __expf(-fabsf(x))); }
; DEVI float gla_la(const float* gl, int t, const float* w2r, float gb) { float x = gb;
; #pragma unroll
;     for (int r = 0; r < 16; ++r) x += gl[t * 16 + r] * w2r[r];
;     return logsigf_(x) * (1.f / 16.f); }
; template <int KIND>
; DEVI void mix_state_phase(unsigned char* smem, const MixArgs a) {
;     ...
;         if (item + (int)gridDim.x < 16 * NCH) ST_PREF(item + (int)gridDim.x);
	v_fma_f32 v140, v119, v124, v8
	v_fmac_f32_e32 v140, v120, v125
	v_fmac_f32_e32 v140, v116, v126
	v_fmac_f32_e32 v140, v121, v127
	s_waitcnt lgkmcnt(6)
	v_fmac_f32_e32 v140, v117, v128
	v_fmac_f32_e32 v140, v118, v129
	v_pk_mul_f32 v[124:125], v[50:51], v[130:131]
	v_add_f32_e32 v124, v140, v124
	v_add_f32_e32 v126, v124, v125
	s_waitcnt lgkmcnt(5)
	v_pk_mul_f32 v[124:125], v[52:53], v[132:133]
	s_nop 0
	v_add_f32_e32 v124, v126, v124
	v_add_f32_e32 v126, v124, v125
	v_pk_mul_f32 v[124:125], v[88:89], v[134:135]
	s_nop 0
	v_add_f32_e32 v124, v126, v124
	v_add_f32_e32 v126, v124, v125
	s_waitcnt lgkmcnt(4)
	v_pk_mul_f32 v[124:125], v[90:91], v[136:137]
	s_nop 0
	v_add_f32_e32 v124, v126, v124
	v_add_f32_e32 v126, v124, v125
	s_waitcnt vmcnt(0)
	v_pk_mul_f32 v[124:125], v[92:93], v[138:139]
	s_nop 0
	v_add_f32_e32 v124, v126, v124
	v_add_f32_e32 v124, v124, v125
	v_min_f32_e32 v125, 0, v124
	v_mul_f32_e64 v124, |v124|, s73
	v_exp_f32_e32 v124, v124
	s_nop 0
	v_add_f32_e32 v124, 1.0, v124
	v_cmp_gt_f32_e32 vcc, s94, v124
	s_nop 1
	v_cndmask_b32_e64 v126, 0, 32, vcc
	v_ldexp_f32 v124, v124, v126
	v_log_f32_e32 v124, v124
	s_nop 0
	v_mul_f32_e32 v126, 0x3f317217, v124
	v_fma_f32 v126, v124, s97, -v126
	v_fmac_f32_e32 v126, 0x3377d1cf, v124
	v_fmac_f32_e32 v126, 0x3f317217, v124
	v_cmp_lt_f32_e64 s[12:13], |v124|, s23
	s_nop 1
	v_cndmask_b32_e64 v124, v124, v126, s[12:13]
	v_cndmask_b32_e32 v126, 0, v211, vcc
	v_sub_f32_e32 v124, v124, v126
	v_sub_f32_e32 v124, v125, v124
	v_fmac_f32_e32 v122, 0x3d800000, v124
	v_mov_b32_e32 v225, v124
	s_waitcnt lgkmcnt(0)
	v_fma_f32 v128, v119, v176, v8
	v_fmac_f32_e32 v128, v120, v177
	v_fmac_f32_e32 v128, v116, v178
	v_fmac_f32_e32 v128, v121, v179
	v_fmac_f32_e32 v128, v117, v180
	v_fmac_f32_e32 v128, v118, v181
	v_pk_mul_f32 v[124:125], v[50:51], v[182:183]
	s_nop 0
	v_add_f32_e32 v124, v128, v124
	v_add_f32_e32 v128, v124, v125
	v_pk_mul_f32 v[124:125], v[52:53], v[184:185]
	s_nop 0
	v_add_f32_e32 v124, v128, v124
	v_add_f32_e32 v128, v124, v125
	v_pk_mul_f32 v[124:125], v[88:89], v[186:187]
	s_nop 0
	v_add_f32_e32 v124, v128, v124
	v_add_f32_e32 v128, v124, v125
	v_pk_mul_f32 v[124:125], v[90:91], v[188:189]
	s_nop 0
	v_add_f32_e32 v123, v128, v124
	v_add_f32_e32 v123, v123, v125
	v_pk_mul_f32 v[124:125], v[92:93], v[190:191]
	s_nop 0
	v_add_f32_e32 v123, v123, v124
	v_add_f32_e32 v123, v123, v125
	v_min_f32_e32 v124, 0, v123
	v_mul_f32_e64 v123, |v123|, s73
	v_exp_f32_e32 v123, v123
	s_nop 0
	v_add_f32_e32 v123, 1.0, v123
	v_cmp_gt_f32_e32 vcc, s94, v123
	s_nop 1
	v_cndmask_b32_e64 v125, 0, 32, vcc
	v_ldexp_f32 v123, v123, v125
	v_log_f32_e32 v123, v123
	s_nop 0
	v_mul_f32_e32 v125, 0x3f317217, v123
	v_fma_f32 v125, v123, s97, -v125
	v_fmac_f32_e32 v125, 0x3377d1cf, v123
	v_fmac_f32_e32 v125, 0x3f317217, v123
	v_cmp_lt_f32_e64 s[12:13], |v123|, s23
	s_nop 1
	v_cndmask_b32_e64 v123, v123, v125, s[12:13]
	v_cndmask_b32_e32 v125, 0, v211, vcc
	v_sub_f32_e32 v123, v123, v125
	v_sub_f32_e32 v123, v124, v123
	v_fmac_f32_e32 v122, 0x3d800000, v123
	v_mov_b32_e32 v226, v123
	v_add_u32_e32 v123, s0, v99
	ds_read_b128 v[124:127], v123
	ds_read_b128 v[128:131], v123 offset:16
	ds_read_b128 v[132:135], v123 offset:32
	ds_read_b128 v[136:139], v123 offset:48
	ds_read_b128 v[176:179], v123 offset:64
	ds_read_b128 v[180:183], v123 offset:80
	ds_read_b128 v[184:187], v123 offset:96
	ds_read_b128 v[188:191], v123 offset:112
	s_addk_i32 s0, 0x80
	s_waitcnt vmcnt(1) lgkmcnt(7)
	v_fma_f32 v140, v119, v124, v8
	v_fmac_f32_e32 v140, v120, v125
	v_fmac_f32_e32 v140, v116, v126
	v_fmac_f32_e32 v140, v121, v127
	s_waitcnt lgkmcnt(6)
	v_fmac_f32_e32 v140, v117, v128
	v_fmac_f32_e32 v140, v118, v129
	v_pk_mul_f32 v[124:125], v[50:51], v[130:131]
	v_add_f32_e32 v124, v140, v124
	v_add_f32_e32 v126, v124, v125
	s_waitcnt lgkmcnt(5)
	v_pk_mul_f32 v[124:125], v[52:53], v[132:133]
	s_nop 0
	v_add_f32_e32 v124, v126, v124
	v_add_f32_e32 v126, v124, v125
	v_pk_mul_f32 v[124:125], v[88:89], v[134:135]
	s_nop 0
	v_add_f32_e32 v124, v126, v124
	v_add_f32_e32 v126, v124, v125
	s_waitcnt lgkmcnt(4)
	v_pk_mul_f32 v[124:125], v[90:91], v[136:137]
	s_nop 0
	v_add_f32_e32 v124, v126, v124
	v_add_f32_e32 v126, v124, v125
	s_waitcnt vmcnt(0)
	v_pk_mul_f32 v[124:125], v[92:93], v[138:139]
	s_nop 0
	v_add_f32_e32 v124, v126, v124
	v_add_f32_e32 v124, v124, v125
	v_min_f32_e32 v125, 0, v124
	v_mul_f32_e64 v124, |v124|, s73
	v_exp_f32_e32 v124, v124
	s_nop 0
	v_add_f32_e32 v124, 1.0, v124
	v_cmp_gt_f32_e32 vcc, s94, v124
	s_nop 1
	v_cndmask_b32_e64 v126, 0, 32, vcc
	v_ldexp_f32 v124, v124, v126
	v_log_f32_e32 v124, v124
	s_nop 0
	v_mul_f32_e32 v126, 0x3f317217, v124
	v_fma_f32 v126, v124, s97, -v126
	v_fmac_f32_e32 v126, 0x3377d1cf, v124
	v_fmac_f32_e32 v126, 0x3f317217, v124
	v_cmp_lt_f32_e64 s[12:13], |v124|, s23
	s_nop 1
	v_cndmask_b32_e64 v124, v124, v126, s[12:13]
	v_cndmask_b32_e32 v126, 0, v211, vcc
	v_sub_f32_e32 v124, v124, v126
	v_sub_f32_e32 v124, v125, v124
	v_fmac_f32_e32 v122, 0x3d800000, v124
	v_mov_b32_e32 v227, v124
	s_waitcnt lgkmcnt(0)
	v_fma_f32 v128, v119, v176, v8
	v_fmac_f32_e32 v128, v120, v177
	v_fmac_f32_e32 v128, v116, v178
	v_fmac_f32_e32 v128, v121, v179
	v_fmac_f32_e32 v128, v117, v180
	v_fmac_f32_e32 v128, v118, v181
	v_pk_mul_f32 v[124:125], v[50:51], v[182:183]
	s_nop 0
	v_add_f32_e32 v124, v128, v124
	v_add_f32_e32 v128, v124, v125
	v_pk_mul_f32 v[124:125], v[52:53], v[184:185]
	s_nop 0
	v_add_f32_e32 v124, v128, v124
	v_add_f32_e32 v128, v124, v125
	v_pk_mul_f32 v[124:125], v[88:89], v[186:187]
	s_nop 0
	v_add_f32_e32 v124, v128, v124
	v_add_f32_e32 v128, v124, v125
	v_pk_mul_f32 v[124:125], v[90:91], v[188:189]
	s_nop 0
	v_add_f32_e32 v123, v128, v124
	v_add_f32_e32 v123, v123, v125
	v_pk_mul_f32 v[124:125], v[92:93], v[190:191]
	s_nop 0
	v_add_f32_e32 v123, v123, v124
	v_add_f32_e32 v123, v123, v125
	v_min_f32_e32 v124, 0, v123
	v_mul_f32_e64 v123, |v123|, s73
	v_exp_f32_e32 v123, v123
	s_nop 0
	v_add_f32_e32 v123, 1.0, v123
	v_cmp_gt_f32_e32 vcc, s94, v123
	s_nop 1
	v_cndmask_b32_e64 v125, 0, 32, vcc
	v_ldexp_f32 v123, v123, v125
	v_log_f32_e32 v123, v123
	s_nop 0
	v_mul_f32_e32 v125, 0x3f317217, v123
	v_fma_f32 v125, v123, s97, -v125
	v_fmac_f32_e32 v125, 0x3377d1cf, v123
	v_fmac_f32_e32 v125, 0x3f317217, v123
	v_cmp_lt_f32_e64 s[12:13], |v123|, s23
	s_nop 1
	v_cndmask_b32_e64 v123, v123, v125, s[12:13]
	v_cndmask_b32_e32 v125, 0, v211, vcc
	v_sub_f32_e32 v123, v123, v125
	v_sub_f32_e32 v123, v124, v123
	v_fmac_f32_e32 v122, 0x3d800000, v123
	v_mov_b32_e32 v228, v123
	s_cmpk_gt_i32 s46, 0x3ff
	s_cselect_b64 s[16:17], -1, 0
	s_and_b64 vcc, exec, s[16:17]
	s_cbranch_vccnz .Lpfm_st
; DEVI void lds_barrier() { asm volatile("s_waitcnt lgkmcnt(0)\n\ts_barrier" ::: "memory"); }
; template <int KIND>
; DEVI void mix_state_phase(unsigned char* smem, const MixArgs a) {
;     ...
;             seg[sg * 128 + ch] = ssum; lds_barrier();
;             float Bc = 0.f, tot = 0.f;
; #pragma unroll
;             for (int s2 = 0; s2 < 4; ++s2) { const float v = seg[s2 * 128 + ch]; tot += v; if (s2 < sg) Bc += v; }
	s_ashr_i32 s0, s46, 31
	s_lshr_b32 s0, s0, 26
	s_add_i32 s0, s46, s0
	s_and_b32 s1, s0, 0x1ffffc0
	s_sub_i32 s12, s46, s1
	s_bfe_u32 s15, s0, 0x20006
	s_ashr_i32 s0, s0, 8
	s_ashr_i32 s1, s0, 31
	s_lshl_b32 s12, s12, 7
	s_lshl_b64 s[0:1], s[0:1], 13
	s_ashr_i32 s13, s12, 31
	s_add_u32 s12, s0, s12
	s_addc_u32 s13, s1, s13
	v_lshl_add_u64 v[0:1], s[12:13], 0, v[54:55]
	v_mov_b64_e32 v[46:47], s[28:29]
	v_lshl_add_u64 v[10:11], s[12:13], 0, v[60:61]
	v_lshl_add_u64 v[18:19], s[12:13], 0, v[64:65]
	v_lshl_add_u64 v[26:27], s[12:13], 0, v[68:69]
	v_mad_u64_u32 v[2:3], s[0:1], v0, s95, v[46:47]
	v_mad_u64_u32 v[12:13], s[18:19], v10, s95, v[46:47]
	v_mad_u64_u32 v[20:21], s[18:19], v18, s95, v[46:47]
	v_mad_u64_u32 v[28:29], s[18:19], v26, s95, v[46:47]
	v_mad_i32_i24 v3, v1, s95, v3
	s_lshl_b32 s0, s15, 9
	s_mov_b32 s1, s67
	v_mad_i32_i24 v13, v11, s95, v13
	v_mad_i32_i24 v21, v19, s95, v21
	v_mad_i32_i24 v29, v27, s95, v29
	v_lshl_add_u64 v[0:1], v[2:3], 0, s[0:1]
	v_lshl_add_u64 v[2:3], s[12:13], 0, v[58:59]
	v_lshl_add_u64 v[10:11], v[12:13], 0, s[0:1]
	v_lshl_add_u64 v[12:13], s[12:13], 0, v[62:63]
	v_lshl_add_u64 v[18:19], v[20:21], 0, s[0:1]
	v_lshl_add_u64 v[20:21], s[12:13], 0, v[66:67]
	v_lshl_add_u64 v[26:27], v[28:29], 0, s[0:1]
	v_lshl_add_u64 v[28:29], s[12:13], 0, v[70:71]
	v_mad_u64_u32 v[4:5], s[18:19], v2, s95, v[46:47]
	v_mad_u64_u32 v[14:15], s[18:19], v12, s95, v[46:47]
	v_mad_u64_u32 v[22:23], s[18:19], v20, s95, v[46:47]
	v_mad_u64_u32 v[30:31], s[18:19], v28, s95, v[46:47]
	v_mad_i32_i24 v5, v3, s95, v5
	v_mad_i32_i24 v15, v13, s95, v15
	v_mad_i32_i24 v23, v21, s95, v23
	v_mad_i32_i24 v31, v29, s95, v31
	v_lshl_add_u64 v[34:35], s[12:13], 0, v[56:57]
	v_lshl_add_u64 v[2:3], v[4:5], 0, s[0:1]
	v_lshl_add_u64 v[12:13], v[14:15], 0, s[0:1]
	v_lshl_add_u64 v[20:21], v[22:23], 0, s[0:1]
	v_lshl_add_u64 v[28:29], v[30:31], 0, s[0:1]
	v_mad_u64_u32 v[36:37], s[0:1], v34, s95, v[46:47]
	s_lshl_b32 s66, s15, 8
	v_mad_i32_i24 v37, v35, s95, v37
	v_mov_b32_e32 v85, v9
	v_lshl_add_u64 v[36:37], v[36:37], 0, s[66:67]
	v_mov_b32_e32 v87, v9
	v_lshlrev_b64 v[34:35], 6, v[34:35]
	v_lshl_add_u64 v[0:1], v[0:1], 0, v[84:85]
	v_lshl_add_u64 v[4:5], v[2:3], 0, v[84:85]
	v_lshl_add_u64 v[10:11], v[10:11], 0, v[84:85]
	v_lshl_add_u64 v[14:15], v[12:13], 0, v[84:85]
	v_lshl_add_u64 v[18:19], v[18:19], 0, v[84:85]
	v_lshl_add_u64 v[22:23], v[20:21], 0, v[84:85]
	v_lshl_add_u64 v[26:27], v[26:27], 0, v[84:85]
	v_lshl_add_u64 v[30:31], v[28:29], 0, v[84:85]
	v_lshl_add_u64 v[36:37], v[36:37], 0, v[86:87]
	v_lshl_add_u64 v[38:39], v[78:79], 0, v[34:35]
	global_load_dwordx4 v[0:3], v[0:1], off offset:2048
	s_nop 0
	global_load_dwordx4 v[4:7], v[4:5], off offset:2048
	s_nop 0
	global_load_dwordx4 v[10:13], v[10:11], off offset:2048
	s_nop 0
	global_load_dwordx4 v[14:17], v[14:15], off offset:2048
	s_nop 0
	global_load_dwordx4 v[18:21], v[18:19], off offset:2048
	s_nop 0
	global_load_dwordx4 v[22:25], v[22:23], off offset:2048
	s_nop 0
	global_load_dwordx4 v[26:29], v[26:27], off offset:2048
	s_nop 0
	global_load_dwordx4 v[30:33], v[30:31], off offset:2048
	s_nop 0
	global_load_dwordx4 v[34:37], v[36:37], off offset:1024
	s_nop 0
	global_load_dword v85, v[38:39], off
	v_lshl_add_u64 v[38:39], s[12:13], 0, v[72:73]
	v_mad_u64_u32 v[40:41], s[0:1], v38, s95, v[46:47]
	v_mad_i32_i24 v41, v39, s95, v41
	v_lshl_add_u64 v[40:41], v[40:41], 0, s[66:67]
	v_lshlrev_b64 v[38:39], 6, v[38:39]
	v_lshl_add_u64 v[40:41], v[40:41], 0, v[86:87]
	v_lshl_add_u64 v[42:43], v[78:79], 0, v[38:39]
	global_load_dwordx4 v[38:41], v[40:41], off offset:1024
	s_nop 0
	global_load_dword v97, v[42:43], off
	v_lshl_add_u64 v[42:43], s[12:13], 0, v[74:75]
	v_mad_u64_u32 v[44:45], s[0:1], v42, s95, v[46:47]
	v_mad_i32_i24 v45, v43, s95, v45
	v_lshl_add_u64 v[44:45], v[44:45], 0, s[66:67]
	v_lshlrev_b64 v[42:43], 6, v[42:43]
	v_lshl_add_u64 v[44:45], v[44:45], 0, v[86:87]
	v_lshl_add_u64 v[48:49], v[78:79], 0, v[42:43]
	global_load_dwordx4 v[42:45], v[44:45], off offset:1024
	s_nop 0
	global_load_dword v98, v[48:49], off
	v_lshl_add_u64 v[48:49], s[12:13], 0, v[76:77]
	v_mad_u64_u32 v[46:47], s[0:1], v48, s95, v[46:47]
	v_mad_i32_i24 v47, v49, s95, v47
	v_lshl_add_u64 v[46:47], v[46:47], 0, s[66:67]
	v_lshl_add_u64 v[46:47], v[46:47], 0, v[86:87]
	v_lshlrev_b64 v[48:49], 6, v[48:49]
	v_lshl_add_u64 v[50:51], v[78:79], 0, v[48:49]
	global_load_dwordx4 v[46:49], v[46:47], off offset:1024
	s_nop 0
	global_load_dword v87, v[50:51], off
.Lpfm_st:
	s_ashr_i32 s15, s14, 31
	ds_write_b32 v95, v122 offset:1536
	s_waitcnt lgkmcnt(0)
	s_barrier
	ds_read2st64_b32 v[122:123], v96 offset0:6 offset1:8
	s_mov_b32 s0, 0
	s_waitcnt lgkmcnt(0)
	v_add_f32_e32 v122, 0, v122
	v_cndmask_b32_e64 v124, 0, v122, s[4:5]
	v_add_f32_e32 v125, v122, v123
	v_add_f32_e32 v122, v123, v124
	v_cndmask_b32_e64 v124, v124, v122, s[6:7]
	ds_read2st64_b32 v[122:123], v96 offset0:10 offset1:12
	s_waitcnt lgkmcnt(0)
	v_add_f32_e32 v125, v125, v122
	v_add_f32_e32 v122, v122, v124
	v_cndmask_b32_e64 v124, v124, v122, s[8:9]
	v_add_f32_e32 v122, v125, v123
	v_add_f32_e32 v123, v123, v124
	v_cndmask_b32_e64 v123, v124, v123, s[10:11]
	v_mov_b32_e32 v124, v100

; DEVI unsigned cvt_pk(float lo, float hi) { f32v2_t f = {lo, hi}; bf16v2_t v = __builtin_convertvector(f, bf16v2_t); return __builtin_bit_cast(unsigned, v); }
; DEVI float logsigf_(float x) { return fminf(x, 0.f) - __logf(1.f + __expf(-fabsf(x))); }
; template <int KIND>
; DEVI void mix_out_phase(unsigned char* smem, const MixArgs a) {
;     ...
;         MIX_PREF(0, 0);
;         lds_barrier();
;         if (KIND == 0) {
; #pragma unroll
;             for (int k = 0; k < 9; ++k) { const int q = tid + k * 512; if (q < 131 * 32) *(u32x4*)(RAW + ((q >> 4) & 1) * (131 * 128) + (q >> 5) * 128 + (q & 15) * 8) = prq[k]; }
;             if (tid < 128) { fI[tid] = pg[0] + a.gateb[h]; fB[tid] = logsigf_(pg[1] + a.gateb[4 + h]); fN[tid] = pg[2]; }
;         } else {
; #pragma unroll
;             for (int k = 0; k < 4; ++k) { const int i = tid + k * 512; *(u32x4*)(QS + (i >> 4) * LP + (i & 15) * 8) = prq[k]; *(u32x4*)(KS + (i >> 4) * LP + (i & 15) * 8) = prq[4 + k]; gl[i] = pg[k]; }
;         }
;         lds_barrier();
;         if (KIND == 1 && item + (int)gridDim.x < 16 * NCH) OUT_PREF(item + (int)gridDim.x);
;         if (KIND == 0) {
;             if (tid < 64) { float x0 = fB[2 * tid], x1 = fB[2 * tid + 1]; float sc = x0 + x1;
; #pragma unroll
;                 for (int o = 1; o < 64; o <<= 1) { const float t = __shfl_up(sc, o); if (tid >= o) sc += t; }
;                 fB[2 * tid] = sc - x1; fB[2 * tid + 1] = sc; }
; #pragma unroll 2
;             for (int i = tid; i < 128 * 32; i += 512) { const int t = (i >> 4) & 127, c8 = (i & 15) * 8, isk = i >> 11; float v[8];
;                 mlstm_conv8_lds(RAW + isk * (131 * 128), a.convw, t, c8, isk * 512 + h * 128 + c8, v); const float sc = isk ? 1.f : 0.08838834764831845f;
;                 u32x4 w; w.x = cvt_pk(v[0] * sc, v[1] * sc); w.y = cvt_pk(v[2] * sc, v[3] * sc); w.z = cvt_pk(v[4] * sc, v[5] * sc); w.w = cvt_pk(v[6] * sc, v[7] * sc);
;                 *(u32x4*)((isk ? KS : QS) + t * LP + c8) = w; }
;         } else {
;             const int ch = tid & 127, sg = tid >> 7; float w2r[16];
; #pragma unroll
;             for (int r = 0; r < 16; ++r) w2r[r] = a.w2[r * 512 + h * 128 + ch];
;             const float gb = a.gateb[h * 128 + ch]; float ssum = 0.f;
;             for (int t = sg * 32; t < sg * 32 + 32; ++t) ssum += gla_la(gl, t, w2r, gb);
.LBB0_688:
	s_ashr_i32 s47, s88, 31
	s_lshr_b32 s0, s47, 26
	s_add_i32 s1, s88, s0
	s_and_b32 s0, s1, 0x1ffffc0
	s_sub_i32 s16, s88, s0
	s_ashr_i32 s14, s1, 8
	s_bfe_u32 s0, s1, 0x20006
	s_ashr_i32 s15, s14, 31
	s_lshl_b32 s1, s16, 7
	s_lshl_b64 s[14:15], s[14:15], 13
	s_ashr_i32 s16, s1, 31
	s_add_u32 s68, s14, s1
	s_addc_u32 s69, s15, s16
	s_mov_b32 s46, s88
	s_lshl_b64 s[14:15], s[46:47], 16
	v_lshl_add_u64 v[36:37], s[68:69], 0, v[186:187]
	v_mov_b64_e32 v[38:39], s[28:29]
	v_lshl_add_u64 v[34:35], v[178:179], 0, s[14:15]
	v_mad_u64_u32 v[40:41], s[14:15], v36, s95, v[38:39]
	v_mad_i32_i24 v41, v37, s95, v41
	s_lshl_b32 s66, s0, 9
	v_lshl_add_u64 v[36:37], v[40:41], 0, s[66:67]
	v_lshl_add_u64 v[40:41], s[68:69], 0, v[190:191]
	v_mad_u64_u32 v[38:39], s[14:15], v40, s95, v[38:39]
	v_mad_i32_i24 v39, v41, s95, v39
	v_lshl_add_u64 v[130:131], v[36:37], 0, v[8:9]
	v_lshl_add_u64 v[36:37], v[34:35], 0, v[188:189]
	v_lshl_add_u64 v[38:39], v[38:39], 0, s[66:67]
	v_lshl_add_u64 v[134:135], v[38:39], 0, v[8:9]
	global_load_dwordx4 v[50:53], v[130:131], off offset:2048
	global_load_dwordx4 v[42:45], v[134:135], off offset:2048
	v_lshl_add_u64 v[34:35], v[34:35], 0, v[192:193]
	global_load_dwordx4 v[54:57], v[36:37], off
	global_load_dwordx4 v[46:49], v[34:35], off
	s_waitcnt lgkmcnt(0)
	s_barrier
	s_waitcnt vmcnt(15)
	ds_write_b128 v213, v[0:3] offset:16384
	s_waitcnt vmcnt(14)
	ds_write_b128 v213, v[4:7] offset:51200
	s_waitcnt vmcnt(13)
	ds_write_b32 v204, v185 offset:4096
	s_waitcnt vmcnt(12)
	ds_write_b128 v215, v[10:13] offset:16384
	s_waitcnt vmcnt(11)
	ds_write_b128 v215, v[14:17] offset:51200
	s_waitcnt vmcnt(10)
	ds_write_b32 v204, v200 offset:6144
	s_waitcnt vmcnt(9)
	ds_write_b128 v194, v[18:21] offset:16384
	s_waitcnt vmcnt(8)
	ds_write_b128 v194, v[22:25] offset:51200
	s_waitcnt vmcnt(7)
	ds_write_b32 v204, v201 offset:8192
	s_waitcnt vmcnt(6)
	ds_write_b128 v196, v[26:29] offset:16384
	s_waitcnt vmcnt(5)
	ds_write_b128 v196, v[30:33] offset:51200
	s_waitcnt vmcnt(4)
	ds_write_b32 v204, v207 offset:10240
	s_add_i32 s88, s88, s22
	s_waitcnt lgkmcnt(0)
	s_barrier
.LBB0_690:
	v_lshlrev_b32_e32 v34, 2, v203
	v_lshl_or_b32 v66, s0, 9, v34
	v_mov_b32_e32 v67, v9
	v_lshl_add_u64 v[58:59], s[84:85], 0, v[66:67]
	v_add_co_u32_e32 v68, vcc, s50, v58
	s_movk_i32 s1, 0x4000
	s_nop 0
	v_addc_co_u32_e32 v69, vcc, 0, v59, vcc
	v_add_co_u32_e32 v34, vcc, s49, v58
	v_readlane_b32 s14, v254, 7
	s_nop 0
	v_addc_co_u32_e32 v35, vcc, 0, v59, vcc
	v_add_co_u32_e32 v70, vcc, s53, v58
	v_readlane_b32 s15, v254, 8
	s_nop 0
	v_addc_co_u32_e32 v71, vcc, 0, v59, vcc
	v_add_co_u32_e32 v38, vcc, s1, v58
	s_movk_i32 s1, 0x5000
	s_nop 0
	v_addc_co_u32_e32 v39, vcc, 0, v59, vcc
	v_add_co_u32_e32 v72, vcc, s1, v58
	s_movk_i32 s1, 0x6000
	s_nop 0
	v_addc_co_u32_e32 v73, vcc, 0, v59, vcc
	v_add_co_u32_e32 v64, vcc, s1, v58
	s_lshl_b32 s89, s0, 8
	s_nop 0
	v_addc_co_u32_e32 v65, vcc, 0, v59, vcc
	global_load_dword v60, v[34:35], off offset:-4096
	global_load_dword v61, v[34:35], off
	global_load_dword v62, v[34:35], off offset:2048
	s_nop 0
	global_load_dword v34, v[38:39], off offset:-4096
	global_load_dword v36, v[38:39], off
	global_load_dword v37, v[38:39], off offset:2048
	s_nop 0
	global_load_dword v38, v[64:65], off offset:-4096
	global_load_dword v40, v[64:65], off
	global_load_dword v41, v[64:65], off offset:2048
	v_add_co_u32_e32 v74, vcc, 0x7000, v58
	s_mov_b32 s0, 0
	s_nop 0
	v_addc_co_u32_e32 v75, vcc, 0, v59, vcc
	global_load_dword v63, v66, s[84:85]
	global_load_dword v64, v66, s[84:85] offset:2048
	global_load_dword v65, v[68:69], off offset:2048
	global_load_dword v35, v[70:71], off offset:2048
	global_load_dword v39, v[72:73], off offset:2048
	global_load_dword v58, v[74:75], off
	s_nop 0
	global_load_dword v66, v66, s[14:15]
	s_nop 0
	global_load_dword v59, v[74:75], off offset:2048
	v_mov_b32_e32 v67, 0
.LBB0_691:
	v_add_u32_e32 v84, s0, v195
	ds_read_b128 v[68:71], v84
	ds_read_b128 v[72:75], v84 offset:16
	ds_read_b128 v[76:79], v84 offset:32
	ds_read_b128 v[80:83], v84 offset:48
	ds_read_b128 v[100:103], v84 offset:64
	ds_read_b128 v[104:107], v84 offset:80
	ds_read_b128 v[108:111], v84 offset:96
	ds_read_b128 v[112:115], v84 offset:112
	s_addk_i32 s0, 0x80
	s_waitcnt vmcnt(1) lgkmcnt(7)
	v_fma_f32 v85, v63, v68, v66
	v_fmac_f32_e32 v85, v64, v69
	v_fmac_f32_e32 v85, v60, v70
	v_fmac_f32_e32 v85, v65, v71
	s_waitcnt lgkmcnt(6)
	v_fmac_f32_e32 v85, v61, v72
	v_fmac_f32_e32 v85, v62, v73
	v_pk_mul_f32 v[68:69], v[34:35], v[74:75]
	v_add_f32_e32 v68, v85, v68
	v_add_f32_e32 v70, v68, v69
	s_waitcnt lgkmcnt(5)
	v_pk_mul_f32 v[68:69], v[36:37], v[76:77]
	s_nop 0
	v_add_f32_e32 v68, v70, v68
	v_add_f32_e32 v70, v68, v69
	v_pk_mul_f32 v[68:69], v[38:39], v[78:79]
	s_nop 0
	v_add_f32_e32 v68, v70, v68
	v_add_f32_e32 v70, v68, v69
	s_waitcnt lgkmcnt(4)
	v_pk_mul_f32 v[68:69], v[40:41], v[80:81]
	s_nop 0
	v_add_f32_e32 v68, v70, v68
	v_add_f32_e32 v70, v68, v69
	s_waitcnt vmcnt(0)
	v_pk_mul_f32 v[68:69], v[58:59], v[82:83]
	s_nop 0
	v_add_f32_e32 v68, v70, v68
	v_add_f32_e32 v68, v68, v69
	v_min_f32_e32 v69, 0, v68
	v_mul_f32_e64 v68, |v68|, s73
	v_exp_f32_e32 v68, v68
	s_nop 0
	v_add_f32_e32 v68, 1.0, v68
	v_cmp_gt_f32_e32 vcc, s94, v68
	s_nop 1
	v_cndmask_b32_e64 v70, 0, 32, vcc
	v_ldexp_f32 v68, v68, v70
	v_log_f32_e32 v68, v68
	s_nop 0
	v_mul_f32_e32 v70, 0x3f317217, v68
	v_fma_f32 v70, v68, s97, -v70
	v_fmac_f32_e32 v70, 0x3377d1cf, v68
	v_fmac_f32_e32 v70, 0x3f317217, v68
	v_cmp_lt_f32_e64 s[14:15], |v68|, s23
	s_nop 1
	v_cndmask_b32_e64 v68, v68, v70, s[14:15]
	v_cndmask_b32_e32 v70, 0, v211, vcc
	v_sub_f32_e32 v68, v68, v70
	v_sub_f32_e32 v68, v69, v68
	v_fmac_f32_e32 v67, 0x3d800000, v68
	v_mov_b32_e32 v86, v68
	s_waitcnt lgkmcnt(0)
; DEVI float logsigf_(float x) { return fminf(x, 0.f) - __logf(1.f + __expf(-fabsf(x))); }
; DEVI float gla_la(const float* gl, int t, const float* w2r, float gb) { float x = gb;
; #pragma unroll
;     for (int r = 0; r < 16; ++r) x += gl[t * 16 + r] * w2r[r];
;     return logsigf_(x) * (1.f / 16.f); }
; template <int KIND>
; DEVI void mix_out_phase(unsigned char* smem, const MixArgs a) {
;     ...
;             for (int t = sg * 32; t < sg * 32 + 32; ++t) ssum += gla_la(gl, t, w2r, gb);
	v_fma_f32 v72, v63, v100, v66
	v_fmac_f32_e32 v72, v64, v101
	v_fmac_f32_e32 v72, v60, v102
	v_fmac_f32_e32 v72, v65, v103
	v_fmac_f32_e32 v72, v61, v104
	v_fmac_f32_e32 v72, v62, v105
	v_pk_mul_f32 v[68:69], v[34:35], v[106:107]
	s_nop 0
	v_add_f32_e32 v68, v72, v68
	v_add_f32_e32 v72, v68, v69
	v_pk_mul_f32 v[68:69], v[36:37], v[108:109]
	s_nop 0
	v_add_f32_e32 v68, v72, v68
	v_add_f32_e32 v72, v68, v69
	v_pk_mul_f32 v[68:69], v[38:39], v[110:111]
	s_nop 0
	v_add_f32_e32 v68, v72, v68
	v_add_f32_e32 v72, v68, v69
	v_pk_mul_f32 v[68:69], v[40:41], v[112:113]
	s_nop 0
	v_add_f32_e32 v68, v72, v68
	v_add_f32_e32 v72, v68, v69
	v_pk_mul_f32 v[68:69], v[58:59], v[114:115]
	s_nop 0
	v_add_f32_e32 v68, v72, v68
	v_add_f32_e32 v68, v68, v69
	v_min_f32_e32 v69, 0, v68
	v_mul_f32_e64 v68, |v68|, s73
	v_exp_f32_e32 v68, v68
	s_nop 0
	v_add_f32_e32 v68, 1.0, v68
	v_cmp_gt_f32_e32 vcc, s94, v68
	s_nop 1
	v_cndmask_b32_e64 v70, 0, 32, vcc
	v_ldexp_f32 v68, v68, v70
	v_log_f32_e32 v68, v68
	s_nop 0
	v_mul_f32_e32 v70, 0x3f317217, v68
	v_fma_f32 v70, v68, s97, -v70
	v_fmac_f32_e32 v70, 0x3377d1cf, v68
	v_fmac_f32_e32 v70, 0x3f317217, v68
	v_cmp_lt_f32_e64 s[14:15], |v68|, s23
	s_nop 1
	v_cndmask_b32_e64 v68, v68, v70, s[14:15]
	v_cndmask_b32_e32 v70, 0, v211, vcc
	v_sub_f32_e32 v68, v68, v70
	v_sub_f32_e32 v68, v69, v68
	v_fmac_f32_e32 v67, 0x3d800000, v68
	v_mov_b32_e32 v87, v68
	v_add_u32_e32 v84, s0, v195
	ds_read_b128 v[68:71], v84
	ds_read_b128 v[72:75], v84 offset:16
	ds_read_b128 v[76:79], v84 offset:32
	ds_read_b128 v[80:83], v84 offset:48
	ds_read_b128 v[100:103], v84 offset:64
	ds_read_b128 v[104:107], v84 offset:80
	ds_read_b128 v[108:111], v84 offset:96
	ds_read_b128 v[112:115], v84 offset:112
	s_addk_i32 s0, 0x80
	s_waitcnt vmcnt(1) lgkmcnt(7)
	v_fma_f32 v85, v63, v68, v66
	v_fmac_f32_e32 v85, v64, v69
	v_fmac_f32_e32 v85, v60, v70
	v_fmac_f32_e32 v85, v65, v71
	s_waitcnt lgkmcnt(6)
	v_fmac_f32_e32 v85, v61, v72
	v_fmac_f32_e32 v85, v62, v73
	v_pk_mul_f32 v[68:69], v[34:35], v[74:75]
	v_add_f32_e32 v68, v85, v68
	v_add_f32_e32 v70, v68, v69
	s_waitcnt lgkmcnt(5)
	v_pk_mul_f32 v[68:69], v[36:37], v[76:77]
	s_nop 0
	v_add_f32_e32 v68, v70, v68
	v_add_f32_e32 v70, v68, v69
	v_pk_mul_f32 v[68:69], v[38:39], v[78:79]
	s_nop 0
	v_add_f32_e32 v68, v70, v68
	v_add_f32_e32 v70, v68, v69
	s_waitcnt lgkmcnt(4)
	v_pk_mul_f32 v[68:69], v[40:41], v[80:81]
	s_nop 0
	v_add_f32_e32 v68, v70, v68
	v_add_f32_e32 v70, v68, v69
	s_waitcnt vmcnt(0)
	v_pk_mul_f32 v[68:69], v[58:59], v[82:83]
	s_nop 0
	v_add_f32_e32 v68, v70, v68
	v_add_f32_e32 v68, v68, v69
	v_min_f32_e32 v69, 0, v68
	v_mul_f32_e64 v68, |v68|, s73
	v_exp_f32_e32 v68, v68
	s_nop 0
	v_add_f32_e32 v68, 1.0, v68
	v_cmp_gt_f32_e32 vcc, s94, v68
	s_nop 1
	v_cndmask_b32_e64 v70, 0, 32, vcc
	v_ldexp_f32 v68, v68, v70
	v_log_f32_e32 v68, v68
	s_nop 0
	v_mul_f32_e32 v70, 0x3f317217, v68
	v_fma_f32 v70, v68, s97, -v70
	v_fmac_f32_e32 v70, 0x3377d1cf, v68
	v_fmac_f32_e32 v70, 0x3f317217, v68
	v_cmp_lt_f32_e64 s[14:15], |v68|, s23
	s_nop 1
	v_cndmask_b32_e64 v68, v68, v70, s[14:15]
	v_cndmask_b32_e32 v70, 0, v211, vcc
	v_sub_f32_e32 v68, v68, v70
	v_sub_f32_e32 v68, v69, v68
	v_fmac_f32_e32 v67, 0x3d800000, v68
	v_mov_b32_e32 v88, v68
	s_waitcnt lgkmcnt(0)
	v_fma_f32 v72, v63, v100, v66
	v_fmac_f32_e32 v72, v64, v101
	v_fmac_f32_e32 v72, v60, v102
	v_fmac_f32_e32 v72, v65, v103
	v_fmac_f32_e32 v72, v61, v104
	v_fmac_f32_e32 v72, v62, v105
	v_pk_mul_f32 v[68:69], v[34:35], v[106:107]
	s_nop 0
	v_add_f32_e32 v68, v72, v68
	v_add_f32_e32 v72, v68, v69
	v_pk_mul_f32 v[68:69], v[36:37], v[108:109]
	s_nop 0
	v_add_f32_e32 v68, v72, v68
	v_add_f32_e32 v72, v68, v69
	v_pk_mul_f32 v[68:69], v[38:39], v[110:111]
	s_nop 0
	v_add_f32_e32 v68, v72, v68
	v_add_f32_e32 v72, v68, v69
	v_pk_mul_f32 v[68:69], v[40:41], v[112:113]
	s_nop 0
	v_add_f32_e32 v68, v72, v68
	v_add_f32_e32 v72, v68, v69
	v_pk_mul_f32 v[68:69], v[58:59], v[114:115]
	s_nop 0
	v_add_f32_e32 v68, v72, v68
	v_add_f32_e32 v68, v68, v69
	v_min_f32_e32 v69, 0, v68
	v_mul_f32_e64 v68, |v68|, s73
	v_exp_f32_e32 v68, v68
	s_nop 0
	v_add_f32_e32 v68, 1.0, v68
	v_cmp_gt_f32_e32 vcc, s94, v68
	s_nop 1
	v_cndmask_b32_e64 v70, 0, 32, vcc
	v_ldexp_f32 v68, v68, v70
	v_log_f32_e32 v68, v68
	s_nop 0
	v_mul_f32_e32 v70, 0x3f317217, v68
	v_fma_f32 v70, v68, s97, -v70
	v_fmac_f32_e32 v70, 0x3377d1cf, v68
	v_fmac_f32_e32 v70, 0x3f317217, v68
	v_cmp_lt_f32_e64 s[14:15], |v68|, s23
	s_nop 1
	v_cndmask_b32_e64 v68, v68, v70, s[14:15]
	v_cndmask_b32_e32 v70, 0, v211, vcc
	v_sub_f32_e32 v68, v68, v70
	v_sub_f32_e32 v68, v69, v68
	v_fmac_f32_e32 v67, 0x3d800000, v68
	v_mov_b32_e32 v89, v68
	v_add_u32_e32 v84, s0, v195
	ds_read_b128 v[68:71], v84
	ds_read_b128 v[72:75], v84 offset:16
	ds_read_b128 v[76:79], v84 offset:32
	ds_read_b128 v[80:83], v84 offset:48
	ds_read_b128 v[100:103], v84 offset:64
	ds_read_b128 v[104:107], v84 offset:80
	ds_read_b128 v[108:111], v84 offset:96
	ds_read_b128 v[112:115], v84 offset:112
	s_addk_i32 s0, 0x80
	s_waitcnt vmcnt(1) lgkmcnt(7)
	v_fma_f32 v85, v63, v68, v66
	v_fmac_f32_e32 v85, v64, v69
	v_fmac_f32_e32 v85, v60, v70
	v_fmac_f32_e32 v85, v65, v71
	s_waitcnt lgkmcnt(6)
	v_fmac_f32_e32 v85, v61, v72
	v_fmac_f32_e32 v85, v62, v73
	v_pk_mul_f32 v[68:69], v[34:35], v[74:75]
	v_add_f32_e32 v68, v85, v68
	v_add_f32_e32 v70, v68, v69
	s_waitcnt lgkmcnt(5)
	v_pk_mul_f32 v[68:69], v[36:37], v[76:77]
	s_nop 0
	v_add_f32_e32 v68, v70, v68
	v_add_f32_e32 v70, v68, v69
	v_pk_mul_f32 v[68:69], v[38:39], v[78:79]
	s_nop 0
	v_add_f32_e32 v68, v70, v68
	v_add_f32_e32 v70, v68, v69
	s_waitcnt lgkmcnt(4)
; DEVI float logsigf_(float x) { return fminf(x, 0.f) - __logf(1.f + __expf(-fabsf(x))); }
; DEVI float gla_la(const float* gl, int t, const float* w2r, float gb) { float x = gb;
; #pragma unroll
;     for (int r = 0; r < 16; ++r) x += gl[t * 16 + r] * w2r[r];
;     return logsigf_(x) * (1.f / 16.f); }
; template <int KIND>
; DEVI void mix_out_phase(unsigned char* smem, const MixArgs a) {
;     ...
;             for (int t = sg * 32; t < sg * 32 + 32; ++t) ssum += gla_la(gl, t, w2r, gb);
	v_pk_mul_f32 v[68:69], v[40:41], v[80:81]
	s_nop 0
	v_add_f32_e32 v68, v70, v68
	v_add_f32_e32 v70, v68, v69
	s_waitcnt vmcnt(0)
	v_pk_mul_f32 v[68:69], v[58:59], v[82:83]
	s_nop 0
	v_add_f32_e32 v68, v70, v68
	v_add_f32_e32 v68, v68, v69
	v_min_f32_e32 v69, 0, v68
	v_mul_f32_e64 v68, |v68|, s73
	v_exp_f32_e32 v68, v68
	s_nop 0
	v_add_f32_e32 v68, 1.0, v68
	v_cmp_gt_f32_e32 vcc, s94, v68
	s_nop 1
	v_cndmask_b32_e64 v70, 0, 32, vcc
	v_ldexp_f32 v68, v68, v70
	v_log_f32_e32 v68, v68
	s_nop 0
	v_mul_f32_e32 v70, 0x3f317217, v68
	v_fma_f32 v70, v68, s97, -v70
	v_fmac_f32_e32 v70, 0x3377d1cf, v68
	v_fmac_f32_e32 v70, 0x3f317217, v68
	v_cmp_lt_f32_e64 s[14:15], |v68|, s23
	s_nop 1
	v_cndmask_b32_e64 v68, v68, v70, s[14:15]
	v_cndmask_b32_e32 v70, 0, v211, vcc
	v_sub_f32_e32 v68, v68, v70
	v_sub_f32_e32 v68, v69, v68
	v_fmac_f32_e32 v67, 0x3d800000, v68
	v_mov_b32_e32 v90, v68
	s_waitcnt lgkmcnt(0)
	v_fma_f32 v72, v63, v100, v66
	v_fmac_f32_e32 v72, v64, v101
	v_fmac_f32_e32 v72, v60, v102
	v_fmac_f32_e32 v72, v65, v103
	v_fmac_f32_e32 v72, v61, v104
	v_fmac_f32_e32 v72, v62, v105
	v_pk_mul_f32 v[68:69], v[34:35], v[106:107]
	s_nop 0
	v_add_f32_e32 v68, v72, v68
	v_add_f32_e32 v72, v68, v69
	v_pk_mul_f32 v[68:69], v[36:37], v[108:109]
	s_nop 0
	v_add_f32_e32 v68, v72, v68
	v_add_f32_e32 v72, v68, v69
	v_pk_mul_f32 v[68:69], v[38:39], v[110:111]
	s_nop 0
	v_add_f32_e32 v68, v72, v68
	v_add_f32_e32 v72, v68, v69
	v_pk_mul_f32 v[68:69], v[40:41], v[112:113]
	s_nop 0
	v_add_f32_e32 v68, v72, v68
	v_add_f32_e32 v72, v68, v69
	v_pk_mul_f32 v[68:69], v[58:59], v[114:115]
	s_nop 0
	v_add_f32_e32 v68, v72, v68
	v_add_f32_e32 v68, v68, v69
	v_min_f32_e32 v69, 0, v68
	v_mul_f32_e64 v68, |v68|, s73
	v_exp_f32_e32 v68, v68
	s_nop 0
	v_add_f32_e32 v68, 1.0, v68
	v_cmp_gt_f32_e32 vcc, s94, v68
	s_nop 1
	v_cndmask_b32_e64 v70, 0, 32, vcc
	v_ldexp_f32 v68, v68, v70
	v_log_f32_e32 v68, v68
	s_nop 0
	v_mul_f32_e32 v70, 0x3f317217, v68
	v_fma_f32 v70, v68, s97, -v70
	v_fmac_f32_e32 v70, 0x3377d1cf, v68
	v_fmac_f32_e32 v70, 0x3f317217, v68
	v_cmp_lt_f32_e64 s[14:15], |v68|, s23
	s_nop 1
	v_cndmask_b32_e64 v68, v68, v70, s[14:15]
	v_cndmask_b32_e32 v70, 0, v211, vcc
	v_sub_f32_e32 v68, v68, v70
	v_sub_f32_e32 v68, v69, v68
	v_fmac_f32_e32 v67, 0x3d800000, v68
	v_mov_b32_e32 v91, v68
	v_add_u32_e32 v84, s0, v195
	ds_read_b128 v[68:71], v84
	ds_read_b128 v[72:75], v84 offset:16
	ds_read_b128 v[76:79], v84 offset:32
	ds_read_b128 v[80:83], v84 offset:48
	ds_read_b128 v[100:103], v84 offset:64
	ds_read_b128 v[104:107], v84 offset:80
	ds_read_b128 v[108:111], v84 offset:96
	ds_read_b128 v[112:115], v84 offset:112
	s_addk_i32 s0, 0x80
	s_waitcnt vmcnt(1) lgkmcnt(7)
	v_fma_f32 v85, v63, v68, v66
	v_fmac_f32_e32 v85, v64, v69
	v_fmac_f32_e32 v85, v60, v70
	v_fmac_f32_e32 v85, v65, v71
	s_waitcnt lgkmcnt(6)
	v_fmac_f32_e32 v85, v61, v72
	v_fmac_f32_e32 v85, v62, v73
	v_pk_mul_f32 v[68:69], v[34:35], v[74:75]
	v_add_f32_e32 v68, v85, v68
	v_add_f32_e32 v70, v68, v69
	s_waitcnt lgkmcnt(5)
	v_pk_mul_f32 v[68:69], v[36:37], v[76:77]
	s_nop 0
	v_add_f32_e32 v68, v70, v68
	v_add_f32_e32 v70, v68, v69
	v_pk_mul_f32 v[68:69], v[38:39], v[78:79]
	s_nop 0
	v_add_f32_e32 v68, v70, v68
	v_add_f32_e32 v70, v68, v69
	s_waitcnt lgkmcnt(4)
	v_pk_mul_f32 v[68:69], v[40:41], v[80:81]
	s_nop 0
	v_add_f32_e32 v68, v70, v68
	v_add_f32_e32 v70, v68, v69
	s_waitcnt vmcnt(0)
	v_pk_mul_f32 v[68:69], v[58:59], v[82:83]
	s_nop 0
	v_add_f32_e32 v68, v70, v68
	v_add_f32_e32 v68, v68, v69
	v_min_f32_e32 v69, 0, v68
	v_mul_f32_e64 v68, |v68|, s73
	v_exp_f32_e32 v68, v68
	s_nop 0
	v_add_f32_e32 v68, 1.0, v68
	v_cmp_gt_f32_e32 vcc, s94, v68
	s_nop 1
	v_cndmask_b32_e64 v70, 0, 32, vcc
	v_ldexp_f32 v68, v68, v70
	v_log_f32_e32 v68, v68
	s_nop 0
	v_mul_f32_e32 v70, 0x3f317217, v68
	v_fma_f32 v70, v68, s97, -v70
	v_fmac_f32_e32 v70, 0x3377d1cf, v68
	v_fmac_f32_e32 v70, 0x3f317217, v68
	v_cmp_lt_f32_e64 s[14:15], |v68|, s23
	s_nop 1
	v_cndmask_b32_e64 v68, v68, v70, s[14:15]
	v_cndmask_b32_e32 v70, 0, v211, vcc
	v_sub_f32_e32 v68, v68, v70
	v_sub_f32_e32 v68, v69, v68
	v_fmac_f32_e32 v67, 0x3d800000, v68
	v_mov_b32_e32 v92, v68
	s_waitcnt lgkmcnt(0)
	v_fma_f32 v72, v63, v100, v66
	v_fmac_f32_e32 v72, v64, v101
	v_fmac_f32_e32 v72, v60, v102
	v_fmac_f32_e32 v72, v65, v103
	v_fmac_f32_e32 v72, v61, v104
	v_fmac_f32_e32 v72, v62, v105
	v_pk_mul_f32 v[68:69], v[34:35], v[106:107]
	s_nop 0
	v_add_f32_e32 v68, v72, v68
	v_add_f32_e32 v72, v68, v69
	v_pk_mul_f32 v[68:69], v[36:37], v[108:109]
	s_nop 0
	v_add_f32_e32 v68, v72, v68
	v_add_f32_e32 v72, v68, v69
	v_pk_mul_f32 v[68:69], v[38:39], v[110:111]
	s_nop 0
	v_add_f32_e32 v68, v72, v68
	v_add_f32_e32 v72, v68, v69
	v_pk_mul_f32 v[68:69], v[40:41], v[112:113]
	s_nop 0
	v_add_f32_e32 v68, v72, v68
	v_add_f32_e32 v72, v68, v69
	v_pk_mul_f32 v[68:69], v[58:59], v[114:115]
	s_nop 0
	v_add_f32_e32 v68, v72, v68
	v_add_f32_e32 v68, v68, v69
	v_min_f32_e32 v69, 0, v68
	v_mul_f32_e64 v68, |v68|, s73
	v_exp_f32_e32 v68, v68
	s_nop 0
	v_add_f32_e32 v68, 1.0, v68
	v_cmp_gt_f32_e32 vcc, s94, v68
	s_nop 1
	v_cndmask_b32_e64 v70, 0, 32, vcc
	v_ldexp_f32 v68, v68, v70
	v_log_f32_e32 v68, v68
	s_nop 0
	v_mul_f32_e32 v70, 0x3f317217, v68
	v_fma_f32 v70, v68, s97, -v70
	v_fmac_f32_e32 v70, 0x3377d1cf, v68
	v_fmac_f32_e32 v70, 0x3f317217, v68
	v_cmp_lt_f32_e64 s[14:15], |v68|, s23
	s_nop 1
	v_cndmask_b32_e64 v68, v68, v70, s[14:15]
	v_cndmask_b32_e32 v70, 0, v211, vcc
	v_sub_f32_e32 v68, v68, v70
	v_sub_f32_e32 v68, v69, v68
	v_fmac_f32_e32 v67, 0x3d800000, v68
	v_mov_b32_e32 v93, v68
	v_add_u32_e32 v84, s0, v195
	ds_read_b128 v[68:71], v84
	ds_read_b128 v[72:75], v84 offset:16
	ds_read_b128 v[76:79], v84 offset:32
	ds_read_b128 v[80:83], v84 offset:48
	ds_read_b128 v[100:103], v84 offset:64
	ds_read_b128 v[104:107], v84 offset:80
	ds_read_b128 v[108:111], v84 offset:96
	ds_read_b128 v[112:115], v84 offset:112
	s_addk_i32 s0, 0x80
	s_waitcnt vmcnt(1) lgkmcnt(7)
; DEVI float logsigf_(float x) { return fminf(x, 0.f) - __logf(1.f + __expf(-fabsf(x))); }
; DEVI float gla_la(const float* gl, int t, const float* w2r, float gb) { float x = gb;
; #pragma unroll
;     for (int r = 0; r < 16; ++r) x += gl[t * 16 + r] * w2r[r];
;     return logsigf_(x) * (1.f / 16.f); }
; template <int KIND>
; DEVI void mix_out_phase(unsigned char* smem, const MixArgs a) {
;     ...
;             for (int t = sg * 32; t < sg * 32 + 32; ++t) ssum += gla_la(gl, t, w2r, gb);
	v_fma_f32 v85, v63, v68, v66
	v_fmac_f32_e32 v85, v64, v69
	v_fmac_f32_e32 v85, v60, v70
	v_fmac_f32_e32 v85, v65, v71
	s_waitcnt lgkmcnt(6)
	v_fmac_f32_e32 v85, v61, v72
	v_fmac_f32_e32 v85, v62, v73
	v_pk_mul_f32 v[68:69], v[34:35], v[74:75]
	v_add_f32_e32 v68, v85, v68
	v_add_f32_e32 v70, v68, v69
	s_waitcnt lgkmcnt(5)
	v_pk_mul_f32 v[68:69], v[36:37], v[76:77]
	s_nop 0
	v_add_f32_e32 v68, v70, v68
	v_add_f32_e32 v70, v68, v69
	v_pk_mul_f32 v[68:69], v[38:39], v[78:79]
	s_nop 0
	v_add_f32_e32 v68, v70, v68
	v_add_f32_e32 v70, v68, v69
	s_waitcnt lgkmcnt(4)
	v_pk_mul_f32 v[68:69], v[40:41], v[80:81]
	s_nop 0
	v_add_f32_e32 v68, v70, v68
	v_add_f32_e32 v70, v68, v69
	s_waitcnt vmcnt(0)
	v_pk_mul_f32 v[68:69], v[58:59], v[82:83]
	s_nop 0
	v_add_f32_e32 v68, v70, v68
	v_add_f32_e32 v68, v68, v69
	v_min_f32_e32 v69, 0, v68
	v_mul_f32_e64 v68, |v68|, s73
	v_exp_f32_e32 v68, v68
	s_nop 0
	v_add_f32_e32 v68, 1.0, v68
	v_cmp_gt_f32_e32 vcc, s94, v68
	s_nop 1
	v_cndmask_b32_e64 v70, 0, 32, vcc
	v_ldexp_f32 v68, v68, v70
	v_log_f32_e32 v68, v68
	s_nop 0
	v_mul_f32_e32 v70, 0x3f317217, v68
	v_fma_f32 v70, v68, s97, -v70
	v_fmac_f32_e32 v70, 0x3377d1cf, v68
	v_fmac_f32_e32 v70, 0x3f317217, v68
	v_cmp_lt_f32_e64 s[14:15], |v68|, s23
	s_nop 1
	v_cndmask_b32_e64 v68, v68, v70, s[14:15]
	v_cndmask_b32_e32 v70, 0, v211, vcc
	v_sub_f32_e32 v68, v68, v70
	v_sub_f32_e32 v68, v69, v68
	v_fmac_f32_e32 v67, 0x3d800000, v68
	v_mov_b32_e32 v94, v68
	s_waitcnt lgkmcnt(0)
	v_fma_f32 v72, v63, v100, v66
	v_fmac_f32_e32 v72, v64, v101
	v_fmac_f32_e32 v72, v60, v102
	v_fmac_f32_e32 v72, v65, v103
	v_fmac_f32_e32 v72, v61, v104
	v_fmac_f32_e32 v72, v62, v105
	v_pk_mul_f32 v[68:69], v[34:35], v[106:107]
	s_nop 0
	v_add_f32_e32 v68, v72, v68
	v_add_f32_e32 v72, v68, v69
	v_pk_mul_f32 v[68:69], v[36:37], v[108:109]
	s_nop 0
	v_add_f32_e32 v68, v72, v68
	v_add_f32_e32 v72, v68, v69
	v_pk_mul_f32 v[68:69], v[38:39], v[110:111]
	s_nop 0
	v_add_f32_e32 v68, v72, v68
	v_add_f32_e32 v72, v68, v69
	v_pk_mul_f32 v[68:69], v[40:41], v[112:113]
	s_nop 0
	v_add_f32_e32 v68, v72, v68
	v_add_f32_e32 v72, v68, v69
	v_pk_mul_f32 v[68:69], v[58:59], v[114:115]
	s_nop 0
	v_add_f32_e32 v68, v72, v68
	v_add_f32_e32 v68, v68, v69
	v_min_f32_e32 v69, 0, v68
	v_mul_f32_e64 v68, |v68|, s73
	v_exp_f32_e32 v68, v68
	s_nop 0
	v_add_f32_e32 v68, 1.0, v68
	v_cmp_gt_f32_e32 vcc, s94, v68
	s_nop 1
	v_cndmask_b32_e64 v70, 0, 32, vcc
	v_ldexp_f32 v68, v68, v70
	v_log_f32_e32 v68, v68
	s_nop 0
	v_mul_f32_e32 v70, 0x3f317217, v68
	v_fma_f32 v70, v68, s97, -v70
	v_fmac_f32_e32 v70, 0x3377d1cf, v68
	v_fmac_f32_e32 v70, 0x3f317217, v68
	v_cmp_lt_f32_e64 s[14:15], |v68|, s23
	s_nop 1
	v_cndmask_b32_e64 v68, v68, v70, s[14:15]
	v_cndmask_b32_e32 v70, 0, v211, vcc
	v_sub_f32_e32 v68, v68, v70
	v_sub_f32_e32 v68, v69, v68
	v_fmac_f32_e32 v67, 0x3d800000, v68
	v_mov_b32_e32 v95, v68
	v_add_u32_e32 v84, s0, v195
	ds_read_b128 v[68:71], v84
	ds_read_b128 v[72:75], v84 offset:16
	ds_read_b128 v[76:79], v84 offset:32
	ds_read_b128 v[80:83], v84 offset:48
	ds_read_b128 v[100:103], v84 offset:64
	ds_read_b128 v[104:107], v84 offset:80
	ds_read_b128 v[108:111], v84 offset:96
	ds_read_b128 v[112:115], v84 offset:112
	s_addk_i32 s0, 0x80
	s_waitcnt vmcnt(1) lgkmcnt(7)
	v_fma_f32 v85, v63, v68, v66
	v_fmac_f32_e32 v85, v64, v69
	v_fmac_f32_e32 v85, v60, v70
	v_fmac_f32_e32 v85, v65, v71
	s_waitcnt lgkmcnt(6)
	v_fmac_f32_e32 v85, v61, v72
	v_fmac_f32_e32 v85, v62, v73
	v_pk_mul_f32 v[68:69], v[34:35], v[74:75]
	v_add_f32_e32 v68, v85, v68
	v_add_f32_e32 v70, v68, v69
	s_waitcnt lgkmcnt(5)
	v_pk_mul_f32 v[68:69], v[36:37], v[76:77]
	s_nop 0
	v_add_f32_e32 v68, v70, v68
	v_add_f32_e32 v70, v68, v69
	v_pk_mul_f32 v[68:69], v[38:39], v[78:79]
	s_nop 0
	v_add_f32_e32 v68, v70, v68
	v_add_f32_e32 v70, v68, v69
	s_waitcnt lgkmcnt(4)
	v_pk_mul_f32 v[68:69], v[40:41], v[80:81]
	s_nop 0
	v_add_f32_e32 v68, v70, v68
	v_add_f32_e32 v70, v68, v69
	s_waitcnt vmcnt(0)
	v_pk_mul_f32 v[68:69], v[58:59], v[82:83]
	s_nop 0
	v_add_f32_e32 v68, v70, v68
	v_add_f32_e32 v68, v68, v69
	v_min_f32_e32 v69, 0, v68
	v_mul_f32_e64 v68, |v68|, s73
	v_exp_f32_e32 v68, v68
	s_nop 0
	v_add_f32_e32 v68, 1.0, v68
	v_cmp_gt_f32_e32 vcc, s94, v68
	s_nop 1
	v_cndmask_b32_e64 v70, 0, 32, vcc
	v_ldexp_f32 v68, v68, v70
	v_log_f32_e32 v68, v68
	s_nop 0
	v_mul_f32_e32 v70, 0x3f317217, v68
	v_fma_f32 v70, v68, s97, -v70
	v_fmac_f32_e32 v70, 0x3377d1cf, v68
	v_fmac_f32_e32 v70, 0x3f317217, v68
	v_cmp_lt_f32_e64 s[14:15], |v68|, s23
	s_nop 1
	v_cndmask_b32_e64 v68, v68, v70, s[14:15]
	v_cndmask_b32_e32 v70, 0, v211, vcc
	v_sub_f32_e32 v68, v68, v70
	v_sub_f32_e32 v68, v69, v68
	v_fmac_f32_e32 v67, 0x3d800000, v68
	v_mov_b32_e32 v96, v68
	s_waitcnt lgkmcnt(0)
	v_fma_f32 v72, v63, v100, v66
	v_fmac_f32_e32 v72, v64, v101
	v_fmac_f32_e32 v72, v60, v102
	v_fmac_f32_e32 v72, v65, v103
	v_fmac_f32_e32 v72, v61, v104
	v_fmac_f32_e32 v72, v62, v105
	v_pk_mul_f32 v[68:69], v[34:35], v[106:107]
	s_nop 0
	v_add_f32_e32 v68, v72, v68
	v_add_f32_e32 v72, v68, v69
	v_pk_mul_f32 v[68:69], v[36:37], v[108:109]
	s_nop 0
	v_add_f32_e32 v68, v72, v68
	v_add_f32_e32 v72, v68, v69
	v_pk_mul_f32 v[68:69], v[38:39], v[110:111]
	s_nop 0
	v_add_f32_e32 v68, v72, v68
	v_add_f32_e32 v72, v68, v69
	v_pk_mul_f32 v[68:69], v[40:41], v[112:113]
	s_nop 0
	v_add_f32_e32 v68, v72, v68
	v_add_f32_e32 v72, v68, v69
	v_pk_mul_f32 v[68:69], v[58:59], v[114:115]
	s_nop 0
	v_add_f32_e32 v68, v72, v68
	v_add_f32_e32 v68, v68, v69
	v_min_f32_e32 v69, 0, v68
	v_mul_f32_e64 v68, |v68|, s73
	v_exp_f32_e32 v68, v68
	s_nop 0
	v_add_f32_e32 v68, 1.0, v68
	v_cmp_gt_f32_e32 vcc, s94, v68
	s_nop 1
	v_cndmask_b32_e64 v70, 0, 32, vcc
	v_ldexp_f32 v68, v68, v70
	v_log_f32_e32 v68, v68
	s_nop 0
	v_mul_f32_e32 v70, 0x3f317217, v68
	v_fma_f32 v70, v68, s97, -v70
	v_fmac_f32_e32 v70, 0x3377d1cf, v68
	v_fmac_f32_e32 v70, 0x3f317217, v68
	v_cmp_lt_f32_e64 s[14:15], |v68|, s23
	s_nop 1
	v_cndmask_b32_e64 v68, v68, v70, s[14:15]
	v_cndmask_b32_e32 v70, 0, v211, vcc
	v_sub_f32_e32 v68, v68, v70
	v_sub_f32_e32 v68, v69, v68
	v_fmac_f32_e32 v67, 0x3d800000, v68
	v_mov_b32_e32 v97, v68
	v_add_u32_e32 v84, s0, v195
	ds_read_b128 v[68:71], v84
	ds_read_b128 v[72:75], v84 offset:16
	ds_read_b128 v[76:79], v84 offset:32
	ds_read_b128 v[80:83], v84 offset:48
	ds_read_b128 v[100:103], v84 offset:64
	ds_read_b128 v[104:107], v84 offset:80
	ds_read_b128 v[108:111], v84 offset:96
	ds_read_b128 v[112:115], v84 offset:112
	s_addk_i32 s0, 0x80
	s_waitcnt vmcnt(1) lgkmcnt(7)
; DEVI float logsigf_(float x) { return fminf(x, 0.f) - __logf(1.f + __expf(-fabsf(x))); }
; DEVI float gla_la(const float* gl, int t, const float* w2r, float gb) { float x = gb;
; #pragma unroll
;     for (int r = 0; r < 16; ++r) x += gl[t * 16 + r] * w2r[r];
;     return logsigf_(x) * (1.f / 16.f); }
; template <int KIND>
; DEVI void mix_out_phase(unsigned char* smem, const MixArgs a) {
;     ...
;             for (int t = sg * 32; t < sg * 32 + 32; ++t) ssum += gla_la(gl, t, w2r, gb);
	v_fma_f32 v85, v63, v68, v66
	v_fmac_f32_e32 v85, v64, v69
	v_fmac_f32_e32 v85, v60, v70
	v_fmac_f32_e32 v85, v65, v71
	s_waitcnt lgkmcnt(6)
	v_fmac_f32_e32 v85, v61, v72
	v_fmac_f32_e32 v85, v62, v73
	v_pk_mul_f32 v[68:69], v[34:35], v[74:75]
	v_add_f32_e32 v68, v85, v68
	v_add_f32_e32 v70, v68, v69
	s_waitcnt lgkmcnt(5)
	v_pk_mul_f32 v[68:69], v[36:37], v[76:77]
	s_nop 0
	v_add_f32_e32 v68, v70, v68
	v_add_f32_e32 v70, v68, v69
	v_pk_mul_f32 v[68:69], v[38:39], v[78:79]
	s_nop 0
	v_add_f32_e32 v68, v70, v68
	v_add_f32_e32 v70, v68, v69
	s_waitcnt lgkmcnt(4)
	v_pk_mul_f32 v[68:69], v[40:41], v[80:81]
	s_nop 0
	v_add_f32_e32 v68, v70, v68
	v_add_f32_e32 v70, v68, v69
	s_waitcnt vmcnt(0)
	v_pk_mul_f32 v[68:69], v[58:59], v[82:83]
	s_nop 0
	v_add_f32_e32 v68, v70, v68
	v_add_f32_e32 v68, v68, v69
	v_min_f32_e32 v69, 0, v68
	v_mul_f32_e64 v68, |v68|, s73
	v_exp_f32_e32 v68, v68
	s_nop 0
	v_add_f32_e32 v68, 1.0, v68
	v_cmp_gt_f32_e32 vcc, s94, v68
	s_nop 1
	v_cndmask_b32_e64 v70, 0, 32, vcc
	v_ldexp_f32 v68, v68, v70
	v_log_f32_e32 v68, v68
	s_nop 0
	v_mul_f32_e32 v70, 0x3f317217, v68
	v_fma_f32 v70, v68, s97, -v70
	v_fmac_f32_e32 v70, 0x3377d1cf, v68
	v_fmac_f32_e32 v70, 0x3f317217, v68
	v_cmp_lt_f32_e64 s[14:15], |v68|, s23
	s_nop 1
	v_cndmask_b32_e64 v68, v68, v70, s[14:15]
	v_cndmask_b32_e32 v70, 0, v211, vcc
	v_sub_f32_e32 v68, v68, v70
	v_sub_f32_e32 v68, v69, v68
	v_fmac_f32_e32 v67, 0x3d800000, v68
	v_mov_b32_e32 v98, v68
	s_waitcnt lgkmcnt(0)
	v_fma_f32 v72, v63, v100, v66
	v_fmac_f32_e32 v72, v64, v101
	v_fmac_f32_e32 v72, v60, v102
	v_fmac_f32_e32 v72, v65, v103
	v_fmac_f32_e32 v72, v61, v104
	v_fmac_f32_e32 v72, v62, v105
	v_pk_mul_f32 v[68:69], v[34:35], v[106:107]
	s_nop 0
	v_add_f32_e32 v68, v72, v68
	v_add_f32_e32 v72, v68, v69
	v_pk_mul_f32 v[68:69], v[36:37], v[108:109]
	s_nop 0
	v_add_f32_e32 v68, v72, v68
	v_add_f32_e32 v72, v68, v69
	v_pk_mul_f32 v[68:69], v[38:39], v[110:111]
	s_nop 0
	v_add_f32_e32 v68, v72, v68
	v_add_f32_e32 v72, v68, v69
	v_pk_mul_f32 v[68:69], v[40:41], v[112:113]
	s_nop 0
	v_add_f32_e32 v68, v72, v68
	v_add_f32_e32 v72, v68, v69
	v_pk_mul_f32 v[68:69], v[58:59], v[114:115]
	s_nop 0
	v_add_f32_e32 v68, v72, v68
	v_add_f32_e32 v68, v68, v69
	v_min_f32_e32 v69, 0, v68
	v_mul_f32_e64 v68, |v68|, s73
	v_exp_f32_e32 v68, v68
	s_nop 0
	v_add_f32_e32 v68, 1.0, v68
	v_cmp_gt_f32_e32 vcc, s94, v68
	s_nop 1
	v_cndmask_b32_e64 v70, 0, 32, vcc
	v_ldexp_f32 v68, v68, v70
	v_log_f32_e32 v68, v68
	s_nop 0
	v_mul_f32_e32 v70, 0x3f317217, v68
	v_fma_f32 v70, v68, s97, -v70
	v_fmac_f32_e32 v70, 0x3377d1cf, v68
	v_fmac_f32_e32 v70, 0x3f317217, v68
	v_cmp_lt_f32_e64 s[14:15], |v68|, s23
	s_nop 1
	v_cndmask_b32_e64 v68, v68, v70, s[14:15]
	v_cndmask_b32_e32 v70, 0, v211, vcc
	v_sub_f32_e32 v68, v68, v70
	v_sub_f32_e32 v68, v69, v68
	v_fmac_f32_e32 v67, 0x3d800000, v68
	v_mov_b32_e32 v99, v68
	v_add_u32_e32 v84, s0, v195
	ds_read_b128 v[68:71], v84
	ds_read_b128 v[72:75], v84 offset:16
	ds_read_b128 v[76:79], v84 offset:32
	ds_read_b128 v[80:83], v84 offset:48
	ds_read_b128 v[100:103], v84 offset:64
	ds_read_b128 v[104:107], v84 offset:80
	ds_read_b128 v[108:111], v84 offset:96
	ds_read_b128 v[112:115], v84 offset:112
	s_addk_i32 s0, 0x80
	s_waitcnt vmcnt(1) lgkmcnt(7)
	v_fma_f32 v85, v63, v68, v66
	v_fmac_f32_e32 v85, v64, v69
	v_fmac_f32_e32 v85, v60, v70
	v_fmac_f32_e32 v85, v65, v71
	s_waitcnt lgkmcnt(6)
	v_fmac_f32_e32 v85, v61, v72
	v_fmac_f32_e32 v85, v62, v73
	v_pk_mul_f32 v[68:69], v[34:35], v[74:75]
	v_add_f32_e32 v68, v85, v68
	v_add_f32_e32 v70, v68, v69
	s_waitcnt lgkmcnt(5)
	v_pk_mul_f32 v[68:69], v[36:37], v[76:77]
	s_nop 0
	v_add_f32_e32 v68, v70, v68
	v_add_f32_e32 v70, v68, v69
	v_pk_mul_f32 v[68:69], v[38:39], v[78:79]
	s_nop 0
	v_add_f32_e32 v68, v70, v68
	v_add_f32_e32 v70, v68, v69
	s_waitcnt lgkmcnt(4)
	v_pk_mul_f32 v[68:69], v[40:41], v[80:81]
	s_nop 0
	v_add_f32_e32 v68, v70, v68
	v_add_f32_e32 v70, v68, v69
	s_waitcnt vmcnt(0)
	v_pk_mul_f32 v[68:69], v[58:59], v[82:83]
	s_nop 0
	v_add_f32_e32 v68, v70, v68
	v_add_f32_e32 v68, v68, v69
	v_min_f32_e32 v69, 0, v68
	v_mul_f32_e64 v68, |v68|, s73
	v_exp_f32_e32 v68, v68
	s_nop 0
	v_add_f32_e32 v68, 1.0, v68
	v_cmp_gt_f32_e32 vcc, s94, v68
	s_nop 1
	v_cndmask_b32_e64 v70, 0, 32, vcc
	v_ldexp_f32 v68, v68, v70
	v_log_f32_e32 v68, v68
	s_nop 0
	v_mul_f32_e32 v70, 0x3f317217, v68
	v_fma_f32 v70, v68, s97, -v70
	v_fmac_f32_e32 v70, 0x3377d1cf, v68
	v_fmac_f32_e32 v70, 0x3f317217, v68
	v_cmp_lt_f32_e64 s[14:15], |v68|, s23
	s_nop 1
	v_cndmask_b32_e64 v68, v68, v70, s[14:15]
	v_cndmask_b32_e32 v70, 0, v211, vcc
	v_sub_f32_e32 v68, v68, v70
	v_sub_f32_e32 v68, v69, v68
	v_fmac_f32_e32 v67, 0x3d800000, v68
	v_mov_b32_e32 v116, v68
	s_waitcnt lgkmcnt(0)
	v_fma_f32 v72, v63, v100, v66
	v_fmac_f32_e32 v72, v64, v101
	v_fmac_f32_e32 v72, v60, v102
	v_fmac_f32_e32 v72, v65, v103
	v_fmac_f32_e32 v72, v61, v104
	v_fmac_f32_e32 v72, v62, v105
	v_pk_mul_f32 v[68:69], v[34:35], v[106:107]
	s_nop 0
	v_add_f32_e32 v68, v72, v68
	v_add_f32_e32 v72, v68, v69
	v_pk_mul_f32 v[68:69], v[36:37], v[108:109]
	s_nop 0
	v_add_f32_e32 v68, v72, v68
	v_add_f32_e32 v72, v68, v69
	v_pk_mul_f32 v[68:69], v[38:39], v[110:111]
	s_nop 0
	v_add_f32_e32 v68, v72, v68
	v_add_f32_e32 v72, v68, v69
	v_pk_mul_f32 v[68:69], v[40:41], v[112:113]
	s_nop 0
	v_add_f32_e32 v68, v72, v68
	v_add_f32_e32 v72, v68, v69
	v_pk_mul_f32 v[68:69], v[58:59], v[114:115]
	s_nop 0
	v_add_f32_e32 v68, v72, v68
	v_add_f32_e32 v68, v68, v69
	v_min_f32_e32 v69, 0, v68
	v_mul_f32_e64 v68, |v68|, s73
	v_exp_f32_e32 v68, v68
	s_nop 0
	v_add_f32_e32 v68, 1.0, v68
	v_cmp_gt_f32_e32 vcc, s94, v68
	s_nop 1
	v_cndmask_b32_e64 v70, 0, 32, vcc
	v_ldexp_f32 v68, v68, v70
	v_log_f32_e32 v68, v68
	s_nop 0
	v_mul_f32_e32 v70, 0x3f317217, v68
	v_fma_f32 v70, v68, s97, -v70
	v_fmac_f32_e32 v70, 0x3377d1cf, v68
	v_fmac_f32_e32 v70, 0x3f317217, v68
	v_cmp_lt_f32_e64 s[14:15], |v68|, s23
	s_nop 1
	v_cndmask_b32_e64 v68, v68, v70, s[14:15]
	v_cndmask_b32_e32 v70, 0, v211, vcc
	v_sub_f32_e32 v68, v68, v70
	v_sub_f32_e32 v68, v69, v68
	v_fmac_f32_e32 v67, 0x3d800000, v68
	v_mov_b32_e32 v117, v68
	v_add_u32_e32 v84, s0, v195
	ds_read_b128 v[68:71], v84
	ds_read_b128 v[72:75], v84 offset:16
	ds_read_b128 v[76:79], v84 offset:32
	ds_read_b128 v[80:83], v84 offset:48
	ds_read_b128 v[100:103], v84 offset:64
	ds_read_b128 v[104:107], v84 offset:80
	ds_read_b128 v[108:111], v84 offset:96
	ds_read_b128 v[112:115], v84 offset:112
	s_addk_i32 s0, 0x80
	s_waitcnt vmcnt(1) lgkmcnt(7)
; DEVI float logsigf_(float x) { return fminf(x, 0.f) - __logf(1.f + __expf(-fabsf(x))); }
; DEVI float gla_la(const float* gl, int t, const float* w2r, float gb) { float x = gb;
; #pragma unroll
;     for (int r = 0; r < 16; ++r) x += gl[t * 16 + r] * w2r[r];
;     return logsigf_(x) * (1.f / 16.f); }
; template <int KIND>
; DEVI void mix_out_phase(unsigned char* smem, const MixArgs a) {
;     ...
;             for (int t = sg * 32; t < sg * 32 + 32; ++t) ssum += gla_la(gl, t, w2r, gb);
	v_fma_f32 v85, v63, v68, v66
	v_fmac_f32_e32 v85, v64, v69
	v_fmac_f32_e32 v85, v60, v70
	v_fmac_f32_e32 v85, v65, v71
	s_waitcnt lgkmcnt(6)
	v_fmac_f32_e32 v85, v61, v72
	v_fmac_f32_e32 v85, v62, v73
	v_pk_mul_f32 v[68:69], v[34:35], v[74:75]
	v_add_f32_e32 v68, v85, v68
	v_add_f32_e32 v70, v68, v69
	s_waitcnt lgkmcnt(5)
	v_pk_mul_f32 v[68:69], v[36:37], v[76:77]
	s_nop 0
	v_add_f32_e32 v68, v70, v68
	v_add_f32_e32 v70, v68, v69
	v_pk_mul_f32 v[68:69], v[38:39], v[78:79]
	s_nop 0
	v_add_f32_e32 v68, v70, v68
	v_add_f32_e32 v70, v68, v69
	s_waitcnt lgkmcnt(4)
	v_pk_mul_f32 v[68:69], v[40:41], v[80:81]
	s_nop 0
	v_add_f32_e32 v68, v70, v68
	v_add_f32_e32 v70, v68, v69
	s_waitcnt vmcnt(0)
	v_pk_mul_f32 v[68:69], v[58:59], v[82:83]
	s_nop 0
	v_add_f32_e32 v68, v70, v68
	v_add_f32_e32 v68, v68, v69
	v_min_f32_e32 v69, 0, v68
	v_mul_f32_e64 v68, |v68|, s73
	v_exp_f32_e32 v68, v68
	s_nop 0
	v_add_f32_e32 v68, 1.0, v68
	v_cmp_gt_f32_e32 vcc, s94, v68
	s_nop 1
	v_cndmask_b32_e64 v70, 0, 32, vcc
	v_ldexp_f32 v68, v68, v70
	v_log_f32_e32 v68, v68
	s_nop 0
	v_mul_f32_e32 v70, 0x3f317217, v68
	v_fma_f32 v70, v68, s97, -v70
	v_fmac_f32_e32 v70, 0x3377d1cf, v68
	v_fmac_f32_e32 v70, 0x3f317217, v68
	v_cmp_lt_f32_e64 s[14:15], |v68|, s23
	s_nop 1
	v_cndmask_b32_e64 v68, v68, v70, s[14:15]
	v_cndmask_b32_e32 v70, 0, v211, vcc
	v_sub_f32_e32 v68, v68, v70
	v_sub_f32_e32 v68, v69, v68
	v_fmac_f32_e32 v67, 0x3d800000, v68
	v_mov_b32_e32 v118, v68
	s_waitcnt lgkmcnt(0)
	v_fma_f32 v72, v63, v100, v66
	v_fmac_f32_e32 v72, v64, v101
	v_fmac_f32_e32 v72, v60, v102
	v_fmac_f32_e32 v72, v65, v103
	v_fmac_f32_e32 v72, v61, v104
	v_fmac_f32_e32 v72, v62, v105
	v_pk_mul_f32 v[68:69], v[34:35], v[106:107]
	s_nop 0
	v_add_f32_e32 v68, v72, v68
	v_add_f32_e32 v72, v68, v69
	v_pk_mul_f32 v[68:69], v[36:37], v[108:109]
	s_nop 0
	v_add_f32_e32 v68, v72, v68
	v_add_f32_e32 v72, v68, v69
	v_pk_mul_f32 v[68:69], v[38:39], v[110:111]
	s_nop 0
	v_add_f32_e32 v68, v72, v68
	v_add_f32_e32 v72, v68, v69
	v_pk_mul_f32 v[68:69], v[40:41], v[112:113]
	s_nop 0
	v_add_f32_e32 v68, v72, v68
	v_add_f32_e32 v72, v68, v69
	v_pk_mul_f32 v[68:69], v[58:59], v[114:115]
	s_nop 0
	v_add_f32_e32 v68, v72, v68
	v_add_f32_e32 v68, v68, v69
	v_min_f32_e32 v69, 0, v68
	v_mul_f32_e64 v68, |v68|, s73
	v_exp_f32_e32 v68, v68
	s_nop 0
	v_add_f32_e32 v68, 1.0, v68
	v_cmp_gt_f32_e32 vcc, s94, v68
	s_nop 1
	v_cndmask_b32_e64 v70, 0, 32, vcc
	v_ldexp_f32 v68, v68, v70
	v_log_f32_e32 v68, v68
	s_nop 0
	v_mul_f32_e32 v70, 0x3f317217, v68
	v_fma_f32 v70, v68, s97, -v70
	v_fmac_f32_e32 v70, 0x3377d1cf, v68
	v_fmac_f32_e32 v70, 0x3f317217, v68
	v_cmp_lt_f32_e64 s[14:15], |v68|, s23
	s_nop 1
	v_cndmask_b32_e64 v68, v68, v70, s[14:15]
	v_cndmask_b32_e32 v70, 0, v211, vcc
	v_sub_f32_e32 v68, v68, v70
	v_sub_f32_e32 v68, v69, v68
	v_fmac_f32_e32 v67, 0x3d800000, v68
	v_mov_b32_e32 v119, v68
	v_add_u32_e32 v84, s0, v195
	ds_read_b128 v[68:71], v84
	ds_read_b128 v[72:75], v84 offset:16
	ds_read_b128 v[76:79], v84 offset:32
	ds_read_b128 v[80:83], v84 offset:48
	ds_read_b128 v[100:103], v84 offset:64
	ds_read_b128 v[104:107], v84 offset:80
	ds_read_b128 v[108:111], v84 offset:96
	ds_read_b128 v[112:115], v84 offset:112
	s_addk_i32 s0, 0x80
	s_waitcnt vmcnt(1) lgkmcnt(7)
	v_fma_f32 v85, v63, v68, v66
	v_fmac_f32_e32 v85, v64, v69
	v_fmac_f32_e32 v85, v60, v70
	v_fmac_f32_e32 v85, v65, v71
	s_waitcnt lgkmcnt(6)
	v_fmac_f32_e32 v85, v61, v72
	v_fmac_f32_e32 v85, v62, v73
	v_pk_mul_f32 v[68:69], v[34:35], v[74:75]
	v_add_f32_e32 v68, v85, v68
	v_add_f32_e32 v70, v68, v69
	s_waitcnt lgkmcnt(5)
	v_pk_mul_f32 v[68:69], v[36:37], v[76:77]
	s_nop 0
	v_add_f32_e32 v68, v70, v68
	v_add_f32_e32 v70, v68, v69
	v_pk_mul_f32 v[68:69], v[38:39], v[78:79]
	s_nop 0
	v_add_f32_e32 v68, v70, v68
	v_add_f32_e32 v70, v68, v69
	s_waitcnt lgkmcnt(4)
	v_pk_mul_f32 v[68:69], v[40:41], v[80:81]
	s_nop 0
	v_add_f32_e32 v68, v70, v68
	v_add_f32_e32 v70, v68, v69
	s_waitcnt vmcnt(0)
	v_pk_mul_f32 v[68:69], v[58:59], v[82:83]
	s_nop 0
	v_add_f32_e32 v68, v70, v68
	v_add_f32_e32 v68, v68, v69
	v_min_f32_e32 v69, 0, v68
	v_mul_f32_e64 v68, |v68|, s73
	v_exp_f32_e32 v68, v68
	s_nop 0
	v_add_f32_e32 v68, 1.0, v68
	v_cmp_gt_f32_e32 vcc, s94, v68
	s_nop 1
	v_cndmask_b32_e64 v70, 0, 32, vcc
	v_ldexp_f32 v68, v68, v70
	v_log_f32_e32 v68, v68
	s_nop 0
	v_mul_f32_e32 v70, 0x3f317217, v68
	v_fma_f32 v70, v68, s97, -v70
	v_fmac_f32_e32 v70, 0x3377d1cf, v68
	v_fmac_f32_e32 v70, 0x3f317217, v68
	v_cmp_lt_f32_e64 s[14:15], |v68|, s23
	s_nop 1
	v_cndmask_b32_e64 v68, v68, v70, s[14:15]
	v_cndmask_b32_e32 v70, 0, v211, vcc
	v_sub_f32_e32 v68, v68, v70
	v_sub_f32_e32 v68, v69, v68
	v_fmac_f32_e32 v67, 0x3d800000, v68
	v_mov_b32_e32 v120, v68
	s_waitcnt lgkmcnt(0)
	v_fma_f32 v72, v63, v100, v66
	v_fmac_f32_e32 v72, v64, v101
	v_fmac_f32_e32 v72, v60, v102
	v_fmac_f32_e32 v72, v65, v103
	v_fmac_f32_e32 v72, v61, v104
	v_fmac_f32_e32 v72, v62, v105
	v_pk_mul_f32 v[68:69], v[34:35], v[106:107]
	s_nop 0
	v_add_f32_e32 v68, v72, v68
	v_add_f32_e32 v72, v68, v69
	v_pk_mul_f32 v[68:69], v[36:37], v[108:109]
	s_nop 0
	v_add_f32_e32 v68, v72, v68
	v_add_f32_e32 v72, v68, v69
	v_pk_mul_f32 v[68:69], v[38:39], v[110:111]
	s_nop 0
	v_add_f32_e32 v68, v72, v68
	v_add_f32_e32 v72, v68, v69
	v_pk_mul_f32 v[68:69], v[40:41], v[112:113]
	s_nop 0
	v_add_f32_e32 v68, v72, v68
	v_add_f32_e32 v72, v68, v69
	v_pk_mul_f32 v[68:69], v[58:59], v[114:115]
	s_nop 0
	v_add_f32_e32 v68, v72, v68
	v_add_f32_e32 v68, v68, v69
	v_min_f32_e32 v69, 0, v68
	v_mul_f32_e64 v68, |v68|, s73
	v_exp_f32_e32 v68, v68
	s_nop 0
	v_add_f32_e32 v68, 1.0, v68
	v_cmp_gt_f32_e32 vcc, s94, v68
	s_nop 1
	v_cndmask_b32_e64 v70, 0, 32, vcc
	v_ldexp_f32 v68, v68, v70
	v_log_f32_e32 v68, v68
	s_nop 0
	v_mul_f32_e32 v70, 0x3f317217, v68
	v_fma_f32 v70, v68, s97, -v70
	v_fmac_f32_e32 v70, 0x3377d1cf, v68
	v_fmac_f32_e32 v70, 0x3f317217, v68
	v_cmp_lt_f32_e64 s[14:15], |v68|, s23
	s_nop 1
	v_cndmask_b32_e64 v68, v68, v70, s[14:15]
	v_cndmask_b32_e32 v70, 0, v211, vcc
	v_sub_f32_e32 v68, v68, v70
	v_sub_f32_e32 v68, v69, v68
	v_fmac_f32_e32 v67, 0x3d800000, v68
	v_mov_b32_e32 v121, v68
	v_add_u32_e32 v84, s0, v195
	ds_read_b128 v[68:71], v84
	ds_read_b128 v[72:75], v84 offset:16
	ds_read_b128 v[76:79], v84 offset:32
	ds_read_b128 v[80:83], v84 offset:48
	ds_read_b128 v[100:103], v84 offset:64
	ds_read_b128 v[104:107], v84 offset:80
	ds_read_b128 v[108:111], v84 offset:96
	ds_read_b128 v[112:115], v84 offset:112
	s_addk_i32 s0, 0x80
	s_waitcnt vmcnt(1) lgkmcnt(7)
; DEVI float logsigf_(float x) { return fminf(x, 0.f) - __logf(1.f + __expf(-fabsf(x))); }
; DEVI float gla_la(const float* gl, int t, const float* w2r, float gb) { float x = gb;
; #pragma unroll
;     for (int r = 0; r < 16; ++r) x += gl[t * 16 + r] * w2r[r];
;     return logsigf_(x) * (1.f / 16.f); }
; template <int KIND>
; DEVI void mix_out_phase(unsigned char* smem, const MixArgs a) {
;     ...
;             for (int t = sg * 32; t < sg * 32 + 32; ++t) ssum += gla_la(gl, t, w2r, gb);
	v_fma_f32 v85, v63, v68, v66
	v_fmac_f32_e32 v85, v64, v69
	v_fmac_f32_e32 v85, v60, v70
	v_fmac_f32_e32 v85, v65, v71
	s_waitcnt lgkmcnt(6)
	v_fmac_f32_e32 v85, v61, v72
	v_fmac_f32_e32 v85, v62, v73
	v_pk_mul_f32 v[68:69], v[34:35], v[74:75]
	v_add_f32_e32 v68, v85, v68
	v_add_f32_e32 v70, v68, v69
	s_waitcnt lgkmcnt(5)
	v_pk_mul_f32 v[68:69], v[36:37], v[76:77]
	s_nop 0
	v_add_f32_e32 v68, v70, v68
	v_add_f32_e32 v70, v68, v69
	v_pk_mul_f32 v[68:69], v[38:39], v[78:79]
	s_nop 0
	v_add_f32_e32 v68, v70, v68
	v_add_f32_e32 v70, v68, v69
	s_waitcnt lgkmcnt(4)
	v_pk_mul_f32 v[68:69], v[40:41], v[80:81]
	s_nop 0
	v_add_f32_e32 v68, v70, v68
	v_add_f32_e32 v70, v68, v69
	s_waitcnt vmcnt(0)
	v_pk_mul_f32 v[68:69], v[58:59], v[82:83]
	s_nop 0
	v_add_f32_e32 v68, v70, v68
	v_add_f32_e32 v68, v68, v69
	v_min_f32_e32 v69, 0, v68
	v_mul_f32_e64 v68, |v68|, s73
	v_exp_f32_e32 v68, v68
	s_nop 0
	v_add_f32_e32 v68, 1.0, v68
	v_cmp_gt_f32_e32 vcc, s94, v68
	s_nop 1
	v_cndmask_b32_e64 v70, 0, 32, vcc
	v_ldexp_f32 v68, v68, v70
	v_log_f32_e32 v68, v68
	s_nop 0
	v_mul_f32_e32 v70, 0x3f317217, v68
	v_fma_f32 v70, v68, s97, -v70
	v_fmac_f32_e32 v70, 0x3377d1cf, v68
	v_fmac_f32_e32 v70, 0x3f317217, v68
	v_cmp_lt_f32_e64 s[14:15], |v68|, s23
	s_nop 1
	v_cndmask_b32_e64 v68, v68, v70, s[14:15]
	v_cndmask_b32_e32 v70, 0, v211, vcc
	v_sub_f32_e32 v68, v68, v70
	v_sub_f32_e32 v68, v69, v68
	v_fmac_f32_e32 v67, 0x3d800000, v68
	v_mov_b32_e32 v122, v68
	s_waitcnt lgkmcnt(0)
	v_fma_f32 v72, v63, v100, v66
	v_fmac_f32_e32 v72, v64, v101
	v_fmac_f32_e32 v72, v60, v102
	v_fmac_f32_e32 v72, v65, v103
	v_fmac_f32_e32 v72, v61, v104
	v_fmac_f32_e32 v72, v62, v105
	v_pk_mul_f32 v[68:69], v[34:35], v[106:107]
	s_nop 0
	v_add_f32_e32 v68, v72, v68
	v_add_f32_e32 v72, v68, v69
	v_pk_mul_f32 v[68:69], v[36:37], v[108:109]
	s_nop 0
	v_add_f32_e32 v68, v72, v68
	v_add_f32_e32 v72, v68, v69
	v_pk_mul_f32 v[68:69], v[38:39], v[110:111]
	s_nop 0
	v_add_f32_e32 v68, v72, v68
	v_add_f32_e32 v72, v68, v69
	v_pk_mul_f32 v[68:69], v[40:41], v[112:113]
	s_nop 0
	v_add_f32_e32 v68, v72, v68
	v_add_f32_e32 v72, v68, v69
	v_pk_mul_f32 v[68:69], v[58:59], v[114:115]
	s_nop 0
	v_add_f32_e32 v68, v72, v68
	v_add_f32_e32 v68, v68, v69
	v_min_f32_e32 v69, 0, v68
	v_mul_f32_e64 v68, |v68|, s73
	v_exp_f32_e32 v68, v68
	s_nop 0
	v_add_f32_e32 v68, 1.0, v68
	v_cmp_gt_f32_e32 vcc, s94, v68
	s_nop 1
	v_cndmask_b32_e64 v70, 0, 32, vcc
	v_ldexp_f32 v68, v68, v70
	v_log_f32_e32 v68, v68
	s_nop 0
	v_mul_f32_e32 v70, 0x3f317217, v68
	v_fma_f32 v70, v68, s97, -v70
	v_fmac_f32_e32 v70, 0x3377d1cf, v68
	v_fmac_f32_e32 v70, 0x3f317217, v68
	v_cmp_lt_f32_e64 s[14:15], |v68|, s23
	s_nop 1
	v_cndmask_b32_e64 v68, v68, v70, s[14:15]
	v_cndmask_b32_e32 v70, 0, v211, vcc
	v_sub_f32_e32 v68, v68, v70
	v_sub_f32_e32 v68, v69, v68
	v_fmac_f32_e32 v67, 0x3d800000, v68
	v_mov_b32_e32 v123, v68
	v_add_u32_e32 v84, s0, v195
	ds_read_b128 v[68:71], v84
	ds_read_b128 v[72:75], v84 offset:16
	ds_read_b128 v[76:79], v84 offset:32
	ds_read_b128 v[80:83], v84 offset:48
	ds_read_b128 v[100:103], v84 offset:64
	ds_read_b128 v[104:107], v84 offset:80
	ds_read_b128 v[108:111], v84 offset:96
	ds_read_b128 v[112:115], v84 offset:112
	s_addk_i32 s0, 0x80
	s_waitcnt vmcnt(1) lgkmcnt(7)
	v_fma_f32 v85, v63, v68, v66
	v_fmac_f32_e32 v85, v64, v69
	v_fmac_f32_e32 v85, v60, v70
	v_fmac_f32_e32 v85, v65, v71
	s_waitcnt lgkmcnt(6)
	v_fmac_f32_e32 v85, v61, v72
	v_fmac_f32_e32 v85, v62, v73
	v_pk_mul_f32 v[68:69], v[34:35], v[74:75]
	v_add_f32_e32 v68, v85, v68
	v_add_f32_e32 v70, v68, v69
	s_waitcnt lgkmcnt(5)
	v_pk_mul_f32 v[68:69], v[36:37], v[76:77]
	s_nop 0
	v_add_f32_e32 v68, v70, v68
	v_add_f32_e32 v70, v68, v69
	v_pk_mul_f32 v[68:69], v[38:39], v[78:79]
	s_nop 0
	v_add_f32_e32 v68, v70, v68
	v_add_f32_e32 v70, v68, v69
	s_waitcnt lgkmcnt(4)
	v_pk_mul_f32 v[68:69], v[40:41], v[80:81]
	s_nop 0
	v_add_f32_e32 v68, v70, v68
	v_add_f32_e32 v70, v68, v69
	s_waitcnt vmcnt(0)
	v_pk_mul_f32 v[68:69], v[58:59], v[82:83]
	s_nop 0
	v_add_f32_e32 v68, v70, v68
	v_add_f32_e32 v68, v68, v69
	v_min_f32_e32 v69, 0, v68
	v_mul_f32_e64 v68, |v68|, s73
	v_exp_f32_e32 v68, v68
	s_nop 0
	v_add_f32_e32 v68, 1.0, v68
	v_cmp_gt_f32_e32 vcc, s94, v68
	s_nop 1
	v_cndmask_b32_e64 v70, 0, 32, vcc
	v_ldexp_f32 v68, v68, v70
	v_log_f32_e32 v68, v68
	s_nop 0
	v_mul_f32_e32 v70, 0x3f317217, v68
	v_fma_f32 v70, v68, s97, -v70
	v_fmac_f32_e32 v70, 0x3377d1cf, v68
	v_fmac_f32_e32 v70, 0x3f317217, v68
	v_cmp_lt_f32_e64 s[14:15], |v68|, s23
	s_nop 1
	v_cndmask_b32_e64 v68, v68, v70, s[14:15]
	v_cndmask_b32_e32 v70, 0, v211, vcc
	v_sub_f32_e32 v68, v68, v70
	v_sub_f32_e32 v68, v69, v68
	v_fmac_f32_e32 v67, 0x3d800000, v68
	v_mov_b32_e32 v124, v68
	s_waitcnt lgkmcnt(0)
	v_fma_f32 v72, v63, v100, v66
	v_fmac_f32_e32 v72, v64, v101
	v_fmac_f32_e32 v72, v60, v102
	v_fmac_f32_e32 v72, v65, v103
	v_fmac_f32_e32 v72, v61, v104
	v_fmac_f32_e32 v72, v62, v105
	v_pk_mul_f32 v[68:69], v[34:35], v[106:107]
	s_nop 0
	v_add_f32_e32 v68, v72, v68
	v_add_f32_e32 v72, v68, v69
	v_pk_mul_f32 v[68:69], v[36:37], v[108:109]
	s_nop 0
	v_add_f32_e32 v68, v72, v68
	v_add_f32_e32 v72, v68, v69
	v_pk_mul_f32 v[68:69], v[38:39], v[110:111]
	s_nop 0
	v_add_f32_e32 v68, v72, v68
	v_add_f32_e32 v72, v68, v69
	v_pk_mul_f32 v[68:69], v[40:41], v[112:113]
	s_nop 0
	v_add_f32_e32 v68, v72, v68
	v_add_f32_e32 v72, v68, v69
	v_pk_mul_f32 v[68:69], v[58:59], v[114:115]
	s_nop 0
	v_add_f32_e32 v68, v72, v68
	v_add_f32_e32 v68, v68, v69
	v_min_f32_e32 v69, 0, v68
	v_mul_f32_e64 v68, |v68|, s73
	v_exp_f32_e32 v68, v68
	s_nop 0
	v_add_f32_e32 v68, 1.0, v68
	v_cmp_gt_f32_e32 vcc, s94, v68
	s_nop 1
	v_cndmask_b32_e64 v70, 0, 32, vcc
	v_ldexp_f32 v68, v68, v70
	v_log_f32_e32 v68, v68
	s_nop 0
	v_mul_f32_e32 v70, 0x3f317217, v68
	v_fma_f32 v70, v68, s97, -v70
	v_fmac_f32_e32 v70, 0x3377d1cf, v68
	v_fmac_f32_e32 v70, 0x3f317217, v68
	v_cmp_lt_f32_e64 s[14:15], |v68|, s23
	s_nop 1
	v_cndmask_b32_e64 v68, v68, v70, s[14:15]
	v_cndmask_b32_e32 v70, 0, v211, vcc
	v_sub_f32_e32 v68, v68, v70
	v_sub_f32_e32 v68, v69, v68
	v_fmac_f32_e32 v67, 0x3d800000, v68
	v_mov_b32_e32 v125, v68
	v_add_u32_e32 v84, s0, v195
	ds_read_b128 v[68:71], v84
	ds_read_b128 v[72:75], v84 offset:16
	ds_read_b128 v[76:79], v84 offset:32
	ds_read_b128 v[80:83], v84 offset:48
	ds_read_b128 v[100:103], v84 offset:64
	ds_read_b128 v[104:107], v84 offset:80
	ds_read_b128 v[108:111], v84 offset:96
	ds_read_b128 v[112:115], v84 offset:112
	s_addk_i32 s0, 0x80
	s_waitcnt vmcnt(1) lgkmcnt(7)
; DEVI float logsigf_(float x) { return fminf(x, 0.f) - __logf(1.f + __expf(-fabsf(x))); }
; DEVI float gla_la(const float* gl, int t, const float* w2r, float gb) { float x = gb;
; #pragma unroll
;     for (int r = 0; r < 16; ++r) x += gl[t * 16 + r] * w2r[r];
;     return logsigf_(x) * (1.f / 16.f); }
; template <int KIND>
; DEVI void mix_out_phase(unsigned char* smem, const MixArgs a) {
;     ...
;             for (int t = sg * 32; t < sg * 32 + 32; ++t) ssum += gla_la(gl, t, w2r, gb);
	v_fma_f32 v85, v63, v68, v66
	v_fmac_f32_e32 v85, v64, v69
	v_fmac_f32_e32 v85, v60, v70
	v_fmac_f32_e32 v85, v65, v71
	s_waitcnt lgkmcnt(6)
	v_fmac_f32_e32 v85, v61, v72
	v_fmac_f32_e32 v85, v62, v73
	v_pk_mul_f32 v[68:69], v[34:35], v[74:75]
	v_add_f32_e32 v68, v85, v68
	v_add_f32_e32 v70, v68, v69
	s_waitcnt lgkmcnt(5)
	v_pk_mul_f32 v[68:69], v[36:37], v[76:77]
	s_nop 0
	v_add_f32_e32 v68, v70, v68
	v_add_f32_e32 v70, v68, v69
	v_pk_mul_f32 v[68:69], v[38:39], v[78:79]
	s_nop 0
	v_add_f32_e32 v68, v70, v68
	v_add_f32_e32 v70, v68, v69
	s_waitcnt lgkmcnt(4)
	v_pk_mul_f32 v[68:69], v[40:41], v[80:81]
	s_nop 0
	v_add_f32_e32 v68, v70, v68
	v_add_f32_e32 v70, v68, v69
	s_waitcnt vmcnt(0)
	v_pk_mul_f32 v[68:69], v[58:59], v[82:83]
	s_nop 0
	v_add_f32_e32 v68, v70, v68
	v_add_f32_e32 v68, v68, v69
	v_min_f32_e32 v69, 0, v68
	v_mul_f32_e64 v68, |v68|, s73
	v_exp_f32_e32 v68, v68
	s_nop 0
	v_add_f32_e32 v68, 1.0, v68
	v_cmp_gt_f32_e32 vcc, s94, v68
	s_nop 1
	v_cndmask_b32_e64 v70, 0, 32, vcc
	v_ldexp_f32 v68, v68, v70
	v_log_f32_e32 v68, v68
	s_nop 0
	v_mul_f32_e32 v70, 0x3f317217, v68
	v_fma_f32 v70, v68, s97, -v70
	v_fmac_f32_e32 v70, 0x3377d1cf, v68
	v_fmac_f32_e32 v70, 0x3f317217, v68
	v_cmp_lt_f32_e64 s[14:15], |v68|, s23
	s_nop 1
	v_cndmask_b32_e64 v68, v68, v70, s[14:15]
	v_cndmask_b32_e32 v70, 0, v211, vcc
	v_sub_f32_e32 v68, v68, v70
	v_sub_f32_e32 v68, v69, v68
	v_fmac_f32_e32 v67, 0x3d800000, v68
	v_mov_b32_e32 v126, v68
	s_waitcnt lgkmcnt(0)
	v_fma_f32 v72, v63, v100, v66
	v_fmac_f32_e32 v72, v64, v101
	v_fmac_f32_e32 v72, v60, v102
	v_fmac_f32_e32 v72, v65, v103
	v_fmac_f32_e32 v72, v61, v104
	v_fmac_f32_e32 v72, v62, v105
	v_pk_mul_f32 v[68:69], v[34:35], v[106:107]
	s_nop 0
	v_add_f32_e32 v68, v72, v68
	v_add_f32_e32 v72, v68, v69
	v_pk_mul_f32 v[68:69], v[36:37], v[108:109]
	s_nop 0
	v_add_f32_e32 v68, v72, v68
	v_add_f32_e32 v72, v68, v69
	v_pk_mul_f32 v[68:69], v[38:39], v[110:111]
	s_nop 0
	v_add_f32_e32 v68, v72, v68
	v_add_f32_e32 v72, v68, v69
	v_pk_mul_f32 v[68:69], v[40:41], v[112:113]
	s_nop 0
	v_add_f32_e32 v68, v72, v68
	v_add_f32_e32 v72, v68, v69
	v_pk_mul_f32 v[68:69], v[58:59], v[114:115]
	s_nop 0
	v_add_f32_e32 v68, v72, v68
	v_add_f32_e32 v68, v68, v69
	v_min_f32_e32 v69, 0, v68
	v_mul_f32_e64 v68, |v68|, s73
	v_exp_f32_e32 v68, v68
	s_nop 0
	v_add_f32_e32 v68, 1.0, v68
	v_cmp_gt_f32_e32 vcc, s94, v68
	s_nop 1
	v_cndmask_b32_e64 v70, 0, 32, vcc
	v_ldexp_f32 v68, v68, v70
	v_log_f32_e32 v68, v68
	s_nop 0
	v_mul_f32_e32 v70, 0x3f317217, v68
	v_fma_f32 v70, v68, s97, -v70
	v_fmac_f32_e32 v70, 0x3377d1cf, v68
	v_fmac_f32_e32 v70, 0x3f317217, v68
	v_cmp_lt_f32_e64 s[14:15], |v68|, s23
	s_nop 1
	v_cndmask_b32_e64 v68, v68, v70, s[14:15]
	v_cndmask_b32_e32 v70, 0, v211, vcc
	v_sub_f32_e32 v68, v68, v70
	v_sub_f32_e32 v68, v69, v68
	v_fmac_f32_e32 v67, 0x3d800000, v68
	v_mov_b32_e32 v127, v68
	v_add_u32_e32 v84, s0, v195
	ds_read_b128 v[68:71], v84
	ds_read_b128 v[72:75], v84 offset:16
	ds_read_b128 v[76:79], v84 offset:32
	ds_read_b128 v[80:83], v84 offset:48
	ds_read_b128 v[100:103], v84 offset:64
	ds_read_b128 v[104:107], v84 offset:80
	ds_read_b128 v[108:111], v84 offset:96
	ds_read_b128 v[112:115], v84 offset:112
	s_addk_i32 s0, 0x80
	s_waitcnt vmcnt(1) lgkmcnt(7)
	v_fma_f32 v85, v63, v68, v66
	v_fmac_f32_e32 v85, v64, v69
	v_fmac_f32_e32 v85, v60, v70
	v_fmac_f32_e32 v85, v65, v71
	s_waitcnt lgkmcnt(6)
	v_fmac_f32_e32 v85, v61, v72
	v_fmac_f32_e32 v85, v62, v73
	v_pk_mul_f32 v[68:69], v[34:35], v[74:75]
	v_add_f32_e32 v68, v85, v68
	v_add_f32_e32 v70, v68, v69
	s_waitcnt lgkmcnt(5)
	v_pk_mul_f32 v[68:69], v[36:37], v[76:77]
	s_nop 0
	v_add_f32_e32 v68, v70, v68
	v_add_f32_e32 v70, v68, v69
	v_pk_mul_f32 v[68:69], v[38:39], v[78:79]
	s_nop 0
	v_add_f32_e32 v68, v70, v68
	v_add_f32_e32 v70, v68, v69
	s_waitcnt lgkmcnt(4)
	v_pk_mul_f32 v[68:69], v[40:41], v[80:81]
	s_nop 0
	v_add_f32_e32 v68, v70, v68
	v_add_f32_e32 v70, v68, v69
	s_waitcnt vmcnt(0)
	v_pk_mul_f32 v[68:69], v[58:59], v[82:83]
	s_nop 0
	v_add_f32_e32 v68, v70, v68
	v_add_f32_e32 v68, v68, v69
	v_min_f32_e32 v69, 0, v68
	v_mul_f32_e64 v68, |v68|, s73
	v_exp_f32_e32 v68, v68
	s_nop 0
	v_add_f32_e32 v68, 1.0, v68
	v_cmp_gt_f32_e32 vcc, s94, v68
	s_nop 1
	v_cndmask_b32_e64 v70, 0, 32, vcc
	v_ldexp_f32 v68, v68, v70
	v_log_f32_e32 v68, v68
	s_nop 0
	v_mul_f32_e32 v70, 0x3f317217, v68
	v_fma_f32 v70, v68, s97, -v70
	v_fmac_f32_e32 v70, 0x3377d1cf, v68
	v_fmac_f32_e32 v70, 0x3f317217, v68
	v_cmp_lt_f32_e64 s[14:15], |v68|, s23
	s_nop 1
	v_cndmask_b32_e64 v68, v68, v70, s[14:15]
	v_cndmask_b32_e32 v70, 0, v211, vcc
	v_sub_f32_e32 v68, v68, v70
	v_sub_f32_e32 v68, v69, v68
	v_fmac_f32_e32 v67, 0x3d800000, v68
	v_mov_b32_e32 v128, v68
	s_waitcnt lgkmcnt(0)
	v_fma_f32 v72, v63, v100, v66
	v_fmac_f32_e32 v72, v64, v101
	v_fmac_f32_e32 v72, v60, v102
	v_fmac_f32_e32 v72, v65, v103
	v_fmac_f32_e32 v72, v61, v104
	v_fmac_f32_e32 v72, v62, v105
	v_pk_mul_f32 v[68:69], v[34:35], v[106:107]
	s_nop 0
	v_add_f32_e32 v68, v72, v68
	v_add_f32_e32 v72, v68, v69
	v_pk_mul_f32 v[68:69], v[36:37], v[108:109]
	s_nop 0
	v_add_f32_e32 v68, v72, v68
	v_add_f32_e32 v72, v68, v69
	v_pk_mul_f32 v[68:69], v[38:39], v[110:111]
	s_nop 0
	v_add_f32_e32 v68, v72, v68
	v_add_f32_e32 v72, v68, v69
	v_pk_mul_f32 v[68:69], v[40:41], v[112:113]
	s_nop 0
	v_add_f32_e32 v68, v72, v68
	v_add_f32_e32 v72, v68, v69
	v_pk_mul_f32 v[68:69], v[58:59], v[114:115]
	s_nop 0
	v_add_f32_e32 v68, v72, v68
	v_add_f32_e32 v68, v68, v69
	v_min_f32_e32 v69, 0, v68
	v_mul_f32_e64 v68, |v68|, s73
	v_exp_f32_e32 v68, v68
	s_nop 0
	v_add_f32_e32 v68, 1.0, v68
	v_cmp_gt_f32_e32 vcc, s94, v68
	s_nop 1
	v_cndmask_b32_e64 v70, 0, 32, vcc
	v_ldexp_f32 v68, v68, v70
	v_log_f32_e32 v68, v68
	s_nop 0
	v_mul_f32_e32 v70, 0x3f317217, v68
	v_fma_f32 v70, v68, s97, -v70
	v_fmac_f32_e32 v70, 0x3377d1cf, v68
	v_fmac_f32_e32 v70, 0x3f317217, v68
	v_cmp_lt_f32_e64 s[14:15], |v68|, s23
	s_nop 1
	v_cndmask_b32_e64 v68, v68, v70, s[14:15]
	v_cndmask_b32_e32 v70, 0, v211, vcc
	v_sub_f32_e32 v68, v68, v70
	v_sub_f32_e32 v68, v69, v68
	v_fmac_f32_e32 v67, 0x3d800000, v68
	v_mov_b32_e32 v129, v68
	v_add_u32_e32 v84, s0, v195
	ds_read_b128 v[68:71], v84
	ds_read_b128 v[72:75], v84 offset:16
	ds_read_b128 v[76:79], v84 offset:32
	ds_read_b128 v[80:83], v84 offset:48
	ds_read_b128 v[100:103], v84 offset:64
	ds_read_b128 v[104:107], v84 offset:80
	ds_read_b128 v[108:111], v84 offset:96
	ds_read_b128 v[112:115], v84 offset:112
	s_addk_i32 s0, 0x80
	s_waitcnt vmcnt(1) lgkmcnt(7)
; DEVI float logsigf_(float x) { return fminf(x, 0.f) - __logf(1.f + __expf(-fabsf(x))); }
; DEVI float gla_la(const float* gl, int t, const float* w2r, float gb) { float x = gb;
; #pragma unroll
;     for (int r = 0; r < 16; ++r) x += gl[t * 16 + r] * w2r[r];
;     return logsigf_(x) * (1.f / 16.f); }
; template <int KIND>
; DEVI void mix_out_phase(unsigned char* smem, const MixArgs a) {
;     ...
;         if (KIND == 1 && item + (int)gridDim.x < 16 * NCH) OUT_PREF(item + (int)gridDim.x);
	v_fma_f32 v85, v63, v68, v66
	v_fmac_f32_e32 v85, v64, v69
	v_fmac_f32_e32 v85, v60, v70
	v_fmac_f32_e32 v85, v65, v71
	s_waitcnt lgkmcnt(6)
	v_fmac_f32_e32 v85, v61, v72
	v_fmac_f32_e32 v85, v62, v73
	v_pk_mul_f32 v[68:69], v[34:35], v[74:75]
	v_add_f32_e32 v68, v85, v68
	v_add_f32_e32 v70, v68, v69
	s_waitcnt lgkmcnt(5)
	v_pk_mul_f32 v[68:69], v[36:37], v[76:77]
	s_nop 0
	v_add_f32_e32 v68, v70, v68
	v_add_f32_e32 v70, v68, v69
	v_pk_mul_f32 v[68:69], v[38:39], v[78:79]
	s_nop 0
	v_add_f32_e32 v68, v70, v68
	v_add_f32_e32 v70, v68, v69
	s_waitcnt lgkmcnt(4)
	v_pk_mul_f32 v[68:69], v[40:41], v[80:81]
	s_nop 0
	v_add_f32_e32 v68, v70, v68
	v_add_f32_e32 v70, v68, v69
	s_waitcnt vmcnt(0)
	v_pk_mul_f32 v[68:69], v[58:59], v[82:83]
	s_nop 0
	v_add_f32_e32 v68, v70, v68
	v_add_f32_e32 v68, v68, v69
	v_min_f32_e32 v69, 0, v68
	v_mul_f32_e64 v68, |v68|, s73
	v_exp_f32_e32 v68, v68
	s_nop 0
	v_add_f32_e32 v68, 1.0, v68
	v_cmp_gt_f32_e32 vcc, s94, v68
	s_nop 1
	v_cndmask_b32_e64 v70, 0, 32, vcc
	v_ldexp_f32 v68, v68, v70
	v_log_f32_e32 v68, v68
	s_nop 0
	v_mul_f32_e32 v70, 0x3f317217, v68
	v_fma_f32 v70, v68, s97, -v70
	v_fmac_f32_e32 v70, 0x3377d1cf, v68
	v_fmac_f32_e32 v70, 0x3f317217, v68
	v_cmp_lt_f32_e64 s[14:15], |v68|, s23
	s_nop 1
	v_cndmask_b32_e64 v68, v68, v70, s[14:15]
	v_cndmask_b32_e32 v70, 0, v211, vcc
	v_sub_f32_e32 v68, v68, v70
	v_sub_f32_e32 v68, v69, v68
	v_fmac_f32_e32 v67, 0x3d800000, v68
	v_mov_b32_e32 v136, v68
	s_waitcnt lgkmcnt(0)
	v_fma_f32 v72, v63, v100, v66
	v_fmac_f32_e32 v72, v64, v101
	v_fmac_f32_e32 v72, v60, v102
	v_fmac_f32_e32 v72, v65, v103
	v_fmac_f32_e32 v72, v61, v104
	v_fmac_f32_e32 v72, v62, v105
	v_pk_mul_f32 v[68:69], v[34:35], v[106:107]
	s_nop 0
	v_add_f32_e32 v68, v72, v68
	v_add_f32_e32 v72, v68, v69
	v_pk_mul_f32 v[68:69], v[36:37], v[108:109]
	s_nop 0
	v_add_f32_e32 v68, v72, v68
	v_add_f32_e32 v72, v68, v69
	v_pk_mul_f32 v[68:69], v[38:39], v[110:111]
	s_nop 0
	v_add_f32_e32 v68, v72, v68
	v_add_f32_e32 v72, v68, v69
	v_pk_mul_f32 v[68:69], v[40:41], v[112:113]
	s_nop 0
	v_add_f32_e32 v68, v72, v68
	v_add_f32_e32 v72, v68, v69
	v_pk_mul_f32 v[68:69], v[58:59], v[114:115]
	s_nop 0
	v_add_f32_e32 v68, v72, v68
	v_add_f32_e32 v68, v68, v69
	v_min_f32_e32 v69, 0, v68
	v_mul_f32_e64 v68, |v68|, s73
	v_exp_f32_e32 v68, v68
	s_nop 0
	v_add_f32_e32 v68, 1.0, v68
	v_cmp_gt_f32_e32 vcc, s94, v68
	s_nop 1
	v_cndmask_b32_e64 v70, 0, 32, vcc
	v_ldexp_f32 v68, v68, v70
	v_log_f32_e32 v68, v68
	s_nop 0
	v_mul_f32_e32 v70, 0x3f317217, v68
	v_fma_f32 v70, v68, s97, -v70
	v_fmac_f32_e32 v70, 0x3377d1cf, v68
	v_fmac_f32_e32 v70, 0x3f317217, v68
	v_cmp_lt_f32_e64 s[14:15], |v68|, s23
	s_nop 1
	v_cndmask_b32_e64 v68, v68, v70, s[14:15]
	v_cndmask_b32_e32 v70, 0, v211, vcc
	v_sub_f32_e32 v68, v68, v70
	v_sub_f32_e32 v68, v69, v68
	v_fmac_f32_e32 v67, 0x3d800000, v68
	v_mov_b32_e32 v137, v68
	v_add_u32_e32 v84, s0, v195
	ds_read_b128 v[68:71], v84
	ds_read_b128 v[72:75], v84 offset:16
	ds_read_b128 v[76:79], v84 offset:32
	ds_read_b128 v[80:83], v84 offset:48
	ds_read_b128 v[100:103], v84 offset:64
	ds_read_b128 v[104:107], v84 offset:80
	ds_read_b128 v[108:111], v84 offset:96
	ds_read_b128 v[112:115], v84 offset:112
	s_addk_i32 s0, 0x80
	s_waitcnt vmcnt(1) lgkmcnt(7)
	v_fma_f32 v85, v63, v68, v66
	v_fmac_f32_e32 v85, v64, v69
	v_fmac_f32_e32 v85, v60, v70
	v_fmac_f32_e32 v85, v65, v71
	s_waitcnt lgkmcnt(6)
	v_fmac_f32_e32 v85, v61, v72
	v_fmac_f32_e32 v85, v62, v73
	v_pk_mul_f32 v[68:69], v[34:35], v[74:75]
	v_add_f32_e32 v68, v85, v68
	v_add_f32_e32 v70, v68, v69
	s_waitcnt lgkmcnt(5)
	v_pk_mul_f32 v[68:69], v[36:37], v[76:77]
	s_nop 0
	v_add_f32_e32 v68, v70, v68
	v_add_f32_e32 v70, v68, v69
	v_pk_mul_f32 v[68:69], v[38:39], v[78:79]
	s_nop 0
	v_add_f32_e32 v68, v70, v68
	v_add_f32_e32 v70, v68, v69
	s_waitcnt lgkmcnt(4)
	v_pk_mul_f32 v[68:69], v[40:41], v[80:81]
	s_nop 0
	v_add_f32_e32 v68, v70, v68
	v_add_f32_e32 v70, v68, v69
	s_waitcnt vmcnt(0)
	v_pk_mul_f32 v[68:69], v[58:59], v[82:83]
	s_nop 0
	v_add_f32_e32 v68, v70, v68
	v_add_f32_e32 v68, v68, v69
	v_min_f32_e32 v69, 0, v68
	v_mul_f32_e64 v68, |v68|, s73
	v_exp_f32_e32 v68, v68
	s_nop 0
	v_add_f32_e32 v68, 1.0, v68
	v_cmp_gt_f32_e32 vcc, s94, v68
	s_nop 1
	v_cndmask_b32_e64 v70, 0, 32, vcc
	v_ldexp_f32 v68, v68, v70
	v_log_f32_e32 v68, v68
	s_nop 0
	v_mul_f32_e32 v70, 0x3f317217, v68
	v_fma_f32 v70, v68, s97, -v70
	v_fmac_f32_e32 v70, 0x3377d1cf, v68
	v_fmac_f32_e32 v70, 0x3f317217, v68
	v_cmp_lt_f32_e64 s[14:15], |v68|, s23
	s_nop 1
	v_cndmask_b32_e64 v68, v68, v70, s[14:15]
	v_cndmask_b32_e32 v70, 0, v211, vcc
	v_sub_f32_e32 v68, v68, v70
	v_sub_f32_e32 v68, v69, v68
	v_fmac_f32_e32 v67, 0x3d800000, v68
	v_mov_b32_e32 v138, v68
	s_waitcnt lgkmcnt(0)
	v_fma_f32 v72, v63, v100, v66
	v_fmac_f32_e32 v72, v64, v101
	v_fmac_f32_e32 v72, v60, v102
	v_fmac_f32_e32 v72, v65, v103
	v_fmac_f32_e32 v72, v61, v104
	v_fmac_f32_e32 v72, v62, v105
	v_pk_mul_f32 v[68:69], v[34:35], v[106:107]
	s_nop 0
	v_add_f32_e32 v68, v72, v68
	v_add_f32_e32 v72, v68, v69
	v_pk_mul_f32 v[68:69], v[36:37], v[108:109]
	s_nop 0
	v_add_f32_e32 v68, v72, v68
	v_add_f32_e32 v72, v68, v69
	v_pk_mul_f32 v[68:69], v[38:39], v[110:111]
	s_nop 0
	v_add_f32_e32 v68, v72, v68
	v_add_f32_e32 v72, v68, v69
	v_pk_mul_f32 v[68:69], v[40:41], v[112:113]
	s_nop 0
	v_add_f32_e32 v68, v72, v68
	v_add_f32_e32 v72, v68, v69
	v_pk_mul_f32 v[68:69], v[58:59], v[114:115]
	s_nop 0
	v_add_f32_e32 v68, v72, v68
	v_add_f32_e32 v68, v68, v69
	v_min_f32_e32 v69, 0, v68
	v_mul_f32_e64 v68, |v68|, s73
	v_exp_f32_e32 v68, v68
	s_nop 0
	v_add_f32_e32 v68, 1.0, v68
	v_cmp_gt_f32_e32 vcc, s94, v68
	s_nop 1
	v_cndmask_b32_e64 v70, 0, 32, vcc
	v_ldexp_f32 v68, v68, v70
	v_log_f32_e32 v68, v68
	s_nop 0
	v_mul_f32_e32 v70, 0x3f317217, v68
	v_fma_f32 v70, v68, s97, -v70
	v_fmac_f32_e32 v70, 0x3377d1cf, v68
	v_fmac_f32_e32 v70, 0x3f317217, v68
	v_cmp_lt_f32_e64 s[14:15], |v68|, s23
	s_nop 1
	v_cndmask_b32_e64 v68, v68, v70, s[14:15]
	v_cndmask_b32_e32 v70, 0, v211, vcc
	v_sub_f32_e32 v68, v68, v70
	v_sub_f32_e32 v68, v69, v68
	v_fmac_f32_e32 v67, 0x3d800000, v68
	v_mov_b32_e32 v139, v68
	s_cmpk_gt_i32 s88, 0x3ff
	s_cselect_b64 s[16:17], -1, 0
	s_and_b64 vcc, exec, s[16:17]
	s_cbranch_vccnz .Lpfm_out
; DEVI void lds_barrier() { asm volatile("s_waitcnt lgkmcnt(0)\n\ts_barrier" ::: "memory"); }
; template <int KIND>
; DEVI void mix_out_phase(unsigned char* smem, const MixArgs a) {
;     ...
;             seg[sg * 128 + ch] = ssum; lds_barrier();
;             float Bc = 0.f;
; #pragma unroll
;             for (int s2 = 0; s2 < 4; ++s2) { const float v = seg[s2 * 128 + ch]; if (s2 < sg) Bc += v; }
	s_ashr_i32 s1, s88, 31
	s_lshr_b32 s1, s1, 26
	s_add_i32 s1, s88, s1
	s_and_b32 s14, s1, 0x1ffffc0
	s_sub_i32 s18, s88, s14
	s_ashr_i32 s14, s1, 8
	s_ashr_i32 s15, s14, 31
	s_lshl_b32 s18, s18, 7
	s_lshl_b64 s[14:15], s[14:15], 13
	s_ashr_i32 s19, s18, 31
	s_add_u32 s14, s14, s18
	s_addc_u32 s15, s15, s19
	s_lshl_b32 s1, s1, 2
	s_and_b32 s66, s1, 0x300
	v_lshl_add_u64 v[26:27], v[180:181], 0, s[66:67]
	v_lshl_add_u64 v[10:11], s[14:15], 0, v[146:147]
	v_lshl_add_u64 v[18:19], s[14:15], 0, v[148:149]
	v_lshl_add_u64 v[28:29], s[14:15], 0, v[150:151]
	v_lshl_add_u64 v[34:35], s[14:15], 0, v[152:153]
	v_mad_u64_u32 v[4:5], s[18:19], v10, s95, v[26:27]
	v_mad_u64_u32 v[14:15], s[18:19], v18, s95, v[26:27]
	v_mad_u64_u32 v[22:23], s[18:19], v28, s95, v[26:27]
	v_mad_u64_u32 v[30:31], s[14:15], v34, s95, v[26:27]
	v_mad_i32_i24 v5, v11, s95, v5
	v_lshlrev_b64 v[10:11], 6, v[10:11]
	v_mad_i32_i24 v15, v19, s95, v15
	v_lshlrev_b64 v[18:19], 6, v[18:19]
	v_mad_i32_i24 v23, v29, s95, v23
	v_lshlrev_b64 v[28:29], 6, v[28:29]
	v_mad_i32_i24 v31, v35, s95, v31
	v_lshlrev_b64 v[34:35], 6, v[34:35]
	v_lshl_add_u64 v[10:11], v[182:183], 0, v[10:11]
	v_lshl_add_u64 v[18:19], v[182:183], 0, v[18:19]
	v_lshl_add_u64 v[28:29], v[182:183], 0, v[28:29]
	v_lshl_add_u64 v[34:35], v[182:183], 0, v[34:35]
	global_load_dwordx4 v[0:3], v[4:5], off
	s_nop 0
	global_load_dwordx4 v[4:7], v[4:5], off offset:1024
	s_nop 0
	global_load_dword v185, v[10:11], off
	s_nop 0
	global_load_dwordx4 v[10:13], v[14:15], off
	s_nop 0
	global_load_dwordx4 v[14:17], v[14:15], off offset:1024
	s_nop 0
	global_load_dword v200, v[18:19], off
	s_nop 0
	global_load_dwordx4 v[18:21], v[22:23], off
	s_nop 0
	global_load_dwordx4 v[22:25], v[22:23], off offset:1024
	s_nop 0
	global_load_dword v201, v[28:29], off
	s_nop 0
	global_load_dwordx4 v[26:29], v[30:31], off
	s_nop 0
	global_load_dwordx4 v[30:33], v[30:31], off offset:1024
	s_nop 0
	global_load_dword v207, v[34:35], off
.Lpfm_out:
	ds_write_b32 v204, v67 offset:1536
	s_waitcnt lgkmcnt(0)
	s_barrier
	v_mov_b32_e32 v67, 0
	s_and_saveexec_b64 s[14:15], s[6:7]
	s_cbranch_execz .LBB0_696
	ds_read_b32 v67, v205 offset:1536
	s_waitcnt lgkmcnt(0)
	v_add_f32_e32 v67, 0, v67
	s_or_b64 exec, exec, s[14:15]
	s_and_saveexec_b64 s[14:15], s[8:9]
	s_cbranch_execnz .LBB0_697
